# int8 weight conversion with 128-byte source rows: adjacent workgroup pairs split K and exchange their 32 column maxima through tagged 8-byte granules (single read of the weights, full cache lines)
# speedup vs baseline: 1.0039x; 1.0039x over previous
.Lp0_after_colmax:
	v_readlane_b32 s0, v254, 15
	s_lshl_b32 s21, s0, 9
	s_mov_b32 s14, s90
	s_cmpk_gt_i32 s90, 0x69ff
	s_waitcnt lgkmcnt(0)
	s_barrier
	s_cbranch_scc1 .LBB0_115
	v_mbcnt_lo_u32_b32 v135, -1, 0
	v_mbcnt_hi_u32_b32 v135, -1, v135
	v_lshrrev_b32_e32 v136, 3, v135
	v_and_b32_e32 v137, 7, v135
	v_lshlrev_b32_e32 v230, 4, v137
	v_lshlrev_b32_e32 v195, 5, v137
	v_lshlrev_b32_e32 v231, 15, v137
	v_lshl_add_u32 v231, v136, 3, v231
	v_readlane_b32 s62, v254, 17
	v_readlane_b32 s1, v254, 16
	v_readlane_b32 s72, v254, 15
	s_mov_b32 s74, 0x42fe0000
	s_mov_b32 s11, 0
	s_and_b32 s12, s72, 1
	s_lshr_b32 s72, s72, 1
	s_mov_b32 s53, 0
	s_lshl_b32 s52, s12, 11
	s_lshl_b32 s3, s1, 8
	s_add_u32 s52, s52, s3
	s_lshl_b32 s3, s72, 10
	s_add_u32 s50, s34, s3
	s_addc_u32 s51, s35, 0
	s_add_u32 s50, s50, 0x10000
	s_addc_u32 s51, s51, 0
	v_lshlrev_b32_e32 v139, 10, v137
	v_lshl_add_u32 v139, v136, 2, v139
	v_add_u32_e32 v139, s62, v139
	v_lshlrev_b32_e32 v174, 2, v135
	v_xor_b32_e32 v192, 0x20, v174
	v_xor_b32_e32 v193, 0x40, v174
	v_xor_b32_e32 v194, 0x80, v174
	v_lshrrev_b32_e32 v175, 4, v135
	v_and_b32_e32 v176, 15, v135
	v_lshlrev_b32_e32 v212, 8, v175
	v_lshl_add_u32 v212, v176, 4, v212
	v_add_u32_e32 v212, s62, v212
	v_lshlrev_b32_e32 v213, 12, v175
	v_lshl_add_u32 v213, v176, 4, v213
	v_readlane_b32 s48, v255, 47
	v_readlane_b32 s49, v255, 48
	v_mul_u32_u24_e32 v138, 0x20000, v136
	v_lshl_add_u32 v138, v137, 4, v138
	s_mul_i32 s3, s52, 0x8000
	s_nop 1
	s_add_u32 s48, s48, s3
	s_addc_u32 s49, s49, 0
	s_mov_b32 s0, s72
	s_cmp_ge_u32 s0, 0x100
	s_cbranch_scc1 .Lc32_gates_done
	s_lshl_b32 s3, s0, 7
	s_add_u32 s56, s48, s3
	s_addc_u32 s57, s49, 0
	global_load_dwordx4 v[6:9], v138, s[56:57]
	s_add_u32 s56, s56, 0x8000
	s_addc_u32 s57, s57, 0
	global_load_dwordx4 v[10:13], v138, s[56:57]
	s_add_u32 s56, s56, 0x8000
	s_addc_u32 s57, s57, 0
	global_load_dwordx4 v[14:17], v138, s[56:57]
	s_add_u32 s56, s56, 0x8000
	s_addc_u32 s57, s57, 0
	global_load_dwordx4 v[18:21], v138, s[56:57]
	s_add_u32 s56, s56, 0xe8000
	s_addc_u32 s57, s57, 0
	global_load_dwordx4 v[22:25], v138, s[56:57]
	s_add_u32 s56, s56, 0x8000
	s_addc_u32 s57, s57, 0
	global_load_dwordx4 v[26:29], v138, s[56:57]
	s_add_u32 s56, s56, 0x8000
	s_addc_u32 s57, s57, 0
	global_load_dwordx4 v[30:33], v138, s[56:57]
	s_add_u32 s56, s56, 0x8000
	s_addc_u32 s57, s57, 0
	global_load_dwordx4 v[34:37], v138, s[56:57]
	s_add_u32 s56, s56, 0xe8000
	s_addc_u32 s57, s57, 0
	global_load_dwordx4 v[38:41], v138, s[56:57]
	s_add_u32 s56, s56, 0x8000
	s_addc_u32 s57, s57, 0
	global_load_dwordx4 v[42:45], v138, s[56:57]
	s_add_u32 s56, s56, 0x8000
	s_addc_u32 s57, s57, 0
	global_load_dwordx4 v[46:49], v138, s[56:57]
	s_add_u32 s56, s56, 0x8000
	s_addc_u32 s57, s57, 0
	global_load_dwordx4 v[50:53], v138, s[56:57]
	s_add_u32 s56, s56, 0xe8000
	s_addc_u32 s57, s57, 0
	global_load_dwordx4 v[54:57], v138, s[56:57]
	s_add_u32 s56, s56, 0x8000
	s_addc_u32 s57, s57, 0
	global_load_dwordx4 v[58:61], v138, s[56:57]
	s_add_u32 s56, s56, 0x8000
	s_addc_u32 s57, s57, 0
	global_load_dwordx4 v[62:65], v138, s[56:57]
	s_add_u32 s56, s56, 0x8000
	s_addc_u32 s57, s57, 0
	global_load_dwordx4 v[66:69], v138, s[56:57]
	s_add_u32 s56, s56, 0xe8000
	s_addc_u32 s57, s57, 0
	global_load_dwordx4 v[70:73], v138, s[56:57]
	s_add_u32 s56, s56, 0x8000
	s_addc_u32 s57, s57, 0
	global_load_dwordx4 v[74:77], v138, s[56:57]
	s_add_u32 s56, s56, 0x8000
	s_addc_u32 s57, s57, 0
	global_load_dwordx4 v[78:81], v138, s[56:57]
	s_add_u32 s56, s56, 0x8000
	s_addc_u32 s57, s57, 0
	global_load_dwordx4 v[82:85], v138, s[56:57]
	s_add_u32 s56, s56, 0xe8000
	s_addc_u32 s57, s57, 0
	global_load_dwordx4 v[86:89], v138, s[56:57]
	s_add_u32 s56, s56, 0x8000
	s_addc_u32 s57, s57, 0
	global_load_dwordx4 v[90:93], v138, s[56:57]
	s_add_u32 s56, s56, 0x8000
	s_addc_u32 s57, s57, 0
	global_load_dwordx4 v[94:97], v138, s[56:57]
	s_add_u32 s56, s56, 0x8000
	s_addc_u32 s57, s57, 0
	global_load_dwordx4 v[98:101], v138, s[56:57]
	s_add_u32 s56, s56, 0xe8000
	s_addc_u32 s57, s57, 0
	global_load_dwordx4 v[102:105], v138, s[56:57]
	s_add_u32 s56, s56, 0x8000
	s_addc_u32 s57, s57, 0
	global_load_dwordx4 v[106:109], v138, s[56:57]
	s_add_u32 s56, s56, 0x8000
	s_addc_u32 s57, s57, 0
	global_load_dwordx4 v[110:113], v138, s[56:57]
	s_add_u32 s56, s56, 0x8000
	s_addc_u32 s57, s57, 0
	global_load_dwordx4 v[114:117], v138, s[56:57]
	s_add_u32 s56, s56, 0xe8000
	s_addc_u32 s57, s57, 0
	global_load_dwordx4 v[118:121], v138, s[56:57]
	s_add_u32 s56, s56, 0x8000
	s_addc_u32 s57, s57, 0
	global_load_dwordx4 v[122:125], v138, s[56:57]
	s_add_u32 s56, s56, 0x8000
	s_addc_u32 s57, s57, 0
	global_load_dwordx4 v[126:129], v138, s[56:57]
	s_add_u32 s56, s56, 0x8000
	s_addc_u32 s57, s57, 0
	global_load_dwordx4 v[130:133], v138, s[56:57]
.Lc32_gates_loop:
	s_lshl_b32 s2, s0, 5
	s_add_u32 s53, s53, 1
	s_mov_b32 s60, s2
	s_lshl_b32 s63, s11, 10
	s_add_u32 s63, s63, 0x21000
	s_lshl_b32 s3, s1, 7
	s_add_u32 s3, s3, s63
	v_add_u32_e32 v172, s3, v230
	v_add_u32_e32 v173, s63, v230
	s_waitcnt vmcnt(0)
	v_max3_f32 v216, |v6|, |v10|, |v14|
	v_max3_f32 v216, v216, |v18|, |v22|
	v_max3_f32 v216, v216, |v26|, |v30|
	v_max3_f32 v216, v216, |v34|, |v38|
	v_max3_f32 v216, v216, |v42|, |v46|
	v_max3_f32 v216, v216, |v50|, |v54|
	v_max3_f32 v216, v216, |v58|, |v62|
	v_max3_f32 v216, v216, |v66|, |v70|
	v_max3_f32 v216, v216, |v74|, |v78|
	v_max3_f32 v216, v216, |v82|, |v86|
	v_max3_f32 v216, v216, |v90|, |v94|
	v_max3_f32 v216, v216, |v98|, |v102|
	v_max3_f32 v216, v216, |v106|, |v110|
	v_max3_f32 v216, v216, |v114|, |v118|
	v_max3_f32 v216, v216, |v122|, |v126|
	v_max_f32_e64 v216, v216, |v130|
	v_max3_f32 v217, |v7|, |v11|, |v15|
	v_max3_f32 v217, v217, |v19|, |v23|
	v_max3_f32 v217, v217, |v27|, |v31|
	v_max3_f32 v217, v217, |v35|, |v39|
	v_max3_f32 v217, v217, |v43|, |v47|
	v_max3_f32 v217, v217, |v51|, |v55|
	v_max3_f32 v217, v217, |v59|, |v63|
	v_max3_f32 v217, v217, |v67|, |v71|
	v_max3_f32 v217, v217, |v75|, |v79|
	v_max3_f32 v217, v217, |v83|, |v87|
	v_max3_f32 v217, v217, |v91|, |v95|
	v_max3_f32 v217, v217, |v99|, |v103|
	v_max3_f32 v217, v217, |v107|, |v111|
	v_max3_f32 v217, v217, |v115|, |v119|
	v_max3_f32 v217, v217, |v123|, |v127|
	v_max_f32_e64 v217, v217, |v131|
	v_max3_f32 v218, |v8|, |v12|, |v16|
	v_max3_f32 v218, v218, |v20|, |v24|
	v_max3_f32 v218, v218, |v28|, |v32|
	v_max3_f32 v218, v218, |v36|, |v40|
	v_max3_f32 v218, v218, |v44|, |v48|
	v_max3_f32 v218, v218, |v52|, |v56|
	v_max3_f32 v218, v218, |v60|, |v64|
	v_max3_f32 v218, v218, |v68|, |v72|
	v_max3_f32 v218, v218, |v76|, |v80|
	v_max3_f32 v218, v218, |v84|, |v88|
	v_max3_f32 v218, v218, |v92|, |v96|
	v_max3_f32 v218, v218, |v100|, |v104|
	v_max3_f32 v218, v218, |v108|, |v112|
	v_max3_f32 v218, v218, |v116|, |v120|
	v_max3_f32 v218, v218, |v124|, |v128|
	v_max_f32_e64 v218, v218, |v132|
	v_max3_f32 v219, |v9|, |v13|, |v17|
	v_max3_f32 v219, v219, |v21|, |v25|
	v_max3_f32 v219, v219, |v29|, |v33|
	v_max3_f32 v219, v219, |v37|, |v41|
	v_max3_f32 v219, v219, |v45|, |v49|
	v_max3_f32 v219, v219, |v53|, |v57|
	v_max3_f32 v219, v219, |v61|, |v65|
	v_max3_f32 v219, v219, |v69|, |v73|
	v_max3_f32 v219, v219, |v77|, |v81|
	v_max3_f32 v219, v219, |v85|, |v89|
	v_max3_f32 v219, v219, |v93|, |v97|
	v_max3_f32 v219, v219, |v101|, |v105|
	v_max3_f32 v219, v219, |v109|, |v113|
	v_max3_f32 v219, v219, |v117|, |v121|
	v_max3_f32 v219, v219, |v125|, |v129|
	v_max_f32_e64 v219, v219, |v133|
	ds_bpermute_b32 v174, v192, v216
	ds_bpermute_b32 v175, v192, v217
	ds_bpermute_b32 v176, v192, v218
	ds_bpermute_b32 v177, v192, v219
	s_waitcnt lgkmcnt(0)
	v_max_f32_e32 v216, v216, v174
	v_max_f32_e32 v217, v217, v175
	v_max_f32_e32 v218, v218, v176
	v_max_f32_e32 v219, v219, v177
	ds_bpermute_b32 v174, v193, v216
	ds_bpermute_b32 v175, v193, v217
	ds_bpermute_b32 v176, v193, v218
	ds_bpermute_b32 v177, v193, v219
	s_waitcnt lgkmcnt(0)
	v_max_f32_e32 v216, v216, v174
	v_max_f32_e32 v217, v217, v175
	v_max_f32_e32 v218, v218, v176
	v_max_f32_e32 v219, v219, v177
	ds_bpermute_b32 v174, v194, v216
	ds_bpermute_b32 v175, v194, v217
	ds_bpermute_b32 v176, v194, v218
	ds_bpermute_b32 v177, v194, v219
	s_waitcnt lgkmcnt(0)
	v_max_f32_e32 v216, v216, v174
	v_max_f32_e32 v217, v217, v175
	v_max_f32_e32 v218, v218, v176
	v_max_f32_e32 v219, v219, v177
	s_mov_b64 s[70:71], exec
	s_mov_b64 exec, 0xff
	ds_write_b128 v172, v[216:219]
	s_mov_b64 exec, s[70:71]
	s_waitcnt lgkmcnt(0)
	s_barrier
	ds_read_b128 v[140:143], v173 offset:0
	ds_read_b128 v[144:147], v173 offset:128
	ds_read_b128 v[148:151], v173 offset:256
	ds_read_b128 v[152:155], v173 offset:384
	ds_read_b128 v[156:159], v173 offset:512
	ds_read_b128 v[160:163], v173 offset:640
	ds_read_b128 v[164:167], v173 offset:768
	ds_read_b128 v[232:235], v173 offset:896
	s_waitcnt lgkmcnt(0)
	v_max3_f32 v220, v140, v144, v148
	v_max3_f32 v220, v220, v152, v156
	v_max3_f32 v220, v220, v160, v164
	v_max_f32_e32 v220, v220, v232
	v_max3_f32 v221, v141, v145, v149
	v_max3_f32 v221, v221, v153, v157
	v_max3_f32 v221, v221, v161, v165
	v_max_f32_e32 v221, v221, v233
	v_max3_f32 v222, v142, v146, v150
	v_max3_f32 v222, v222, v154, v158
	v_max3_f32 v222, v222, v162, v166
	v_max_f32_e32 v222, v222, v234
	v_max3_f32 v223, v143, v147, v151
	v_max3_f32 v223, v223, v155, v159
	v_max3_f32 v223, v223, v163, v167
	v_max_f32_e32 v223, v223, v235
	s_lshl_b32 s3, s11, 9
	s_lshl_b32 s10, s12, 8
	s_add_u32 s10, s10, s3
	s_add_u32 s66, s50, s10
	s_addc_u32 s67, s51, 0
	s_mov_b64 s[70:71], exec
	s_mov_b64 exec, 0xff
	s_cmp_lg_u32 s1, 0
	s_cbranch_scc1 .Lc32_gates_nopub
	v_mov_b32_e32 v249, s53
	v_mov_b32_e32 v248, v220
	global_store_dwordx2 v195, v[248:249], s[66:67] offset:0 sc0 sc1
	s_nop 1
	v_mov_b32_e32 v248, v221
	global_store_dwordx2 v195, v[248:249], s[66:67] offset:8 sc0 sc1
	s_nop 1
	v_mov_b32_e32 v248, v222
	global_store_dwordx2 v195, v[248:249], s[66:67] offset:16 sc0 sc1
	s_nop 1
	v_mov_b32_e32 v248, v223
	global_store_dwordx2 v195, v[248:249], s[66:67] offset:24 sc0 sc1
	s_nop 1
.Lc32_gates_nopub:
	s_xor_b32 s10, s10, 0x100
	s_add_u32 s66, s50, s10
	s_addc_u32 s67, s51, 0
	s_movk_i32 s54, 0x1000
.Lc32_gates_poll:
	global_load_dwordx2 v[240:241], v195, s[66:67] offset:0 sc0 sc1
	global_load_dwordx2 v[242:243], v195, s[66:67] offset:8 sc0 sc1
	global_load_dwordx2 v[244:245], v195, s[66:67] offset:16 sc0 sc1
	global_load_dwordx2 v[246:247], v195, s[66:67] offset:24 sc0 sc1
	s_waitcnt vmcnt(0)
	v_cmp_ne_u32_e32 vcc, s53, v241
	v_cmp_ne_u32_e64 s[56:57], s53, v243
	s_nop 1
	s_or_b64 vcc, vcc, s[56:57]
	v_cmp_ne_u32_e64 s[56:57], s53, v245
	s_nop 1
	s_or_b64 vcc, vcc, s[56:57]
	v_cmp_ne_u32_e64 s[56:57], s53, v247
	s_nop 1
	s_or_b64 vcc, vcc, s[56:57]
	s_nop 1
	s_and_b64 vcc, vcc, exec
	s_cbranch_vccz .Lc32_gates_got
	s_sleep 1
	s_sub_u32 s54, s54, 1
	s_cmp_lg_u32 s54, 0
	s_cbranch_scc1 .Lc32_gates_poll
.Lc32_gates_got:
	v_max_f32_e32 v220, v220, v240
	v_max_f32_e32 v221, v221, v242
	v_max_f32_e32 v222, v222, v244
	v_max_f32_e32 v223, v223, v246
	s_mov_b64 exec, s[70:71]
	v_lshlrev_b32_e32 v174, 2, v137
	ds_bpermute_b32 v175, v174, v220
	ds_bpermute_b32 v176, v174, v221
	ds_bpermute_b32 v177, v174, v222
	ds_bpermute_b32 v178, v174, v223
	s_waitcnt lgkmcnt(0)
	v_mov_b32_e32 v220, v175
	v_mov_b32_e32 v221, v176
	v_mov_b32_e32 v222, v177
	v_mov_b32_e32 v223, v178
	s_or_b32 s3, s1, s12
	s_cmp_lg_u32 s3, 0
	s_cbranch_scc1 .Lc32_gates_nocm
	s_lshl_b32 s3, s2, 2
	s_add_u32 s56, s34, s3
	s_addc_u32 s57, s35, 0
	s_add_u32 s56, s56, 0x80000
	s_addc_u32 s57, s57, 0
	s_mov_b64 s[70:71], exec
	s_mov_b64 exec, 0xff
	global_store_dwordx4 v230, v[220:223], s[56:57]
	s_mov_b64 exec, s[70:71]
.Lc32_gates_nocm:
	v_div_scale_f32 v175, s[70:71], v220, v220, s74
	v_rcp_f32_e32 v176, v175
	s_nop 0
	v_fma_f32 v177, -v175, v176, 1.0
	v_fmac_f32_e32 v176, v177, v176
	v_div_scale_f32 v177, vcc, s74, v220, s74
	v_mul_f32_e32 v178, v177, v176
	v_fma_f32 v180, -v175, v178, v177
	v_fmac_f32_e32 v178, v180, v176
	v_fma_f32 v175, -v175, v178, v177
	s_nop 0
	v_div_fmas_f32 v175, v175, v176, v178
	v_div_fixup_f32 v175, v175, v220, s74
	v_cmp_lt_f32_e32 vcc, 0, v220
	s_nop 1
	v_cndmask_b32_e32 v226, 0, v175, vcc
	v_div_scale_f32 v175, s[70:71], v221, v221, s74
	v_rcp_f32_e32 v176, v175
	s_nop 0
	v_fma_f32 v177, -v175, v176, 1.0
	v_fmac_f32_e32 v176, v177, v176
	v_div_scale_f32 v177, vcc, s74, v221, s74
	v_mul_f32_e32 v178, v177, v176
	v_fma_f32 v180, -v175, v178, v177
	v_fmac_f32_e32 v178, v180, v176
	v_fma_f32 v175, -v175, v178, v177
	s_nop 0
	v_div_fmas_f32 v175, v175, v176, v178
	v_div_fixup_f32 v175, v175, v221, s74
	v_cmp_lt_f32_e32 vcc, 0, v221
	s_nop 1
	v_cndmask_b32_e32 v227, 0, v175, vcc
	v_div_scale_f32 v175, s[70:71], v222, v222, s74
	v_rcp_f32_e32 v176, v175
	s_nop 0
	v_fma_f32 v177, -v175, v176, 1.0
	v_fmac_f32_e32 v176, v177, v176
	v_div_scale_f32 v177, vcc, s74, v222, s74
	v_mul_f32_e32 v178, v177, v176
	v_fma_f32 v180, -v175, v178, v177
	v_fmac_f32_e32 v178, v180, v176
	v_fma_f32 v175, -v175, v178, v177
	s_nop 0
	v_div_fmas_f32 v175, v175, v176, v178
	v_div_fixup_f32 v175, v175, v222, s74
	v_cmp_lt_f32_e32 vcc, 0, v222
	s_nop 1
	v_cndmask_b32_e32 v228, 0, v175, vcc
	v_div_scale_f32 v175, s[70:71], v223, v223, s74
	v_rcp_f32_e32 v176, v175
	s_nop 0
	v_fma_f32 v177, -v175, v176, 1.0
	v_fmac_f32_e32 v176, v177, v176
	v_div_scale_f32 v177, vcc, s74, v223, s74
	v_mul_f32_e32 v178, v177, v176
	v_fma_f32 v180, -v175, v178, v177
	v_fmac_f32_e32 v178, v180, v176
	v_fma_f32 v175, -v175, v178, v177
	s_nop 0
	v_div_fmas_f32 v175, v175, v176, v178
	v_div_fixup_f32 v175, v175, v223, s74
	v_cmp_lt_f32_e32 vcc, 0, v223
	s_nop 1
	v_cndmask_b32_e32 v229, 0, v175, vcc
	s_add_u32 s10, s0, 128
	s_lshl_b32 s3, s10, 7
	s_add_u32 s56, s48, s3
	s_addc_u32 s57, s49, 0
	v_mul_f32_e32 v186, v6, v226
	v_mul_f32_e32 v187, v7, v227
	v_rndne_f32_e32 v186, v186
	v_rndne_f32_e32 v187, v187
	v_cvt_i32_f32_sdwa v190, v186 dst_sel:BYTE_0 dst_unused:UNUSED_PAD src0_sel:DWORD
	v_cvt_i32_f32_sdwa v196, v187 dst_sel:BYTE_0 dst_unused:UNUSED_PAD src0_sel:DWORD
	v_mul_f32_e32 v186, v10, v226
	v_mul_f32_e32 v187, v11, v227
	v_rndne_f32_e32 v186, v186
	v_rndne_f32_e32 v187, v187
	v_cvt_i32_f32_sdwa v190, v186 dst_sel:BYTE_1 dst_unused:UNUSED_PRESERVE src0_sel:DWORD
	v_cvt_i32_f32_sdwa v196, v187 dst_sel:BYTE_1 dst_unused:UNUSED_PRESERVE src0_sel:DWORD
	v_mul_f32_e32 v186, v14, v226
	v_mul_f32_e32 v187, v15, v227
	v_rndne_f32_e32 v186, v186
	v_rndne_f32_e32 v187, v187
	v_cvt_i32_f32_sdwa v190, v186 dst_sel:BYTE_2 dst_unused:UNUSED_PRESERVE src0_sel:DWORD
	v_cvt_i32_f32_sdwa v196, v187 dst_sel:BYTE_2 dst_unused:UNUSED_PRESERVE src0_sel:DWORD
	v_mul_f32_e32 v186, v18, v226
	v_mul_f32_e32 v187, v19, v227
	v_rndne_f32_e32 v186, v186
	v_rndne_f32_e32 v187, v187
	v_cvt_i32_f32_sdwa v190, v186 dst_sel:BYTE_3 dst_unused:UNUSED_PRESERVE src0_sel:DWORD
	v_cvt_i32_f32_sdwa v196, v187 dst_sel:BYTE_3 dst_unused:UNUSED_PRESERVE src0_sel:DWORD
	s_nop 0
	ds_write_b32 v139, v190 offset:0
	ds_write_b32 v139, v196 offset:256
	v_mul_f32_e32 v186, v8, v228
	v_mul_f32_e32 v187, v9, v229
	v_rndne_f32_e32 v186, v186
	v_rndne_f32_e32 v187, v187
	v_cvt_i32_f32_sdwa v190, v186 dst_sel:BYTE_0 dst_unused:UNUSED_PAD src0_sel:DWORD
	v_cvt_i32_f32_sdwa v196, v187 dst_sel:BYTE_0 dst_unused:UNUSED_PAD src0_sel:DWORD
	v_mul_f32_e32 v186, v12, v228
	v_mul_f32_e32 v187, v13, v229
	v_rndne_f32_e32 v186, v186
	v_rndne_f32_e32 v187, v187
	v_cvt_i32_f32_sdwa v190, v186 dst_sel:BYTE_1 dst_unused:UNUSED_PRESERVE src0_sel:DWORD
	v_cvt_i32_f32_sdwa v196, v187 dst_sel:BYTE_1 dst_unused:UNUSED_PRESERVE src0_sel:DWORD
	v_mul_f32_e32 v186, v16, v228
	v_mul_f32_e32 v187, v17, v229
	v_rndne_f32_e32 v186, v186
	v_rndne_f32_e32 v187, v187
	v_cvt_i32_f32_sdwa v190, v186 dst_sel:BYTE_2 dst_unused:UNUSED_PRESERVE src0_sel:DWORD
	v_cvt_i32_f32_sdwa v196, v187 dst_sel:BYTE_2 dst_unused:UNUSED_PRESERVE src0_sel:DWORD
	v_mul_f32_e32 v186, v20, v228
	v_mul_f32_e32 v187, v21, v229
	v_rndne_f32_e32 v186, v186
	v_rndne_f32_e32 v187, v187
	v_cvt_i32_f32_sdwa v190, v186 dst_sel:BYTE_3 dst_unused:UNUSED_PRESERVE src0_sel:DWORD
	v_cvt_i32_f32_sdwa v196, v187 dst_sel:BYTE_3 dst_unused:UNUSED_PRESERVE src0_sel:DWORD
	s_nop 0
	ds_write_b32 v139, v190 offset:512
	ds_write_b32 v139, v196 offset:768
	s_cmp_ge_u32 s10, 0x100
	s_cbranch_scc1 .Lc32_gates_nopf_0
	global_load_dwordx4 v[6:9], v138, s[56:57]
	s_add_u32 s56, s56, 0x8000
	s_addc_u32 s57, s57, 0
	global_load_dwordx4 v[10:13], v138, s[56:57]
	s_add_u32 s56, s56, 0x8000
	s_addc_u32 s57, s57, 0
	global_load_dwordx4 v[14:17], v138, s[56:57]
	s_add_u32 s56, s56, 0x8000
	s_addc_u32 s57, s57, 0
	global_load_dwordx4 v[18:21], v138, s[56:57]
	s_add_u32 s56, s56, 0xe8000
	s_addc_u32 s57, s57, 0
.Lc32_gates_nopf_0:
	v_mul_f32_e32 v186, v22, v226
	v_mul_f32_e32 v187, v23, v227
	v_rndne_f32_e32 v186, v186
	v_rndne_f32_e32 v187, v187
	v_cvt_i32_f32_sdwa v190, v186 dst_sel:BYTE_0 dst_unused:UNUSED_PAD src0_sel:DWORD
	v_cvt_i32_f32_sdwa v196, v187 dst_sel:BYTE_0 dst_unused:UNUSED_PAD src0_sel:DWORD
	v_mul_f32_e32 v186, v26, v226
	v_mul_f32_e32 v187, v27, v227
	v_rndne_f32_e32 v186, v186
	v_rndne_f32_e32 v187, v187
	v_cvt_i32_f32_sdwa v190, v186 dst_sel:BYTE_1 dst_unused:UNUSED_PRESERVE src0_sel:DWORD
	v_cvt_i32_f32_sdwa v196, v187 dst_sel:BYTE_1 dst_unused:UNUSED_PRESERVE src0_sel:DWORD
	v_mul_f32_e32 v186, v30, v226
	v_mul_f32_e32 v187, v31, v227
	v_rndne_f32_e32 v186, v186
	v_rndne_f32_e32 v187, v187
	v_cvt_i32_f32_sdwa v190, v186 dst_sel:BYTE_2 dst_unused:UNUSED_PRESERVE src0_sel:DWORD
	v_cvt_i32_f32_sdwa v196, v187 dst_sel:BYTE_2 dst_unused:UNUSED_PRESERVE src0_sel:DWORD
	v_mul_f32_e32 v186, v34, v226
	v_mul_f32_e32 v187, v35, v227
	v_rndne_f32_e32 v186, v186
	v_rndne_f32_e32 v187, v187
	v_cvt_i32_f32_sdwa v190, v186 dst_sel:BYTE_3 dst_unused:UNUSED_PRESERVE src0_sel:DWORD
	v_cvt_i32_f32_sdwa v196, v187 dst_sel:BYTE_3 dst_unused:UNUSED_PRESERVE src0_sel:DWORD
	s_nop 0
	ds_write_b32 v139, v190 offset:32
	ds_write_b32 v139, v196 offset:288
	v_mul_f32_e32 v186, v24, v228
	v_mul_f32_e32 v187, v25, v229
	v_rndne_f32_e32 v186, v186
	v_rndne_f32_e32 v187, v187
	v_cvt_i32_f32_sdwa v190, v186 dst_sel:BYTE_0 dst_unused:UNUSED_PAD src0_sel:DWORD
	v_cvt_i32_f32_sdwa v196, v187 dst_sel:BYTE_0 dst_unused:UNUSED_PAD src0_sel:DWORD
	v_mul_f32_e32 v186, v28, v228
	v_mul_f32_e32 v187, v29, v229
	v_rndne_f32_e32 v186, v186
	v_rndne_f32_e32 v187, v187
	v_cvt_i32_f32_sdwa v190, v186 dst_sel:BYTE_1 dst_unused:UNUSED_PRESERVE src0_sel:DWORD
	v_cvt_i32_f32_sdwa v196, v187 dst_sel:BYTE_1 dst_unused:UNUSED_PRESERVE src0_sel:DWORD
	v_mul_f32_e32 v186, v32, v228
	v_mul_f32_e32 v187, v33, v229
	v_rndne_f32_e32 v186, v186
	v_rndne_f32_e32 v187, v187
	v_cvt_i32_f32_sdwa v190, v186 dst_sel:BYTE_2 dst_unused:UNUSED_PRESERVE src0_sel:DWORD
	v_cvt_i32_f32_sdwa v196, v187 dst_sel:BYTE_2 dst_unused:UNUSED_PRESERVE src0_sel:DWORD
	v_mul_f32_e32 v186, v36, v228
	v_mul_f32_e32 v187, v37, v229
	v_rndne_f32_e32 v186, v186
	v_rndne_f32_e32 v187, v187
	v_cvt_i32_f32_sdwa v190, v186 dst_sel:BYTE_3 dst_unused:UNUSED_PRESERVE src0_sel:DWORD
	v_cvt_i32_f32_sdwa v196, v187 dst_sel:BYTE_3 dst_unused:UNUSED_PRESERVE src0_sel:DWORD
	s_nop 0
	ds_write_b32 v139, v190 offset:544
	ds_write_b32 v139, v196 offset:800
	s_cmp_ge_u32 s10, 0x100
	s_cbranch_scc1 .Lc32_gates_nopf_1
	global_load_dwordx4 v[22:25], v138, s[56:57]
	s_add_u32 s56, s56, 0x8000
	s_addc_u32 s57, s57, 0
	global_load_dwordx4 v[26:29], v138, s[56:57]
	s_add_u32 s56, s56, 0x8000
	s_addc_u32 s57, s57, 0
	global_load_dwordx4 v[30:33], v138, s[56:57]
	s_add_u32 s56, s56, 0x8000
	s_addc_u32 s57, s57, 0
	global_load_dwordx4 v[34:37], v138, s[56:57]
	s_add_u32 s56, s56, 0xe8000
	s_addc_u32 s57, s57, 0
.Lc32_gates_nopf_1:
	v_mul_f32_e32 v186, v38, v226
	v_mul_f32_e32 v187, v39, v227
	v_rndne_f32_e32 v186, v186
	v_rndne_f32_e32 v187, v187
	v_cvt_i32_f32_sdwa v190, v186 dst_sel:BYTE_0 dst_unused:UNUSED_PAD src0_sel:DWORD
	v_cvt_i32_f32_sdwa v196, v187 dst_sel:BYTE_0 dst_unused:UNUSED_PAD src0_sel:DWORD
	v_mul_f32_e32 v186, v42, v226
	v_mul_f32_e32 v187, v43, v227
	v_rndne_f32_e32 v186, v186
	v_rndne_f32_e32 v187, v187
	v_cvt_i32_f32_sdwa v190, v186 dst_sel:BYTE_1 dst_unused:UNUSED_PRESERVE src0_sel:DWORD
	v_cvt_i32_f32_sdwa v196, v187 dst_sel:BYTE_1 dst_unused:UNUSED_PRESERVE src0_sel:DWORD
	v_mul_f32_e32 v186, v46, v226
	v_mul_f32_e32 v187, v47, v227
	v_rndne_f32_e32 v186, v186
	v_rndne_f32_e32 v187, v187
	v_cvt_i32_f32_sdwa v190, v186 dst_sel:BYTE_2 dst_unused:UNUSED_PRESERVE src0_sel:DWORD
	v_cvt_i32_f32_sdwa v196, v187 dst_sel:BYTE_2 dst_unused:UNUSED_PRESERVE src0_sel:DWORD
	v_mul_f32_e32 v186, v50, v226
	v_mul_f32_e32 v187, v51, v227
	v_rndne_f32_e32 v186, v186
	v_rndne_f32_e32 v187, v187
	v_cvt_i32_f32_sdwa v190, v186 dst_sel:BYTE_3 dst_unused:UNUSED_PRESERVE src0_sel:DWORD
	v_cvt_i32_f32_sdwa v196, v187 dst_sel:BYTE_3 dst_unused:UNUSED_PRESERVE src0_sel:DWORD
	s_nop 0
	ds_write_b32 v139, v190 offset:64
	ds_write_b32 v139, v196 offset:320
	v_mul_f32_e32 v186, v40, v228
	v_mul_f32_e32 v187, v41, v229
	v_rndne_f32_e32 v186, v186
	v_rndne_f32_e32 v187, v187
	v_cvt_i32_f32_sdwa v190, v186 dst_sel:BYTE_0 dst_unused:UNUSED_PAD src0_sel:DWORD
	v_cvt_i32_f32_sdwa v196, v187 dst_sel:BYTE_0 dst_unused:UNUSED_PAD src0_sel:DWORD
	v_mul_f32_e32 v186, v44, v228
	v_mul_f32_e32 v187, v45, v229
	v_rndne_f32_e32 v186, v186
	v_rndne_f32_e32 v187, v187
	v_cvt_i32_f32_sdwa v190, v186 dst_sel:BYTE_1 dst_unused:UNUSED_PRESERVE src0_sel:DWORD
	v_cvt_i32_f32_sdwa v196, v187 dst_sel:BYTE_1 dst_unused:UNUSED_PRESERVE src0_sel:DWORD
	v_mul_f32_e32 v186, v48, v228
	v_mul_f32_e32 v187, v49, v229
	v_rndne_f32_e32 v186, v186
	v_rndne_f32_e32 v187, v187
	v_cvt_i32_f32_sdwa v190, v186 dst_sel:BYTE_2 dst_unused:UNUSED_PRESERVE src0_sel:DWORD
	v_cvt_i32_f32_sdwa v196, v187 dst_sel:BYTE_2 dst_unused:UNUSED_PRESERVE src0_sel:DWORD
	v_mul_f32_e32 v186, v52, v228
	v_mul_f32_e32 v187, v53, v229
	v_rndne_f32_e32 v186, v186
	v_rndne_f32_e32 v187, v187
	v_cvt_i32_f32_sdwa v190, v186 dst_sel:BYTE_3 dst_unused:UNUSED_PRESERVE src0_sel:DWORD
	v_cvt_i32_f32_sdwa v196, v187 dst_sel:BYTE_3 dst_unused:UNUSED_PRESERVE src0_sel:DWORD
	s_nop 0
	ds_write_b32 v139, v190 offset:576
	ds_write_b32 v139, v196 offset:832
	s_cmp_ge_u32 s10, 0x100
	s_cbranch_scc1 .Lc32_gates_nopf_2
	global_load_dwordx4 v[38:41], v138, s[56:57]
	s_add_u32 s56, s56, 0x8000
	s_addc_u32 s57, s57, 0
	global_load_dwordx4 v[42:45], v138, s[56:57]
	s_add_u32 s56, s56, 0x8000
	s_addc_u32 s57, s57, 0
	global_load_dwordx4 v[46:49], v138, s[56:57]
	s_add_u32 s56, s56, 0x8000
	s_addc_u32 s57, s57, 0
	global_load_dwordx4 v[50:53], v138, s[56:57]
	s_add_u32 s56, s56, 0xe8000
	s_addc_u32 s57, s57, 0
.Lc32_gates_nopf_2:
	v_mul_f32_e32 v186, v54, v226
	v_mul_f32_e32 v187, v55, v227
	v_rndne_f32_e32 v186, v186
	v_rndne_f32_e32 v187, v187
	v_cvt_i32_f32_sdwa v190, v186 dst_sel:BYTE_0 dst_unused:UNUSED_PAD src0_sel:DWORD
	v_cvt_i32_f32_sdwa v196, v187 dst_sel:BYTE_0 dst_unused:UNUSED_PAD src0_sel:DWORD
	v_mul_f32_e32 v186, v58, v226
	v_mul_f32_e32 v187, v59, v227
	v_rndne_f32_e32 v186, v186
	v_rndne_f32_e32 v187, v187
	v_cvt_i32_f32_sdwa v190, v186 dst_sel:BYTE_1 dst_unused:UNUSED_PRESERVE src0_sel:DWORD
	v_cvt_i32_f32_sdwa v196, v187 dst_sel:BYTE_1 dst_unused:UNUSED_PRESERVE src0_sel:DWORD
	v_mul_f32_e32 v186, v62, v226
	v_mul_f32_e32 v187, v63, v227
	v_rndne_f32_e32 v186, v186
	v_rndne_f32_e32 v187, v187
	v_cvt_i32_f32_sdwa v190, v186 dst_sel:BYTE_2 dst_unused:UNUSED_PRESERVE src0_sel:DWORD
	v_cvt_i32_f32_sdwa v196, v187 dst_sel:BYTE_2 dst_unused:UNUSED_PRESERVE src0_sel:DWORD
	v_mul_f32_e32 v186, v66, v226
	v_mul_f32_e32 v187, v67, v227
	v_rndne_f32_e32 v186, v186
	v_rndne_f32_e32 v187, v187
	v_cvt_i32_f32_sdwa v190, v186 dst_sel:BYTE_3 dst_unused:UNUSED_PRESERVE src0_sel:DWORD
	v_cvt_i32_f32_sdwa v196, v187 dst_sel:BYTE_3 dst_unused:UNUSED_PRESERVE src0_sel:DWORD
	s_nop 0
	ds_write_b32 v139, v190 offset:96
	ds_write_b32 v139, v196 offset:352
	v_mul_f32_e32 v186, v56, v228
	v_mul_f32_e32 v187, v57, v229
	v_rndne_f32_e32 v186, v186
	v_rndne_f32_e32 v187, v187
	v_cvt_i32_f32_sdwa v190, v186 dst_sel:BYTE_0 dst_unused:UNUSED_PAD src0_sel:DWORD
	v_cvt_i32_f32_sdwa v196, v187 dst_sel:BYTE_0 dst_unused:UNUSED_PAD src0_sel:DWORD
	v_mul_f32_e32 v186, v60, v228
	v_mul_f32_e32 v187, v61, v229
	v_rndne_f32_e32 v186, v186
	v_rndne_f32_e32 v187, v187
	v_cvt_i32_f32_sdwa v190, v186 dst_sel:BYTE_1 dst_unused:UNUSED_PRESERVE src0_sel:DWORD
	v_cvt_i32_f32_sdwa v196, v187 dst_sel:BYTE_1 dst_unused:UNUSED_PRESERVE src0_sel:DWORD
	v_mul_f32_e32 v186, v64, v228
	v_mul_f32_e32 v187, v65, v229
	v_rndne_f32_e32 v186, v186
	v_rndne_f32_e32 v187, v187
	v_cvt_i32_f32_sdwa v190, v186 dst_sel:BYTE_2 dst_unused:UNUSED_PRESERVE src0_sel:DWORD
	v_cvt_i32_f32_sdwa v196, v187 dst_sel:BYTE_2 dst_unused:UNUSED_PRESERVE src0_sel:DWORD
	v_mul_f32_e32 v186, v68, v228
	v_mul_f32_e32 v187, v69, v229
	v_rndne_f32_e32 v186, v186
	v_rndne_f32_e32 v187, v187
	v_cvt_i32_f32_sdwa v190, v186 dst_sel:BYTE_3 dst_unused:UNUSED_PRESERVE src0_sel:DWORD
	v_cvt_i32_f32_sdwa v196, v187 dst_sel:BYTE_3 dst_unused:UNUSED_PRESERVE src0_sel:DWORD
	s_nop 0
	ds_write_b32 v139, v190 offset:608
	ds_write_b32 v139, v196 offset:864
	s_cmp_ge_u32 s10, 0x100
	s_cbranch_scc1 .Lc32_gates_nopf_3
	global_load_dwordx4 v[54:57], v138, s[56:57]
	s_add_u32 s56, s56, 0x8000
	s_addc_u32 s57, s57, 0
	global_load_dwordx4 v[58:61], v138, s[56:57]
	s_add_u32 s56, s56, 0x8000
	s_addc_u32 s57, s57, 0
	global_load_dwordx4 v[62:65], v138, s[56:57]
	s_add_u32 s56, s56, 0x8000
	s_addc_u32 s57, s57, 0
	global_load_dwordx4 v[66:69], v138, s[56:57]
	s_add_u32 s56, s56, 0xe8000
	s_addc_u32 s57, s57, 0
.Lc32_gates_nopf_3:
	v_mul_f32_e32 v186, v70, v226
	v_mul_f32_e32 v187, v71, v227
	v_rndne_f32_e32 v186, v186
	v_rndne_f32_e32 v187, v187
	v_cvt_i32_f32_sdwa v190, v186 dst_sel:BYTE_0 dst_unused:UNUSED_PAD src0_sel:DWORD
	v_cvt_i32_f32_sdwa v196, v187 dst_sel:BYTE_0 dst_unused:UNUSED_PAD src0_sel:DWORD
	v_mul_f32_e32 v186, v74, v226
	v_mul_f32_e32 v187, v75, v227
	v_rndne_f32_e32 v186, v186
	v_rndne_f32_e32 v187, v187
	v_cvt_i32_f32_sdwa v190, v186 dst_sel:BYTE_1 dst_unused:UNUSED_PRESERVE src0_sel:DWORD
	v_cvt_i32_f32_sdwa v196, v187 dst_sel:BYTE_1 dst_unused:UNUSED_PRESERVE src0_sel:DWORD
	v_mul_f32_e32 v186, v78, v226
	v_mul_f32_e32 v187, v79, v227
	v_rndne_f32_e32 v186, v186
	v_rndne_f32_e32 v187, v187
	v_cvt_i32_f32_sdwa v190, v186 dst_sel:BYTE_2 dst_unused:UNUSED_PRESERVE src0_sel:DWORD
	v_cvt_i32_f32_sdwa v196, v187 dst_sel:BYTE_2 dst_unused:UNUSED_PRESERVE src0_sel:DWORD
	v_mul_f32_e32 v186, v82, v226
	v_mul_f32_e32 v187, v83, v227
	v_rndne_f32_e32 v186, v186
	v_rndne_f32_e32 v187, v187
	v_cvt_i32_f32_sdwa v190, v186 dst_sel:BYTE_3 dst_unused:UNUSED_PRESERVE src0_sel:DWORD
	v_cvt_i32_f32_sdwa v196, v187 dst_sel:BYTE_3 dst_unused:UNUSED_PRESERVE src0_sel:DWORD
	s_nop 0
	ds_write_b32 v139, v190 offset:128
	ds_write_b32 v139, v196 offset:384
	v_mul_f32_e32 v186, v72, v228
	v_mul_f32_e32 v187, v73, v229
	v_rndne_f32_e32 v186, v186
	v_rndne_f32_e32 v187, v187
	v_cvt_i32_f32_sdwa v190, v186 dst_sel:BYTE_0 dst_unused:UNUSED_PAD src0_sel:DWORD
	v_cvt_i32_f32_sdwa v196, v187 dst_sel:BYTE_0 dst_unused:UNUSED_PAD src0_sel:DWORD
	v_mul_f32_e32 v186, v76, v228
	v_mul_f32_e32 v187, v77, v229
	v_rndne_f32_e32 v186, v186
	v_rndne_f32_e32 v187, v187
	v_cvt_i32_f32_sdwa v190, v186 dst_sel:BYTE_1 dst_unused:UNUSED_PRESERVE src0_sel:DWORD
	v_cvt_i32_f32_sdwa v196, v187 dst_sel:BYTE_1 dst_unused:UNUSED_PRESERVE src0_sel:DWORD
	v_mul_f32_e32 v186, v80, v228
	v_mul_f32_e32 v187, v81, v229
	v_rndne_f32_e32 v186, v186
	v_rndne_f32_e32 v187, v187
	v_cvt_i32_f32_sdwa v190, v186 dst_sel:BYTE_2 dst_unused:UNUSED_PRESERVE src0_sel:DWORD
	v_cvt_i32_f32_sdwa v196, v187 dst_sel:BYTE_2 dst_unused:UNUSED_PRESERVE src0_sel:DWORD
	v_mul_f32_e32 v186, v84, v228
	v_mul_f32_e32 v187, v85, v229
	v_rndne_f32_e32 v186, v186
	v_rndne_f32_e32 v187, v187
	v_cvt_i32_f32_sdwa v190, v186 dst_sel:BYTE_3 dst_unused:UNUSED_PRESERVE src0_sel:DWORD
	v_cvt_i32_f32_sdwa v196, v187 dst_sel:BYTE_3 dst_unused:UNUSED_PRESERVE src0_sel:DWORD
	s_nop 0
	ds_write_b32 v139, v190 offset:640
	ds_write_b32 v139, v196 offset:896
	s_cmp_ge_u32 s10, 0x100
	s_cbranch_scc1 .Lc32_gates_nopf_4
	global_load_dwordx4 v[70:73], v138, s[56:57]
	s_add_u32 s56, s56, 0x8000
	s_addc_u32 s57, s57, 0
	global_load_dwordx4 v[74:77], v138, s[56:57]
	s_add_u32 s56, s56, 0x8000
	s_addc_u32 s57, s57, 0
	global_load_dwordx4 v[78:81], v138, s[56:57]
	s_add_u32 s56, s56, 0x8000
	s_addc_u32 s57, s57, 0
	global_load_dwordx4 v[82:85], v138, s[56:57]
	s_add_u32 s56, s56, 0xe8000
	s_addc_u32 s57, s57, 0
.Lc32_gates_nopf_4:
	v_mul_f32_e32 v186, v86, v226
	v_mul_f32_e32 v187, v87, v227
	v_rndne_f32_e32 v186, v186
	v_rndne_f32_e32 v187, v187
	v_cvt_i32_f32_sdwa v190, v186 dst_sel:BYTE_0 dst_unused:UNUSED_PAD src0_sel:DWORD
	v_cvt_i32_f32_sdwa v196, v187 dst_sel:BYTE_0 dst_unused:UNUSED_PAD src0_sel:DWORD
	v_mul_f32_e32 v186, v90, v226
	v_mul_f32_e32 v187, v91, v227
	v_rndne_f32_e32 v186, v186
	v_rndne_f32_e32 v187, v187
	v_cvt_i32_f32_sdwa v190, v186 dst_sel:BYTE_1 dst_unused:UNUSED_PRESERVE src0_sel:DWORD
	v_cvt_i32_f32_sdwa v196, v187 dst_sel:BYTE_1 dst_unused:UNUSED_PRESERVE src0_sel:DWORD
	v_mul_f32_e32 v186, v94, v226
	v_mul_f32_e32 v187, v95, v227
	v_rndne_f32_e32 v186, v186
	v_rndne_f32_e32 v187, v187
	v_cvt_i32_f32_sdwa v190, v186 dst_sel:BYTE_2 dst_unused:UNUSED_PRESERVE src0_sel:DWORD
	v_cvt_i32_f32_sdwa v196, v187 dst_sel:BYTE_2 dst_unused:UNUSED_PRESERVE src0_sel:DWORD
	v_mul_f32_e32 v186, v98, v226
	v_mul_f32_e32 v187, v99, v227
	v_rndne_f32_e32 v186, v186
	v_rndne_f32_e32 v187, v187
	v_cvt_i32_f32_sdwa v190, v186 dst_sel:BYTE_3 dst_unused:UNUSED_PRESERVE src0_sel:DWORD
	v_cvt_i32_f32_sdwa v196, v187 dst_sel:BYTE_3 dst_unused:UNUSED_PRESERVE src0_sel:DWORD
	s_nop 0
	ds_write_b32 v139, v190 offset:160
	ds_write_b32 v139, v196 offset:416
	v_mul_f32_e32 v186, v88, v228
	v_mul_f32_e32 v187, v89, v229
	v_rndne_f32_e32 v186, v186
	v_rndne_f32_e32 v187, v187
	v_cvt_i32_f32_sdwa v190, v186 dst_sel:BYTE_0 dst_unused:UNUSED_PAD src0_sel:DWORD
	v_cvt_i32_f32_sdwa v196, v187 dst_sel:BYTE_0 dst_unused:UNUSED_PAD src0_sel:DWORD
	v_mul_f32_e32 v186, v92, v228
	v_mul_f32_e32 v187, v93, v229
	v_rndne_f32_e32 v186, v186
	v_rndne_f32_e32 v187, v187
	v_cvt_i32_f32_sdwa v190, v186 dst_sel:BYTE_1 dst_unused:UNUSED_PRESERVE src0_sel:DWORD
	v_cvt_i32_f32_sdwa v196, v187 dst_sel:BYTE_1 dst_unused:UNUSED_PRESERVE src0_sel:DWORD
	v_mul_f32_e32 v186, v96, v228
	v_mul_f32_e32 v187, v97, v229
	v_rndne_f32_e32 v186, v186
	v_rndne_f32_e32 v187, v187
	v_cvt_i32_f32_sdwa v190, v186 dst_sel:BYTE_2 dst_unused:UNUSED_PRESERVE src0_sel:DWORD
	v_cvt_i32_f32_sdwa v196, v187 dst_sel:BYTE_2 dst_unused:UNUSED_PRESERVE src0_sel:DWORD
	v_mul_f32_e32 v186, v100, v228
	v_mul_f32_e32 v187, v101, v229
	v_rndne_f32_e32 v186, v186
	v_rndne_f32_e32 v187, v187
	v_cvt_i32_f32_sdwa v190, v186 dst_sel:BYTE_3 dst_unused:UNUSED_PRESERVE src0_sel:DWORD
	v_cvt_i32_f32_sdwa v196, v187 dst_sel:BYTE_3 dst_unused:UNUSED_PRESERVE src0_sel:DWORD
	s_nop 0
	ds_write_b32 v139, v190 offset:672
	ds_write_b32 v139, v196 offset:928
	s_cmp_ge_u32 s10, 0x100
	s_cbranch_scc1 .Lc32_gates_nopf_5
	global_load_dwordx4 v[86:89], v138, s[56:57]
	s_add_u32 s56, s56, 0x8000
	s_addc_u32 s57, s57, 0
	global_load_dwordx4 v[90:93], v138, s[56:57]
	s_add_u32 s56, s56, 0x8000
	s_addc_u32 s57, s57, 0
	global_load_dwordx4 v[94:97], v138, s[56:57]
	s_add_u32 s56, s56, 0x8000
	s_addc_u32 s57, s57, 0
	global_load_dwordx4 v[98:101], v138, s[56:57]
	s_add_u32 s56, s56, 0xe8000
	s_addc_u32 s57, s57, 0
.Lc32_gates_nopf_5:
	v_mul_f32_e32 v186, v102, v226
	v_mul_f32_e32 v187, v103, v227
	v_rndne_f32_e32 v186, v186
	v_rndne_f32_e32 v187, v187
	v_cvt_i32_f32_sdwa v190, v186 dst_sel:BYTE_0 dst_unused:UNUSED_PAD src0_sel:DWORD
	v_cvt_i32_f32_sdwa v196, v187 dst_sel:BYTE_0 dst_unused:UNUSED_PAD src0_sel:DWORD
	v_mul_f32_e32 v186, v106, v226
	v_mul_f32_e32 v187, v107, v227
	v_rndne_f32_e32 v186, v186
	v_rndne_f32_e32 v187, v187
	v_cvt_i32_f32_sdwa v190, v186 dst_sel:BYTE_1 dst_unused:UNUSED_PRESERVE src0_sel:DWORD
	v_cvt_i32_f32_sdwa v196, v187 dst_sel:BYTE_1 dst_unused:UNUSED_PRESERVE src0_sel:DWORD
	v_mul_f32_e32 v186, v110, v226
	v_mul_f32_e32 v187, v111, v227
	v_rndne_f32_e32 v186, v186
	v_rndne_f32_e32 v187, v187
	v_cvt_i32_f32_sdwa v190, v186 dst_sel:BYTE_2 dst_unused:UNUSED_PRESERVE src0_sel:DWORD
	v_cvt_i32_f32_sdwa v196, v187 dst_sel:BYTE_2 dst_unused:UNUSED_PRESERVE src0_sel:DWORD
	v_mul_f32_e32 v186, v114, v226
	v_mul_f32_e32 v187, v115, v227
	v_rndne_f32_e32 v186, v186
	v_rndne_f32_e32 v187, v187
	v_cvt_i32_f32_sdwa v190, v186 dst_sel:BYTE_3 dst_unused:UNUSED_PRESERVE src0_sel:DWORD
	v_cvt_i32_f32_sdwa v196, v187 dst_sel:BYTE_3 dst_unused:UNUSED_PRESERVE src0_sel:DWORD
	s_nop 0
	ds_write_b32 v139, v190 offset:192
	ds_write_b32 v139, v196 offset:448
	v_mul_f32_e32 v186, v104, v228
	v_mul_f32_e32 v187, v105, v229
	v_rndne_f32_e32 v186, v186
	v_rndne_f32_e32 v187, v187
	v_cvt_i32_f32_sdwa v190, v186 dst_sel:BYTE_0 dst_unused:UNUSED_PAD src0_sel:DWORD
	v_cvt_i32_f32_sdwa v196, v187 dst_sel:BYTE_0 dst_unused:UNUSED_PAD src0_sel:DWORD
	v_mul_f32_e32 v186, v108, v228
	v_mul_f32_e32 v187, v109, v229
	v_rndne_f32_e32 v186, v186
	v_rndne_f32_e32 v187, v187
	v_cvt_i32_f32_sdwa v190, v186 dst_sel:BYTE_1 dst_unused:UNUSED_PRESERVE src0_sel:DWORD
	v_cvt_i32_f32_sdwa v196, v187 dst_sel:BYTE_1 dst_unused:UNUSED_PRESERVE src0_sel:DWORD
	v_mul_f32_e32 v186, v112, v228
	v_mul_f32_e32 v187, v113, v229
	v_rndne_f32_e32 v186, v186
	v_rndne_f32_e32 v187, v187
	v_cvt_i32_f32_sdwa v190, v186 dst_sel:BYTE_2 dst_unused:UNUSED_PRESERVE src0_sel:DWORD
	v_cvt_i32_f32_sdwa v196, v187 dst_sel:BYTE_2 dst_unused:UNUSED_PRESERVE src0_sel:DWORD
	v_mul_f32_e32 v186, v116, v228
	v_mul_f32_e32 v187, v117, v229
	v_rndne_f32_e32 v186, v186
	v_rndne_f32_e32 v187, v187
	v_cvt_i32_f32_sdwa v190, v186 dst_sel:BYTE_3 dst_unused:UNUSED_PRESERVE src0_sel:DWORD
	v_cvt_i32_f32_sdwa v196, v187 dst_sel:BYTE_3 dst_unused:UNUSED_PRESERVE src0_sel:DWORD
	s_nop 0
	ds_write_b32 v139, v190 offset:704
	ds_write_b32 v139, v196 offset:960
	s_cmp_ge_u32 s10, 0x100
	s_cbranch_scc1 .Lc32_gates_nopf_6
	global_load_dwordx4 v[102:105], v138, s[56:57]
	s_add_u32 s56, s56, 0x8000
	s_addc_u32 s57, s57, 0
	global_load_dwordx4 v[106:109], v138, s[56:57]
	s_add_u32 s56, s56, 0x8000
	s_addc_u32 s57, s57, 0
	global_load_dwordx4 v[110:113], v138, s[56:57]
	s_add_u32 s56, s56, 0x8000
	s_addc_u32 s57, s57, 0
	global_load_dwordx4 v[114:117], v138, s[56:57]
	s_add_u32 s56, s56, 0xe8000
	s_addc_u32 s57, s57, 0
.Lc32_gates_nopf_6:
	v_mul_f32_e32 v186, v118, v226
	v_mul_f32_e32 v187, v119, v227
	v_rndne_f32_e32 v186, v186
	v_rndne_f32_e32 v187, v187
	v_cvt_i32_f32_sdwa v190, v186 dst_sel:BYTE_0 dst_unused:UNUSED_PAD src0_sel:DWORD
	v_cvt_i32_f32_sdwa v196, v187 dst_sel:BYTE_0 dst_unused:UNUSED_PAD src0_sel:DWORD
	v_mul_f32_e32 v186, v122, v226
	v_mul_f32_e32 v187, v123, v227
	v_rndne_f32_e32 v186, v186
	v_rndne_f32_e32 v187, v187
	v_cvt_i32_f32_sdwa v190, v186 dst_sel:BYTE_1 dst_unused:UNUSED_PRESERVE src0_sel:DWORD
	v_cvt_i32_f32_sdwa v196, v187 dst_sel:BYTE_1 dst_unused:UNUSED_PRESERVE src0_sel:DWORD
	v_mul_f32_e32 v186, v126, v226
	v_mul_f32_e32 v187, v127, v227
	v_rndne_f32_e32 v186, v186
	v_rndne_f32_e32 v187, v187
	v_cvt_i32_f32_sdwa v190, v186 dst_sel:BYTE_2 dst_unused:UNUSED_PRESERVE src0_sel:DWORD
	v_cvt_i32_f32_sdwa v196, v187 dst_sel:BYTE_2 dst_unused:UNUSED_PRESERVE src0_sel:DWORD
	v_mul_f32_e32 v186, v130, v226
	v_mul_f32_e32 v187, v131, v227
	v_rndne_f32_e32 v186, v186
	v_rndne_f32_e32 v187, v187
	v_cvt_i32_f32_sdwa v190, v186 dst_sel:BYTE_3 dst_unused:UNUSED_PRESERVE src0_sel:DWORD
	v_cvt_i32_f32_sdwa v196, v187 dst_sel:BYTE_3 dst_unused:UNUSED_PRESERVE src0_sel:DWORD
	s_nop 0
	ds_write_b32 v139, v190 offset:224
	ds_write_b32 v139, v196 offset:480
	v_mul_f32_e32 v186, v120, v228
	v_mul_f32_e32 v187, v121, v229
	v_rndne_f32_e32 v186, v186
	v_rndne_f32_e32 v187, v187
	v_cvt_i32_f32_sdwa v190, v186 dst_sel:BYTE_0 dst_unused:UNUSED_PAD src0_sel:DWORD
	v_cvt_i32_f32_sdwa v196, v187 dst_sel:BYTE_0 dst_unused:UNUSED_PAD src0_sel:DWORD
	v_mul_f32_e32 v186, v124, v228
	v_mul_f32_e32 v187, v125, v229
	v_rndne_f32_e32 v186, v186
	v_rndne_f32_e32 v187, v187
	v_cvt_i32_f32_sdwa v190, v186 dst_sel:BYTE_1 dst_unused:UNUSED_PRESERVE src0_sel:DWORD
	v_cvt_i32_f32_sdwa v196, v187 dst_sel:BYTE_1 dst_unused:UNUSED_PRESERVE src0_sel:DWORD
	v_mul_f32_e32 v186, v128, v228
	v_mul_f32_e32 v187, v129, v229
	v_rndne_f32_e32 v186, v186
	v_rndne_f32_e32 v187, v187
	v_cvt_i32_f32_sdwa v190, v186 dst_sel:BYTE_2 dst_unused:UNUSED_PRESERVE src0_sel:DWORD
	v_cvt_i32_f32_sdwa v196, v187 dst_sel:BYTE_2 dst_unused:UNUSED_PRESERVE src0_sel:DWORD
	v_mul_f32_e32 v186, v132, v228
	v_mul_f32_e32 v187, v133, v229
	v_rndne_f32_e32 v186, v186
	v_rndne_f32_e32 v187, v187
	v_cvt_i32_f32_sdwa v190, v186 dst_sel:BYTE_3 dst_unused:UNUSED_PRESERVE src0_sel:DWORD
	v_cvt_i32_f32_sdwa v196, v187 dst_sel:BYTE_3 dst_unused:UNUSED_PRESERVE src0_sel:DWORD
	s_nop 0
	ds_write_b32 v139, v190 offset:736
	ds_write_b32 v139, v196 offset:992
	s_cmp_ge_u32 s10, 0x100
	s_cbranch_scc1 .Lc32_gates_nopf_7
	global_load_dwordx4 v[118:121], v138, s[56:57]
	s_add_u32 s56, s56, 0x8000
	s_addc_u32 s57, s57, 0
	global_load_dwordx4 v[122:125], v138, s[56:57]
	s_add_u32 s56, s56, 0x8000
	s_addc_u32 s57, s57, 0
	global_load_dwordx4 v[126:129], v138, s[56:57]
	s_add_u32 s56, s56, 0x8000
	s_addc_u32 s57, s57, 0
	global_load_dwordx4 v[130:133], v138, s[56:57]
.Lc32_gates_nopf_7:
	s_waitcnt lgkmcnt(0)
	s_lshl_b32 s3, s60, 12
	s_add_u32 s3, s3, s52
	s_add_u32 s58, s34, s3
	s_addc_u32 s59, s35, 0
	s_add_u32 s58, s58, 0x5100000
	s_addc_u32 s59, s59, 0
	ds_read_b128 v[204:207], v212 offset:0
	s_waitcnt lgkmcnt(0)
	global_store_dwordx4 v213, v[204:207], s[58:59]
	s_add_u32 s58, s58, 0x4000
	s_addc_u32 s59, s59, 0
	ds_read_b128 v[208:211], v212 offset:1024
	s_waitcnt lgkmcnt(0)
	global_store_dwordx4 v213, v[208:211], s[58:59]
	s_add_u32 s58, s58, 0x4000
	s_addc_u32 s59, s59, 0
	ds_read_b128 v[204:207], v212 offset:2048
	s_waitcnt lgkmcnt(0)
	global_store_dwordx4 v213, v[204:207], s[58:59]
	s_add_u32 s58, s58, 0x4000
	s_addc_u32 s59, s59, 0
	ds_read_b128 v[208:211], v212 offset:3072
	s_waitcnt lgkmcnt(0)
	global_store_dwordx4 v213, v[208:211], s[58:59]
	s_add_u32 s58, s58, 0x4000
	s_addc_u32 s59, s59, 0
	ds_read_b128 v[204:207], v212 offset:4096
	s_waitcnt lgkmcnt(0)
	global_store_dwordx4 v213, v[204:207], s[58:59]
	s_add_u32 s58, s58, 0x4000
	s_addc_u32 s59, s59, 0
	ds_read_b128 v[208:211], v212 offset:5120
	s_waitcnt lgkmcnt(0)
	global_store_dwordx4 v213, v[208:211], s[58:59]
	s_add_u32 s58, s58, 0x4000
	s_addc_u32 s59, s59, 0
	ds_read_b128 v[204:207], v212 offset:6144
	s_waitcnt lgkmcnt(0)
	global_store_dwordx4 v213, v[204:207], s[58:59]
	s_add_u32 s58, s58, 0x4000
	s_addc_u32 s59, s59, 0
	ds_read_b128 v[208:211], v212 offset:7168
	s_waitcnt lgkmcnt(0)
	global_store_dwordx4 v213, v[208:211], s[58:59]
	s_xor_b32 s11, s11, 1
	s_add_u32 s0, s0, 128
	s_cmp_lt_u32 s0, 0x100
	s_cbranch_scc1 .Lc32_gates_loop
.Lc32_gates_done:
	v_readlane_b32 s48, v255, 19
	v_readlane_b32 s49, v255, 20
	v_mul_u32_u24_e32 v138, 0x56000, v136
	v_lshl_add_u32 v138, v137, 4, v138
	s_mul_i32 s3, s52, 0x15800
	s_nop 1
	s_add_u32 s48, s48, s3
	s_addc_u32 s49, s49, 0
	s_mov_b32 s0, s72
	s_cmp_ge_u32 s0, 0x2b0
	s_cbranch_scc1 .Lc32_ffn1_done
	s_lshl_b32 s3, s0, 7
	s_add_u32 s56, s48, s3
	s_addc_u32 s57, s49, 0
	global_load_dwordx4 v[6:9], v138, s[56:57]
	s_add_u32 s56, s56, 0x15800
	s_addc_u32 s57, s57, 0
	global_load_dwordx4 v[10:13], v138, s[56:57]
	s_add_u32 s56, s56, 0x15800
	s_addc_u32 s57, s57, 0
	global_load_dwordx4 v[14:17], v138, s[56:57]
	s_add_u32 s56, s56, 0x15800
	s_addc_u32 s57, s57, 0
	global_load_dwordx4 v[18:21], v138, s[56:57]
	s_add_u32 s56, s56, 0x26f800
	s_addc_u32 s57, s57, 0
	global_load_dwordx4 v[22:25], v138, s[56:57]
	s_add_u32 s56, s56, 0x15800
	s_addc_u32 s57, s57, 0
	global_load_dwordx4 v[26:29], v138, s[56:57]
	s_add_u32 s56, s56, 0x15800
	s_addc_u32 s57, s57, 0
	global_load_dwordx4 v[30:33], v138, s[56:57]
	s_add_u32 s56, s56, 0x15800
	s_addc_u32 s57, s57, 0
	global_load_dwordx4 v[34:37], v138, s[56:57]
	s_add_u32 s56, s56, 0x26f800
	s_addc_u32 s57, s57, 0
	global_load_dwordx4 v[38:41], v138, s[56:57]
	s_add_u32 s56, s56, 0x15800
	s_addc_u32 s57, s57, 0
	global_load_dwordx4 v[42:45], v138, s[56:57]
	s_add_u32 s56, s56, 0x15800
	s_addc_u32 s57, s57, 0
	global_load_dwordx4 v[46:49], v138, s[56:57]
	s_add_u32 s56, s56, 0x15800
	s_addc_u32 s57, s57, 0
	global_load_dwordx4 v[50:53], v138, s[56:57]
	s_add_u32 s56, s56, 0x26f800
	s_addc_u32 s57, s57, 0
	global_load_dwordx4 v[54:57], v138, s[56:57]
	s_add_u32 s56, s56, 0x15800
	s_addc_u32 s57, s57, 0
	global_load_dwordx4 v[58:61], v138, s[56:57]
	s_add_u32 s56, s56, 0x15800
	s_addc_u32 s57, s57, 0
	global_load_dwordx4 v[62:65], v138, s[56:57]
	s_add_u32 s56, s56, 0x15800
	s_addc_u32 s57, s57, 0
	global_load_dwordx4 v[66:69], v138, s[56:57]
	s_add_u32 s56, s56, 0x26f800
	s_addc_u32 s57, s57, 0
	global_load_dwordx4 v[70:73], v138, s[56:57]
	s_add_u32 s56, s56, 0x15800
	s_addc_u32 s57, s57, 0
	global_load_dwordx4 v[74:77], v138, s[56:57]
	s_add_u32 s56, s56, 0x15800
	s_addc_u32 s57, s57, 0
	global_load_dwordx4 v[78:81], v138, s[56:57]
	s_add_u32 s56, s56, 0x15800
	s_addc_u32 s57, s57, 0
	global_load_dwordx4 v[82:85], v138, s[56:57]
	s_add_u32 s56, s56, 0x26f800
	s_addc_u32 s57, s57, 0
	global_load_dwordx4 v[86:89], v138, s[56:57]
	s_add_u32 s56, s56, 0x15800
	s_addc_u32 s57, s57, 0
	global_load_dwordx4 v[90:93], v138, s[56:57]
	s_add_u32 s56, s56, 0x15800
	s_addc_u32 s57, s57, 0
	global_load_dwordx4 v[94:97], v138, s[56:57]
	s_add_u32 s56, s56, 0x15800
	s_addc_u32 s57, s57, 0
	global_load_dwordx4 v[98:101], v138, s[56:57]
	s_add_u32 s56, s56, 0x26f800
	s_addc_u32 s57, s57, 0
	global_load_dwordx4 v[102:105], v138, s[56:57]
	s_add_u32 s56, s56, 0x15800
	s_addc_u32 s57, s57, 0
	global_load_dwordx4 v[106:109], v138, s[56:57]
	s_add_u32 s56, s56, 0x15800
	s_addc_u32 s57, s57, 0
	global_load_dwordx4 v[110:113], v138, s[56:57]
	s_add_u32 s56, s56, 0x15800
	s_addc_u32 s57, s57, 0
	global_load_dwordx4 v[114:117], v138, s[56:57]
	s_add_u32 s56, s56, 0x26f800
	s_addc_u32 s57, s57, 0
	global_load_dwordx4 v[118:121], v138, s[56:57]
	s_add_u32 s56, s56, 0x15800
	s_addc_u32 s57, s57, 0
	global_load_dwordx4 v[122:125], v138, s[56:57]
	s_add_u32 s56, s56, 0x15800
	s_addc_u32 s57, s57, 0
	global_load_dwordx4 v[126:129], v138, s[56:57]
	s_add_u32 s56, s56, 0x15800
	s_addc_u32 s57, s57, 0
	global_load_dwordx4 v[130:133], v138, s[56:57]
.Lc32_ffn1_loop:
	s_lshl_b32 s2, s0, 5
	s_add_u32 s53, s53, 1
	s_cmp_ge_u32 s2, 0x2b00
	s_cselect_b32 s75, 128, 0
	s_cselect_b32 s3, 0x2b00, 0
	s_sub_u32 s3, s2, s3
	s_lshr_b32 s60, s3, 7
	s_lshl_b32 s60, s60, 8
	s_and_b32 s3, s3, 127
	s_add_u32 s60, s60, s3
	s_add_u32 s60, s60, s75
	s_lshl_b32 s63, s11, 10
	s_add_u32 s63, s63, 0x21000
	s_lshl_b32 s3, s1, 7
	s_add_u32 s3, s3, s63
	v_add_u32_e32 v172, s3, v230
	v_add_u32_e32 v173, s63, v230
	s_waitcnt vmcnt(0)
	v_max3_f32 v216, |v6|, |v10|, |v14|
	v_max3_f32 v216, v216, |v18|, |v22|
	v_max3_f32 v216, v216, |v26|, |v30|
	v_max3_f32 v216, v216, |v34|, |v38|
	v_max3_f32 v216, v216, |v42|, |v46|
	v_max3_f32 v216, v216, |v50|, |v54|
	v_max3_f32 v216, v216, |v58|, |v62|
	v_max3_f32 v216, v216, |v66|, |v70|
	v_max3_f32 v216, v216, |v74|, |v78|
	v_max3_f32 v216, v216, |v82|, |v86|
	v_max3_f32 v216, v216, |v90|, |v94|
	v_max3_f32 v216, v216, |v98|, |v102|
	v_max3_f32 v216, v216, |v106|, |v110|
	v_max3_f32 v216, v216, |v114|, |v118|
	v_max3_f32 v216, v216, |v122|, |v126|
	v_max_f32_e64 v216, v216, |v130|
	v_max3_f32 v217, |v7|, |v11|, |v15|
	v_max3_f32 v217, v217, |v19|, |v23|
	v_max3_f32 v217, v217, |v27|, |v31|
	v_max3_f32 v217, v217, |v35|, |v39|
	v_max3_f32 v217, v217, |v43|, |v47|
	v_max3_f32 v217, v217, |v51|, |v55|
	v_max3_f32 v217, v217, |v59|, |v63|
	v_max3_f32 v217, v217, |v67|, |v71|
	v_max3_f32 v217, v217, |v75|, |v79|
	v_max3_f32 v217, v217, |v83|, |v87|
	v_max3_f32 v217, v217, |v91|, |v95|
	v_max3_f32 v217, v217, |v99|, |v103|
	v_max3_f32 v217, v217, |v107|, |v111|
	v_max3_f32 v217, v217, |v115|, |v119|
	v_max3_f32 v217, v217, |v123|, |v127|
	v_max_f32_e64 v217, v217, |v131|
	v_max3_f32 v218, |v8|, |v12|, |v16|
	v_max3_f32 v218, v218, |v20|, |v24|
	v_max3_f32 v218, v218, |v28|, |v32|
	v_max3_f32 v218, v218, |v36|, |v40|
	v_max3_f32 v218, v218, |v44|, |v48|
	v_max3_f32 v218, v218, |v52|, |v56|
	v_max3_f32 v218, v218, |v60|, |v64|
	v_max3_f32 v218, v218, |v68|, |v72|
	v_max3_f32 v218, v218, |v76|, |v80|
	v_max3_f32 v218, v218, |v84|, |v88|
	v_max3_f32 v218, v218, |v92|, |v96|
	v_max3_f32 v218, v218, |v100|, |v104|
	v_max3_f32 v218, v218, |v108|, |v112|
	v_max3_f32 v218, v218, |v116|, |v120|
	v_max3_f32 v218, v218, |v124|, |v128|
	v_max_f32_e64 v218, v218, |v132|
	v_max3_f32 v219, |v9|, |v13|, |v17|
	v_max3_f32 v219, v219, |v21|, |v25|
	v_max3_f32 v219, v219, |v29|, |v33|
	v_max3_f32 v219, v219, |v37|, |v41|
	v_max3_f32 v219, v219, |v45|, |v49|
	v_max3_f32 v219, v219, |v53|, |v57|
	v_max3_f32 v219, v219, |v61|, |v65|
	v_max3_f32 v219, v219, |v69|, |v73|
	v_max3_f32 v219, v219, |v77|, |v81|
	v_max3_f32 v219, v219, |v85|, |v89|
	v_max3_f32 v219, v219, |v93|, |v97|
	v_max3_f32 v219, v219, |v101|, |v105|
	v_max3_f32 v219, v219, |v109|, |v113|
	v_max3_f32 v219, v219, |v117|, |v121|
	v_max3_f32 v219, v219, |v125|, |v129|
	v_max_f32_e64 v219, v219, |v133|
	ds_bpermute_b32 v174, v192, v216
	ds_bpermute_b32 v175, v192, v217
	ds_bpermute_b32 v176, v192, v218
	ds_bpermute_b32 v177, v192, v219
	s_waitcnt lgkmcnt(0)
	v_max_f32_e32 v216, v216, v174
	v_max_f32_e32 v217, v217, v175
	v_max_f32_e32 v218, v218, v176
	v_max_f32_e32 v219, v219, v177
	ds_bpermute_b32 v174, v193, v216
	ds_bpermute_b32 v175, v193, v217
	ds_bpermute_b32 v176, v193, v218
	ds_bpermute_b32 v177, v193, v219
	s_waitcnt lgkmcnt(0)
	v_max_f32_e32 v216, v216, v174
	v_max_f32_e32 v217, v217, v175
	v_max_f32_e32 v218, v218, v176
	v_max_f32_e32 v219, v219, v177
	ds_bpermute_b32 v174, v194, v216
	ds_bpermute_b32 v175, v194, v217
	ds_bpermute_b32 v176, v194, v218
	ds_bpermute_b32 v177, v194, v219
	s_waitcnt lgkmcnt(0)
	v_max_f32_e32 v216, v216, v174
	v_max_f32_e32 v217, v217, v175
	v_max_f32_e32 v218, v218, v176
	v_max_f32_e32 v219, v219, v177
	s_mov_b64 s[70:71], exec
	s_mov_b64 exec, 0xff
	ds_write_b128 v172, v[216:219]
	s_mov_b64 exec, s[70:71]
	s_waitcnt lgkmcnt(0)
	s_barrier
	ds_read_b128 v[140:143], v173 offset:0
	ds_read_b128 v[144:147], v173 offset:128
	ds_read_b128 v[148:151], v173 offset:256
	ds_read_b128 v[152:155], v173 offset:384
	ds_read_b128 v[156:159], v173 offset:512
	ds_read_b128 v[160:163], v173 offset:640
	ds_read_b128 v[164:167], v173 offset:768
	ds_read_b128 v[232:235], v173 offset:896
	s_waitcnt lgkmcnt(0)
	v_max3_f32 v220, v140, v144, v148
	v_max3_f32 v220, v220, v152, v156
	v_max3_f32 v220, v220, v160, v164
	v_max_f32_e32 v220, v220, v232
	v_max3_f32 v221, v141, v145, v149
	v_max3_f32 v221, v221, v153, v157
	v_max3_f32 v221, v221, v161, v165
	v_max_f32_e32 v221, v221, v233
	v_max3_f32 v222, v142, v146, v150
	v_max3_f32 v222, v222, v154, v158
	v_max3_f32 v222, v222, v162, v166
	v_max_f32_e32 v222, v222, v234
	v_max3_f32 v223, v143, v147, v151
	v_max3_f32 v223, v223, v155, v159
	v_max3_f32 v223, v223, v163, v167
	v_max_f32_e32 v223, v223, v235
	s_lshl_b32 s3, s11, 9
	s_lshl_b32 s10, s12, 8
	s_add_u32 s10, s10, s3
	s_add_u32 s66, s50, s10
	s_addc_u32 s67, s51, 0
	s_mov_b64 s[70:71], exec
	s_mov_b64 exec, 0xff
	s_cmp_lg_u32 s1, 0
	s_cbranch_scc1 .Lc32_ffn1_nopub
	v_mov_b32_e32 v249, s53
	v_mov_b32_e32 v248, v220
	global_store_dwordx2 v195, v[248:249], s[66:67] offset:0 sc0 sc1
	s_nop 1
	v_mov_b32_e32 v248, v221
	global_store_dwordx2 v195, v[248:249], s[66:67] offset:8 sc0 sc1
	s_nop 1
	v_mov_b32_e32 v248, v222
	global_store_dwordx2 v195, v[248:249], s[66:67] offset:16 sc0 sc1
	s_nop 1
	v_mov_b32_e32 v248, v223
	global_store_dwordx2 v195, v[248:249], s[66:67] offset:24 sc0 sc1
	s_nop 1

.Lc32_ffn1_got:
	v_max_f32_e32 v220, v220, v240
	v_max_f32_e32 v221, v221, v242
	v_max_f32_e32 v222, v222, v244
	v_max_f32_e32 v223, v223, v246
	s_mov_b64 exec, s[70:71]
	v_lshlrev_b32_e32 v174, 2, v137
	ds_bpermute_b32 v175, v174, v220
	ds_bpermute_b32 v176, v174, v221
	ds_bpermute_b32 v177, v174, v222
	ds_bpermute_b32 v178, v174, v223
	s_waitcnt lgkmcnt(0)
	v_mov_b32_e32 v220, v175
	v_mov_b32_e32 v221, v176
	v_mov_b32_e32 v222, v177
	v_mov_b32_e32 v223, v178
	s_or_b32 s3, s1, s12
	s_cmp_lg_u32 s3, 0
	s_cbranch_scc1 .Lc32_ffn1_nocm
	s_lshl_b32 s3, s2, 2
	s_add_u32 s56, s34, s3
	s_addc_u32 s57, s35, 0
	s_add_u32 s56, s56, 0x40000
	s_addc_u32 s57, s57, 0
	s_mov_b64 s[70:71], exec
	s_mov_b64 exec, 0xff
	global_store_dwordx4 v230, v[220:223], s[56:57]
	s_mov_b64 exec, s[70:71]
.Lc32_ffn1_nocm:
	v_div_scale_f32 v175, s[70:71], v220, v220, s74
	v_rcp_f32_e32 v176, v175
	s_nop 0
	v_fma_f32 v177, -v175, v176, 1.0
	v_fmac_f32_e32 v176, v177, v176
	v_div_scale_f32 v177, vcc, s74, v220, s74
	v_mul_f32_e32 v178, v177, v176
	v_fma_f32 v180, -v175, v178, v177
	v_fmac_f32_e32 v178, v180, v176
	v_fma_f32 v175, -v175, v178, v177
	s_nop 0
	v_div_fmas_f32 v175, v175, v176, v178
	v_div_fixup_f32 v175, v175, v220, s74
	v_cmp_lt_f32_e32 vcc, 0, v220
	s_nop 1
	v_cndmask_b32_e32 v226, 0, v175, vcc
	v_div_scale_f32 v175, s[70:71], v221, v221, s74
	v_rcp_f32_e32 v176, v175
	s_nop 0
	v_fma_f32 v177, -v175, v176, 1.0
	v_fmac_f32_e32 v176, v177, v176
	v_div_scale_f32 v177, vcc, s74, v221, s74
	v_mul_f32_e32 v178, v177, v176
	v_fma_f32 v180, -v175, v178, v177
	v_fmac_f32_e32 v178, v180, v176
	v_fma_f32 v175, -v175, v178, v177
	s_nop 0
	v_div_fmas_f32 v175, v175, v176, v178
	v_div_fixup_f32 v175, v175, v221, s74
	v_cmp_lt_f32_e32 vcc, 0, v221
	s_nop 1
	v_cndmask_b32_e32 v227, 0, v175, vcc
	v_div_scale_f32 v175, s[70:71], v222, v222, s74
	v_rcp_f32_e32 v176, v175
	s_nop 0
	v_fma_f32 v177, -v175, v176, 1.0
	v_fmac_f32_e32 v176, v177, v176
	v_div_scale_f32 v177, vcc, s74, v222, s74
	v_mul_f32_e32 v178, v177, v176
	v_fma_f32 v180, -v175, v178, v177
	v_fmac_f32_e32 v178, v180, v176
	v_fma_f32 v175, -v175, v178, v177
	s_nop 0
	v_div_fmas_f32 v175, v175, v176, v178
	v_div_fixup_f32 v175, v175, v222, s74
	v_cmp_lt_f32_e32 vcc, 0, v222
	s_nop 1
	v_cndmask_b32_e32 v228, 0, v175, vcc
	v_div_scale_f32 v175, s[70:71], v223, v223, s74
	v_rcp_f32_e32 v176, v175
	s_nop 0
	v_fma_f32 v177, -v175, v176, 1.0
	v_fmac_f32_e32 v176, v177, v176
	v_div_scale_f32 v177, vcc, s74, v223, s74
	v_mul_f32_e32 v178, v177, v176
	v_fma_f32 v180, -v175, v178, v177
	v_fmac_f32_e32 v178, v180, v176
	v_fma_f32 v175, -v175, v178, v177
	s_nop 0
	v_div_fmas_f32 v175, v175, v176, v178
	v_div_fixup_f32 v175, v175, v223, s74
	v_cmp_lt_f32_e32 vcc, 0, v223
	s_nop 1
	v_cndmask_b32_e32 v229, 0, v175, vcc
	s_add_u32 s10, s0, 128
	s_lshl_b32 s3, s10, 7
	s_add_u32 s56, s48, s3
	s_addc_u32 s57, s49, 0
	v_mul_f32_e32 v186, v6, v226
	v_mul_f32_e32 v187, v7, v227
	v_rndne_f32_e32 v186, v186
	v_rndne_f32_e32 v187, v187
	v_cvt_i32_f32_sdwa v190, v186 dst_sel:BYTE_0 dst_unused:UNUSED_PAD src0_sel:DWORD
	v_cvt_i32_f32_sdwa v196, v187 dst_sel:BYTE_0 dst_unused:UNUSED_PAD src0_sel:DWORD
	v_mul_f32_e32 v186, v10, v226
	v_mul_f32_e32 v187, v11, v227
	v_rndne_f32_e32 v186, v186
	v_rndne_f32_e32 v187, v187
	v_cvt_i32_f32_sdwa v190, v186 dst_sel:BYTE_1 dst_unused:UNUSED_PRESERVE src0_sel:DWORD
	v_cvt_i32_f32_sdwa v196, v187 dst_sel:BYTE_1 dst_unused:UNUSED_PRESERVE src0_sel:DWORD
	v_mul_f32_e32 v186, v14, v226
	v_mul_f32_e32 v187, v15, v227
	v_rndne_f32_e32 v186, v186
	v_rndne_f32_e32 v187, v187
	v_cvt_i32_f32_sdwa v190, v186 dst_sel:BYTE_2 dst_unused:UNUSED_PRESERVE src0_sel:DWORD
	v_cvt_i32_f32_sdwa v196, v187 dst_sel:BYTE_2 dst_unused:UNUSED_PRESERVE src0_sel:DWORD
	v_mul_f32_e32 v186, v18, v226
	v_mul_f32_e32 v187, v19, v227
	v_rndne_f32_e32 v186, v186
	v_rndne_f32_e32 v187, v187
	v_cvt_i32_f32_sdwa v190, v186 dst_sel:BYTE_3 dst_unused:UNUSED_PRESERVE src0_sel:DWORD
	v_cvt_i32_f32_sdwa v196, v187 dst_sel:BYTE_3 dst_unused:UNUSED_PRESERVE src0_sel:DWORD
	s_nop 0
	ds_write_b32 v139, v190 offset:0
	ds_write_b32 v139, v196 offset:256
	v_mul_f32_e32 v186, v8, v228
	v_mul_f32_e32 v187, v9, v229
	v_rndne_f32_e32 v186, v186
	v_rndne_f32_e32 v187, v187
	v_cvt_i32_f32_sdwa v190, v186 dst_sel:BYTE_0 dst_unused:UNUSED_PAD src0_sel:DWORD
	v_cvt_i32_f32_sdwa v196, v187 dst_sel:BYTE_0 dst_unused:UNUSED_PAD src0_sel:DWORD
	v_mul_f32_e32 v186, v12, v228
	v_mul_f32_e32 v187, v13, v229
	v_rndne_f32_e32 v186, v186
	v_rndne_f32_e32 v187, v187
	v_cvt_i32_f32_sdwa v190, v186 dst_sel:BYTE_1 dst_unused:UNUSED_PRESERVE src0_sel:DWORD
	v_cvt_i32_f32_sdwa v196, v187 dst_sel:BYTE_1 dst_unused:UNUSED_PRESERVE src0_sel:DWORD
	v_mul_f32_e32 v186, v16, v228
	v_mul_f32_e32 v187, v17, v229
	v_rndne_f32_e32 v186, v186
	v_rndne_f32_e32 v187, v187
	v_cvt_i32_f32_sdwa v190, v186 dst_sel:BYTE_2 dst_unused:UNUSED_PRESERVE src0_sel:DWORD
	v_cvt_i32_f32_sdwa v196, v187 dst_sel:BYTE_2 dst_unused:UNUSED_PRESERVE src0_sel:DWORD
	v_mul_f32_e32 v186, v20, v228
	v_mul_f32_e32 v187, v21, v229
	v_rndne_f32_e32 v186, v186
	v_rndne_f32_e32 v187, v187
	v_cvt_i32_f32_sdwa v190, v186 dst_sel:BYTE_3 dst_unused:UNUSED_PRESERVE src0_sel:DWORD
	v_cvt_i32_f32_sdwa v196, v187 dst_sel:BYTE_3 dst_unused:UNUSED_PRESERVE src0_sel:DWORD
	s_nop 0
	ds_write_b32 v139, v190 offset:512
	ds_write_b32 v139, v196 offset:768
	s_cmp_ge_u32 s10, 0x2b0
	s_cbranch_scc1 .Lc32_ffn1_nopf_0
	global_load_dwordx4 v[6:9], v138, s[56:57]
	s_add_u32 s56, s56, 0x15800
	s_addc_u32 s57, s57, 0
	global_load_dwordx4 v[10:13], v138, s[56:57]
	s_add_u32 s56, s56, 0x15800
	s_addc_u32 s57, s57, 0
	global_load_dwordx4 v[14:17], v138, s[56:57]
	s_add_u32 s56, s56, 0x15800
	s_addc_u32 s57, s57, 0
	global_load_dwordx4 v[18:21], v138, s[56:57]
	s_add_u32 s56, s56, 0x26f800
	s_addc_u32 s57, s57, 0
.Lc32_ffn1_nopf_0:
	v_mul_f32_e32 v186, v22, v226
	v_mul_f32_e32 v187, v23, v227
	v_rndne_f32_e32 v186, v186
	v_rndne_f32_e32 v187, v187
	v_cvt_i32_f32_sdwa v190, v186 dst_sel:BYTE_0 dst_unused:UNUSED_PAD src0_sel:DWORD
	v_cvt_i32_f32_sdwa v196, v187 dst_sel:BYTE_0 dst_unused:UNUSED_PAD src0_sel:DWORD
	v_mul_f32_e32 v186, v26, v226
	v_mul_f32_e32 v187, v27, v227
	v_rndne_f32_e32 v186, v186
	v_rndne_f32_e32 v187, v187
	v_cvt_i32_f32_sdwa v190, v186 dst_sel:BYTE_1 dst_unused:UNUSED_PRESERVE src0_sel:DWORD
	v_cvt_i32_f32_sdwa v196, v187 dst_sel:BYTE_1 dst_unused:UNUSED_PRESERVE src0_sel:DWORD
	v_mul_f32_e32 v186, v30, v226
	v_mul_f32_e32 v187, v31, v227
	v_rndne_f32_e32 v186, v186
	v_rndne_f32_e32 v187, v187
	v_cvt_i32_f32_sdwa v190, v186 dst_sel:BYTE_2 dst_unused:UNUSED_PRESERVE src0_sel:DWORD
	v_cvt_i32_f32_sdwa v196, v187 dst_sel:BYTE_2 dst_unused:UNUSED_PRESERVE src0_sel:DWORD
	v_mul_f32_e32 v186, v34, v226
	v_mul_f32_e32 v187, v35, v227
	v_rndne_f32_e32 v186, v186
	v_rndne_f32_e32 v187, v187
	v_cvt_i32_f32_sdwa v190, v186 dst_sel:BYTE_3 dst_unused:UNUSED_PRESERVE src0_sel:DWORD
	v_cvt_i32_f32_sdwa v196, v187 dst_sel:BYTE_3 dst_unused:UNUSED_PRESERVE src0_sel:DWORD
	s_nop 0
	ds_write_b32 v139, v190 offset:32
	ds_write_b32 v139, v196 offset:288
	v_mul_f32_e32 v186, v24, v228
	v_mul_f32_e32 v187, v25, v229
	v_rndne_f32_e32 v186, v186
	v_rndne_f32_e32 v187, v187
	v_cvt_i32_f32_sdwa v190, v186 dst_sel:BYTE_0 dst_unused:UNUSED_PAD src0_sel:DWORD
	v_cvt_i32_f32_sdwa v196, v187 dst_sel:BYTE_0 dst_unused:UNUSED_PAD src0_sel:DWORD
	v_mul_f32_e32 v186, v28, v228
	v_mul_f32_e32 v187, v29, v229
	v_rndne_f32_e32 v186, v186
	v_rndne_f32_e32 v187, v187
	v_cvt_i32_f32_sdwa v190, v186 dst_sel:BYTE_1 dst_unused:UNUSED_PRESERVE src0_sel:DWORD
	v_cvt_i32_f32_sdwa v196, v187 dst_sel:BYTE_1 dst_unused:UNUSED_PRESERVE src0_sel:DWORD
	v_mul_f32_e32 v186, v32, v228
	v_mul_f32_e32 v187, v33, v229
	v_rndne_f32_e32 v186, v186
	v_rndne_f32_e32 v187, v187
	v_cvt_i32_f32_sdwa v190, v186 dst_sel:BYTE_2 dst_unused:UNUSED_PRESERVE src0_sel:DWORD
	v_cvt_i32_f32_sdwa v196, v187 dst_sel:BYTE_2 dst_unused:UNUSED_PRESERVE src0_sel:DWORD
	v_mul_f32_e32 v186, v36, v228
	v_mul_f32_e32 v187, v37, v229
	v_rndne_f32_e32 v186, v186
	v_rndne_f32_e32 v187, v187
	v_cvt_i32_f32_sdwa v190, v186 dst_sel:BYTE_3 dst_unused:UNUSED_PRESERVE src0_sel:DWORD
	v_cvt_i32_f32_sdwa v196, v187 dst_sel:BYTE_3 dst_unused:UNUSED_PRESERVE src0_sel:DWORD
	s_nop 0
	ds_write_b32 v139, v190 offset:544
	ds_write_b32 v139, v196 offset:800
	s_cmp_ge_u32 s10, 0x2b0
	s_cbranch_scc1 .Lc32_ffn1_nopf_1
	global_load_dwordx4 v[22:25], v138, s[56:57]
	s_add_u32 s56, s56, 0x15800
	s_addc_u32 s57, s57, 0
	global_load_dwordx4 v[26:29], v138, s[56:57]
	s_add_u32 s56, s56, 0x15800
	s_addc_u32 s57, s57, 0
	global_load_dwordx4 v[30:33], v138, s[56:57]
	s_add_u32 s56, s56, 0x15800
	s_addc_u32 s57, s57, 0
	global_load_dwordx4 v[34:37], v138, s[56:57]
	s_add_u32 s56, s56, 0x26f800
	s_addc_u32 s57, s57, 0
.Lc32_ffn1_nopf_1:
	v_mul_f32_e32 v186, v38, v226
	v_mul_f32_e32 v187, v39, v227
	v_rndne_f32_e32 v186, v186
	v_rndne_f32_e32 v187, v187
	v_cvt_i32_f32_sdwa v190, v186 dst_sel:BYTE_0 dst_unused:UNUSED_PAD src0_sel:DWORD
	v_cvt_i32_f32_sdwa v196, v187 dst_sel:BYTE_0 dst_unused:UNUSED_PAD src0_sel:DWORD
	v_mul_f32_e32 v186, v42, v226
	v_mul_f32_e32 v187, v43, v227
	v_rndne_f32_e32 v186, v186
	v_rndne_f32_e32 v187, v187
	v_cvt_i32_f32_sdwa v190, v186 dst_sel:BYTE_1 dst_unused:UNUSED_PRESERVE src0_sel:DWORD
	v_cvt_i32_f32_sdwa v196, v187 dst_sel:BYTE_1 dst_unused:UNUSED_PRESERVE src0_sel:DWORD
	v_mul_f32_e32 v186, v46, v226
	v_mul_f32_e32 v187, v47, v227
	v_rndne_f32_e32 v186, v186
	v_rndne_f32_e32 v187, v187
	v_cvt_i32_f32_sdwa v190, v186 dst_sel:BYTE_2 dst_unused:UNUSED_PRESERVE src0_sel:DWORD
	v_cvt_i32_f32_sdwa v196, v187 dst_sel:BYTE_2 dst_unused:UNUSED_PRESERVE src0_sel:DWORD
	v_mul_f32_e32 v186, v50, v226
	v_mul_f32_e32 v187, v51, v227
	v_rndne_f32_e32 v186, v186
	v_rndne_f32_e32 v187, v187
	v_cvt_i32_f32_sdwa v190, v186 dst_sel:BYTE_3 dst_unused:UNUSED_PRESERVE src0_sel:DWORD
	v_cvt_i32_f32_sdwa v196, v187 dst_sel:BYTE_3 dst_unused:UNUSED_PRESERVE src0_sel:DWORD
	s_nop 0
	ds_write_b32 v139, v190 offset:64
	ds_write_b32 v139, v196 offset:320
	v_mul_f32_e32 v186, v40, v228
	v_mul_f32_e32 v187, v41, v229
	v_rndne_f32_e32 v186, v186
	v_rndne_f32_e32 v187, v187
	v_cvt_i32_f32_sdwa v190, v186 dst_sel:BYTE_0 dst_unused:UNUSED_PAD src0_sel:DWORD
	v_cvt_i32_f32_sdwa v196, v187 dst_sel:BYTE_0 dst_unused:UNUSED_PAD src0_sel:DWORD
	v_mul_f32_e32 v186, v44, v228
	v_mul_f32_e32 v187, v45, v229
	v_rndne_f32_e32 v186, v186
	v_rndne_f32_e32 v187, v187
	v_cvt_i32_f32_sdwa v190, v186 dst_sel:BYTE_1 dst_unused:UNUSED_PRESERVE src0_sel:DWORD
	v_cvt_i32_f32_sdwa v196, v187 dst_sel:BYTE_1 dst_unused:UNUSED_PRESERVE src0_sel:DWORD
	v_mul_f32_e32 v186, v48, v228
	v_mul_f32_e32 v187, v49, v229
	v_rndne_f32_e32 v186, v186
	v_rndne_f32_e32 v187, v187
	v_cvt_i32_f32_sdwa v190, v186 dst_sel:BYTE_2 dst_unused:UNUSED_PRESERVE src0_sel:DWORD
	v_cvt_i32_f32_sdwa v196, v187 dst_sel:BYTE_2 dst_unused:UNUSED_PRESERVE src0_sel:DWORD
	v_mul_f32_e32 v186, v52, v228
	v_mul_f32_e32 v187, v53, v229
	v_rndne_f32_e32 v186, v186
	v_rndne_f32_e32 v187, v187
	v_cvt_i32_f32_sdwa v190, v186 dst_sel:BYTE_3 dst_unused:UNUSED_PRESERVE src0_sel:DWORD
	v_cvt_i32_f32_sdwa v196, v187 dst_sel:BYTE_3 dst_unused:UNUSED_PRESERVE src0_sel:DWORD
	s_nop 0
	ds_write_b32 v139, v190 offset:576
	ds_write_b32 v139, v196 offset:832
	s_cmp_ge_u32 s10, 0x2b0
	s_cbranch_scc1 .Lc32_ffn1_nopf_2
	global_load_dwordx4 v[38:41], v138, s[56:57]
	s_add_u32 s56, s56, 0x15800
	s_addc_u32 s57, s57, 0
	global_load_dwordx4 v[42:45], v138, s[56:57]
	s_add_u32 s56, s56, 0x15800
	s_addc_u32 s57, s57, 0
	global_load_dwordx4 v[46:49], v138, s[56:57]
	s_add_u32 s56, s56, 0x15800
	s_addc_u32 s57, s57, 0
	global_load_dwordx4 v[50:53], v138, s[56:57]
	s_add_u32 s56, s56, 0x26f800
	s_addc_u32 s57, s57, 0
.Lc32_ffn1_nopf_2:
	v_mul_f32_e32 v186, v54, v226
	v_mul_f32_e32 v187, v55, v227
	v_rndne_f32_e32 v186, v186
	v_rndne_f32_e32 v187, v187
	v_cvt_i32_f32_sdwa v190, v186 dst_sel:BYTE_0 dst_unused:UNUSED_PAD src0_sel:DWORD
	v_cvt_i32_f32_sdwa v196, v187 dst_sel:BYTE_0 dst_unused:UNUSED_PAD src0_sel:DWORD
	v_mul_f32_e32 v186, v58, v226
	v_mul_f32_e32 v187, v59, v227
	v_rndne_f32_e32 v186, v186
	v_rndne_f32_e32 v187, v187
	v_cvt_i32_f32_sdwa v190, v186 dst_sel:BYTE_1 dst_unused:UNUSED_PRESERVE src0_sel:DWORD
	v_cvt_i32_f32_sdwa v196, v187 dst_sel:BYTE_1 dst_unused:UNUSED_PRESERVE src0_sel:DWORD
	v_mul_f32_e32 v186, v62, v226
	v_mul_f32_e32 v187, v63, v227
	v_rndne_f32_e32 v186, v186
	v_rndne_f32_e32 v187, v187
	v_cvt_i32_f32_sdwa v190, v186 dst_sel:BYTE_2 dst_unused:UNUSED_PRESERVE src0_sel:DWORD
	v_cvt_i32_f32_sdwa v196, v187 dst_sel:BYTE_2 dst_unused:UNUSED_PRESERVE src0_sel:DWORD
	v_mul_f32_e32 v186, v66, v226
	v_mul_f32_e32 v187, v67, v227
	v_rndne_f32_e32 v186, v186
	v_rndne_f32_e32 v187, v187
	v_cvt_i32_f32_sdwa v190, v186 dst_sel:BYTE_3 dst_unused:UNUSED_PRESERVE src0_sel:DWORD
	v_cvt_i32_f32_sdwa v196, v187 dst_sel:BYTE_3 dst_unused:UNUSED_PRESERVE src0_sel:DWORD
	s_nop 0
	ds_write_b32 v139, v190 offset:96
	ds_write_b32 v139, v196 offset:352
	v_mul_f32_e32 v186, v56, v228
	v_mul_f32_e32 v187, v57, v229
	v_rndne_f32_e32 v186, v186
	v_rndne_f32_e32 v187, v187
	v_cvt_i32_f32_sdwa v190, v186 dst_sel:BYTE_0 dst_unused:UNUSED_PAD src0_sel:DWORD
	v_cvt_i32_f32_sdwa v196, v187 dst_sel:BYTE_0 dst_unused:UNUSED_PAD src0_sel:DWORD
	v_mul_f32_e32 v186, v60, v228
	v_mul_f32_e32 v187, v61, v229
	v_rndne_f32_e32 v186, v186
	v_rndne_f32_e32 v187, v187
	v_cvt_i32_f32_sdwa v190, v186 dst_sel:BYTE_1 dst_unused:UNUSED_PRESERVE src0_sel:DWORD
	v_cvt_i32_f32_sdwa v196, v187 dst_sel:BYTE_1 dst_unused:UNUSED_PRESERVE src0_sel:DWORD
	v_mul_f32_e32 v186, v64, v228
	v_mul_f32_e32 v187, v65, v229
	v_rndne_f32_e32 v186, v186
	v_rndne_f32_e32 v187, v187
	v_cvt_i32_f32_sdwa v190, v186 dst_sel:BYTE_2 dst_unused:UNUSED_PRESERVE src0_sel:DWORD
	v_cvt_i32_f32_sdwa v196, v187 dst_sel:BYTE_2 dst_unused:UNUSED_PRESERVE src0_sel:DWORD
	v_mul_f32_e32 v186, v68, v228
	v_mul_f32_e32 v187, v69, v229
	v_rndne_f32_e32 v186, v186
	v_rndne_f32_e32 v187, v187
	v_cvt_i32_f32_sdwa v190, v186 dst_sel:BYTE_3 dst_unused:UNUSED_PRESERVE src0_sel:DWORD
	v_cvt_i32_f32_sdwa v196, v187 dst_sel:BYTE_3 dst_unused:UNUSED_PRESERVE src0_sel:DWORD
	s_nop 0
	ds_write_b32 v139, v190 offset:608
	ds_write_b32 v139, v196 offset:864
	s_cmp_ge_u32 s10, 0x2b0
	s_cbranch_scc1 .Lc32_ffn1_nopf_3
	global_load_dwordx4 v[54:57], v138, s[56:57]
	s_add_u32 s56, s56, 0x15800
	s_addc_u32 s57, s57, 0
	global_load_dwordx4 v[58:61], v138, s[56:57]
	s_add_u32 s56, s56, 0x15800
	s_addc_u32 s57, s57, 0
	global_load_dwordx4 v[62:65], v138, s[56:57]
	s_add_u32 s56, s56, 0x15800
	s_addc_u32 s57, s57, 0
	global_load_dwordx4 v[66:69], v138, s[56:57]
	s_add_u32 s56, s56, 0x26f800
	s_addc_u32 s57, s57, 0
.Lc32_ffn1_nopf_3:
	v_mul_f32_e32 v186, v70, v226
	v_mul_f32_e32 v187, v71, v227
	v_rndne_f32_e32 v186, v186
	v_rndne_f32_e32 v187, v187
	v_cvt_i32_f32_sdwa v190, v186 dst_sel:BYTE_0 dst_unused:UNUSED_PAD src0_sel:DWORD
	v_cvt_i32_f32_sdwa v196, v187 dst_sel:BYTE_0 dst_unused:UNUSED_PAD src0_sel:DWORD
	v_mul_f32_e32 v186, v74, v226
	v_mul_f32_e32 v187, v75, v227
	v_rndne_f32_e32 v186, v186
	v_rndne_f32_e32 v187, v187
	v_cvt_i32_f32_sdwa v190, v186 dst_sel:BYTE_1 dst_unused:UNUSED_PRESERVE src0_sel:DWORD
	v_cvt_i32_f32_sdwa v196, v187 dst_sel:BYTE_1 dst_unused:UNUSED_PRESERVE src0_sel:DWORD
	v_mul_f32_e32 v186, v78, v226
	v_mul_f32_e32 v187, v79, v227
	v_rndne_f32_e32 v186, v186
	v_rndne_f32_e32 v187, v187
	v_cvt_i32_f32_sdwa v190, v186 dst_sel:BYTE_2 dst_unused:UNUSED_PRESERVE src0_sel:DWORD
	v_cvt_i32_f32_sdwa v196, v187 dst_sel:BYTE_2 dst_unused:UNUSED_PRESERVE src0_sel:DWORD
	v_mul_f32_e32 v186, v82, v226
	v_mul_f32_e32 v187, v83, v227
	v_rndne_f32_e32 v186, v186
	v_rndne_f32_e32 v187, v187
	v_cvt_i32_f32_sdwa v190, v186 dst_sel:BYTE_3 dst_unused:UNUSED_PRESERVE src0_sel:DWORD
	v_cvt_i32_f32_sdwa v196, v187 dst_sel:BYTE_3 dst_unused:UNUSED_PRESERVE src0_sel:DWORD
	s_nop 0
	ds_write_b32 v139, v190 offset:128
	ds_write_b32 v139, v196 offset:384
	v_mul_f32_e32 v186, v72, v228
	v_mul_f32_e32 v187, v73, v229
	v_rndne_f32_e32 v186, v186
	v_rndne_f32_e32 v187, v187
	v_cvt_i32_f32_sdwa v190, v186 dst_sel:BYTE_0 dst_unused:UNUSED_PAD src0_sel:DWORD
	v_cvt_i32_f32_sdwa v196, v187 dst_sel:BYTE_0 dst_unused:UNUSED_PAD src0_sel:DWORD
	v_mul_f32_e32 v186, v76, v228
	v_mul_f32_e32 v187, v77, v229
	v_rndne_f32_e32 v186, v186
	v_rndne_f32_e32 v187, v187
	v_cvt_i32_f32_sdwa v190, v186 dst_sel:BYTE_1 dst_unused:UNUSED_PRESERVE src0_sel:DWORD
	v_cvt_i32_f32_sdwa v196, v187 dst_sel:BYTE_1 dst_unused:UNUSED_PRESERVE src0_sel:DWORD
	v_mul_f32_e32 v186, v80, v228
	v_mul_f32_e32 v187, v81, v229
	v_rndne_f32_e32 v186, v186
	v_rndne_f32_e32 v187, v187
	v_cvt_i32_f32_sdwa v190, v186 dst_sel:BYTE_2 dst_unused:UNUSED_PRESERVE src0_sel:DWORD
	v_cvt_i32_f32_sdwa v196, v187 dst_sel:BYTE_2 dst_unused:UNUSED_PRESERVE src0_sel:DWORD
	v_mul_f32_e32 v186, v84, v228
	v_mul_f32_e32 v187, v85, v229
	v_rndne_f32_e32 v186, v186
	v_rndne_f32_e32 v187, v187
	v_cvt_i32_f32_sdwa v190, v186 dst_sel:BYTE_3 dst_unused:UNUSED_PRESERVE src0_sel:DWORD
	v_cvt_i32_f32_sdwa v196, v187 dst_sel:BYTE_3 dst_unused:UNUSED_PRESERVE src0_sel:DWORD
	s_nop 0
	ds_write_b32 v139, v190 offset:640
	ds_write_b32 v139, v196 offset:896
	s_cmp_ge_u32 s10, 0x2b0
	s_cbranch_scc1 .Lc32_ffn1_nopf_4
	global_load_dwordx4 v[70:73], v138, s[56:57]
	s_add_u32 s56, s56, 0x15800
	s_addc_u32 s57, s57, 0
	global_load_dwordx4 v[74:77], v138, s[56:57]
	s_add_u32 s56, s56, 0x15800
	s_addc_u32 s57, s57, 0
	global_load_dwordx4 v[78:81], v138, s[56:57]
	s_add_u32 s56, s56, 0x15800
	s_addc_u32 s57, s57, 0
	global_load_dwordx4 v[82:85], v138, s[56:57]
	s_add_u32 s56, s56, 0x26f800
	s_addc_u32 s57, s57, 0
.Lc32_ffn1_nopf_4:
	v_mul_f32_e32 v186, v86, v226
	v_mul_f32_e32 v187, v87, v227
	v_rndne_f32_e32 v186, v186
	v_rndne_f32_e32 v187, v187
	v_cvt_i32_f32_sdwa v190, v186 dst_sel:BYTE_0 dst_unused:UNUSED_PAD src0_sel:DWORD
	v_cvt_i32_f32_sdwa v196, v187 dst_sel:BYTE_0 dst_unused:UNUSED_PAD src0_sel:DWORD
	v_mul_f32_e32 v186, v90, v226
	v_mul_f32_e32 v187, v91, v227
	v_rndne_f32_e32 v186, v186
	v_rndne_f32_e32 v187, v187
	v_cvt_i32_f32_sdwa v190, v186 dst_sel:BYTE_1 dst_unused:UNUSED_PRESERVE src0_sel:DWORD
	v_cvt_i32_f32_sdwa v196, v187 dst_sel:BYTE_1 dst_unused:UNUSED_PRESERVE src0_sel:DWORD
	v_mul_f32_e32 v186, v94, v226
	v_mul_f32_e32 v187, v95, v227
	v_rndne_f32_e32 v186, v186
	v_rndne_f32_e32 v187, v187
	v_cvt_i32_f32_sdwa v190, v186 dst_sel:BYTE_2 dst_unused:UNUSED_PRESERVE src0_sel:DWORD
	v_cvt_i32_f32_sdwa v196, v187 dst_sel:BYTE_2 dst_unused:UNUSED_PRESERVE src0_sel:DWORD
	v_mul_f32_e32 v186, v98, v226
	v_mul_f32_e32 v187, v99, v227
	v_rndne_f32_e32 v186, v186
	v_rndne_f32_e32 v187, v187
	v_cvt_i32_f32_sdwa v190, v186 dst_sel:BYTE_3 dst_unused:UNUSED_PRESERVE src0_sel:DWORD
	v_cvt_i32_f32_sdwa v196, v187 dst_sel:BYTE_3 dst_unused:UNUSED_PRESERVE src0_sel:DWORD
	s_nop 0
	ds_write_b32 v139, v190 offset:160
	ds_write_b32 v139, v196 offset:416
	v_mul_f32_e32 v186, v88, v228
	v_mul_f32_e32 v187, v89, v229
	v_rndne_f32_e32 v186, v186
	v_rndne_f32_e32 v187, v187
	v_cvt_i32_f32_sdwa v190, v186 dst_sel:BYTE_0 dst_unused:UNUSED_PAD src0_sel:DWORD
	v_cvt_i32_f32_sdwa v196, v187 dst_sel:BYTE_0 dst_unused:UNUSED_PAD src0_sel:DWORD
	v_mul_f32_e32 v186, v92, v228
	v_mul_f32_e32 v187, v93, v229
	v_rndne_f32_e32 v186, v186
	v_rndne_f32_e32 v187, v187
	v_cvt_i32_f32_sdwa v190, v186 dst_sel:BYTE_1 dst_unused:UNUSED_PRESERVE src0_sel:DWORD
	v_cvt_i32_f32_sdwa v196, v187 dst_sel:BYTE_1 dst_unused:UNUSED_PRESERVE src0_sel:DWORD
	v_mul_f32_e32 v186, v96, v228
	v_mul_f32_e32 v187, v97, v229
	v_rndne_f32_e32 v186, v186
	v_rndne_f32_e32 v187, v187
	v_cvt_i32_f32_sdwa v190, v186 dst_sel:BYTE_2 dst_unused:UNUSED_PRESERVE src0_sel:DWORD
	v_cvt_i32_f32_sdwa v196, v187 dst_sel:BYTE_2 dst_unused:UNUSED_PRESERVE src0_sel:DWORD
	v_mul_f32_e32 v186, v100, v228
	v_mul_f32_e32 v187, v101, v229
	v_rndne_f32_e32 v186, v186
	v_rndne_f32_e32 v187, v187
	v_cvt_i32_f32_sdwa v190, v186 dst_sel:BYTE_3 dst_unused:UNUSED_PRESERVE src0_sel:DWORD
	v_cvt_i32_f32_sdwa v196, v187 dst_sel:BYTE_3 dst_unused:UNUSED_PRESERVE src0_sel:DWORD
	s_nop 0
	ds_write_b32 v139, v190 offset:672
	ds_write_b32 v139, v196 offset:928
	s_cmp_ge_u32 s10, 0x2b0
	s_cbranch_scc1 .Lc32_ffn1_nopf_5
	global_load_dwordx4 v[86:89], v138, s[56:57]
	s_add_u32 s56, s56, 0x15800
	s_addc_u32 s57, s57, 0
	global_load_dwordx4 v[90:93], v138, s[56:57]
	s_add_u32 s56, s56, 0x15800
	s_addc_u32 s57, s57, 0
	global_load_dwordx4 v[94:97], v138, s[56:57]
	s_add_u32 s56, s56, 0x15800
	s_addc_u32 s57, s57, 0
	global_load_dwordx4 v[98:101], v138, s[56:57]
	s_add_u32 s56, s56, 0x26f800
	s_addc_u32 s57, s57, 0
.Lc32_ffn1_nopf_5:
	v_mul_f32_e32 v186, v102, v226
	v_mul_f32_e32 v187, v103, v227
	v_rndne_f32_e32 v186, v186
	v_rndne_f32_e32 v187, v187
	v_cvt_i32_f32_sdwa v190, v186 dst_sel:BYTE_0 dst_unused:UNUSED_PAD src0_sel:DWORD
	v_cvt_i32_f32_sdwa v196, v187 dst_sel:BYTE_0 dst_unused:UNUSED_PAD src0_sel:DWORD
	v_mul_f32_e32 v186, v106, v226
	v_mul_f32_e32 v187, v107, v227
	v_rndne_f32_e32 v186, v186
	v_rndne_f32_e32 v187, v187
	v_cvt_i32_f32_sdwa v190, v186 dst_sel:BYTE_1 dst_unused:UNUSED_PRESERVE src0_sel:DWORD
	v_cvt_i32_f32_sdwa v196, v187 dst_sel:BYTE_1 dst_unused:UNUSED_PRESERVE src0_sel:DWORD
	v_mul_f32_e32 v186, v110, v226
	v_mul_f32_e32 v187, v111, v227
	v_rndne_f32_e32 v186, v186
	v_rndne_f32_e32 v187, v187
	v_cvt_i32_f32_sdwa v190, v186 dst_sel:BYTE_2 dst_unused:UNUSED_PRESERVE src0_sel:DWORD
	v_cvt_i32_f32_sdwa v196, v187 dst_sel:BYTE_2 dst_unused:UNUSED_PRESERVE src0_sel:DWORD
	v_mul_f32_e32 v186, v114, v226
	v_mul_f32_e32 v187, v115, v227
	v_rndne_f32_e32 v186, v186
	v_rndne_f32_e32 v187, v187
	v_cvt_i32_f32_sdwa v190, v186 dst_sel:BYTE_3 dst_unused:UNUSED_PRESERVE src0_sel:DWORD
	v_cvt_i32_f32_sdwa v196, v187 dst_sel:BYTE_3 dst_unused:UNUSED_PRESERVE src0_sel:DWORD
	s_nop 0
	ds_write_b32 v139, v190 offset:192
	ds_write_b32 v139, v196 offset:448
	v_mul_f32_e32 v186, v104, v228
	v_mul_f32_e32 v187, v105, v229
	v_rndne_f32_e32 v186, v186
	v_rndne_f32_e32 v187, v187
	v_cvt_i32_f32_sdwa v190, v186 dst_sel:BYTE_0 dst_unused:UNUSED_PAD src0_sel:DWORD
	v_cvt_i32_f32_sdwa v196, v187 dst_sel:BYTE_0 dst_unused:UNUSED_PAD src0_sel:DWORD
	v_mul_f32_e32 v186, v108, v228
	v_mul_f32_e32 v187, v109, v229
	v_rndne_f32_e32 v186, v186
	v_rndne_f32_e32 v187, v187
	v_cvt_i32_f32_sdwa v190, v186 dst_sel:BYTE_1 dst_unused:UNUSED_PRESERVE src0_sel:DWORD
	v_cvt_i32_f32_sdwa v196, v187 dst_sel:BYTE_1 dst_unused:UNUSED_PRESERVE src0_sel:DWORD
	v_mul_f32_e32 v186, v112, v228
	v_mul_f32_e32 v187, v113, v229
	v_rndne_f32_e32 v186, v186
	v_rndne_f32_e32 v187, v187
	v_cvt_i32_f32_sdwa v190, v186 dst_sel:BYTE_2 dst_unused:UNUSED_PRESERVE src0_sel:DWORD
	v_cvt_i32_f32_sdwa v196, v187 dst_sel:BYTE_2 dst_unused:UNUSED_PRESERVE src0_sel:DWORD
	v_mul_f32_e32 v186, v116, v228
	v_mul_f32_e32 v187, v117, v229
	v_rndne_f32_e32 v186, v186
	v_rndne_f32_e32 v187, v187
	v_cvt_i32_f32_sdwa v190, v186 dst_sel:BYTE_3 dst_unused:UNUSED_PRESERVE src0_sel:DWORD
	v_cvt_i32_f32_sdwa v196, v187 dst_sel:BYTE_3 dst_unused:UNUSED_PRESERVE src0_sel:DWORD
	s_nop 0
	ds_write_b32 v139, v190 offset:704
	ds_write_b32 v139, v196 offset:960
	s_cmp_ge_u32 s10, 0x2b0
	s_cbranch_scc1 .Lc32_ffn1_nopf_6
	global_load_dwordx4 v[102:105], v138, s[56:57]
	s_add_u32 s56, s56, 0x15800
	s_addc_u32 s57, s57, 0
	global_load_dwordx4 v[106:109], v138, s[56:57]
	s_add_u32 s56, s56, 0x15800
	s_addc_u32 s57, s57, 0
	global_load_dwordx4 v[110:113], v138, s[56:57]
	s_add_u32 s56, s56, 0x15800
	s_addc_u32 s57, s57, 0
	global_load_dwordx4 v[114:117], v138, s[56:57]
	s_add_u32 s56, s56, 0x26f800
	s_addc_u32 s57, s57, 0
.Lc32_ffn1_nopf_6:
	v_mul_f32_e32 v186, v118, v226
	v_mul_f32_e32 v187, v119, v227
	v_rndne_f32_e32 v186, v186
	v_rndne_f32_e32 v187, v187
	v_cvt_i32_f32_sdwa v190, v186 dst_sel:BYTE_0 dst_unused:UNUSED_PAD src0_sel:DWORD
	v_cvt_i32_f32_sdwa v196, v187 dst_sel:BYTE_0 dst_unused:UNUSED_PAD src0_sel:DWORD
	v_mul_f32_e32 v186, v122, v226
	v_mul_f32_e32 v187, v123, v227
	v_rndne_f32_e32 v186, v186
	v_rndne_f32_e32 v187, v187
	v_cvt_i32_f32_sdwa v190, v186 dst_sel:BYTE_1 dst_unused:UNUSED_PRESERVE src0_sel:DWORD
	v_cvt_i32_f32_sdwa v196, v187 dst_sel:BYTE_1 dst_unused:UNUSED_PRESERVE src0_sel:DWORD
	v_mul_f32_e32 v186, v126, v226
	v_mul_f32_e32 v187, v127, v227
	v_rndne_f32_e32 v186, v186
	v_rndne_f32_e32 v187, v187
	v_cvt_i32_f32_sdwa v190, v186 dst_sel:BYTE_2 dst_unused:UNUSED_PRESERVE src0_sel:DWORD
	v_cvt_i32_f32_sdwa v196, v187 dst_sel:BYTE_2 dst_unused:UNUSED_PRESERVE src0_sel:DWORD
	v_mul_f32_e32 v186, v130, v226
	v_mul_f32_e32 v187, v131, v227
	v_rndne_f32_e32 v186, v186
	v_rndne_f32_e32 v187, v187
	v_cvt_i32_f32_sdwa v190, v186 dst_sel:BYTE_3 dst_unused:UNUSED_PRESERVE src0_sel:DWORD
	v_cvt_i32_f32_sdwa v196, v187 dst_sel:BYTE_3 dst_unused:UNUSED_PRESERVE src0_sel:DWORD
	s_nop 0
	ds_write_b32 v139, v190 offset:224
	ds_write_b32 v139, v196 offset:480
	v_mul_f32_e32 v186, v120, v228
	v_mul_f32_e32 v187, v121, v229
	v_rndne_f32_e32 v186, v186
	v_rndne_f32_e32 v187, v187
	v_cvt_i32_f32_sdwa v190, v186 dst_sel:BYTE_0 dst_unused:UNUSED_PAD src0_sel:DWORD
	v_cvt_i32_f32_sdwa v196, v187 dst_sel:BYTE_0 dst_unused:UNUSED_PAD src0_sel:DWORD
	v_mul_f32_e32 v186, v124, v228
	v_mul_f32_e32 v187, v125, v229
	v_rndne_f32_e32 v186, v186
	v_rndne_f32_e32 v187, v187
	v_cvt_i32_f32_sdwa v190, v186 dst_sel:BYTE_1 dst_unused:UNUSED_PRESERVE src0_sel:DWORD
	v_cvt_i32_f32_sdwa v196, v187 dst_sel:BYTE_1 dst_unused:UNUSED_PRESERVE src0_sel:DWORD
	v_mul_f32_e32 v186, v128, v228
	v_mul_f32_e32 v187, v129, v229
	v_rndne_f32_e32 v186, v186
	v_rndne_f32_e32 v187, v187
	v_cvt_i32_f32_sdwa v190, v186 dst_sel:BYTE_2 dst_unused:UNUSED_PRESERVE src0_sel:DWORD
	v_cvt_i32_f32_sdwa v196, v187 dst_sel:BYTE_2 dst_unused:UNUSED_PRESERVE src0_sel:DWORD
	v_mul_f32_e32 v186, v132, v228
	v_mul_f32_e32 v187, v133, v229
	v_rndne_f32_e32 v186, v186
	v_rndne_f32_e32 v187, v187
	v_cvt_i32_f32_sdwa v190, v186 dst_sel:BYTE_3 dst_unused:UNUSED_PRESERVE src0_sel:DWORD
	v_cvt_i32_f32_sdwa v196, v187 dst_sel:BYTE_3 dst_unused:UNUSED_PRESERVE src0_sel:DWORD
	s_nop 0
	ds_write_b32 v139, v190 offset:736
	ds_write_b32 v139, v196 offset:992
	s_cmp_ge_u32 s10, 0x2b0
	s_cbranch_scc1 .Lc32_ffn1_nopf_7
	global_load_dwordx4 v[118:121], v138, s[56:57]
	s_add_u32 s56, s56, 0x15800
	s_addc_u32 s57, s57, 0
	global_load_dwordx4 v[122:125], v138, s[56:57]
	s_add_u32 s56, s56, 0x15800
	s_addc_u32 s57, s57, 0
	global_load_dwordx4 v[126:129], v138, s[56:57]
	s_add_u32 s56, s56, 0x15800
	s_addc_u32 s57, s57, 0
	global_load_dwordx4 v[130:133], v138, s[56:57]
.Lc32_ffn1_nopf_7:
	s_waitcnt lgkmcnt(0)
	s_lshl_b32 s3, s60, 12
	s_add_u32 s3, s3, s52
	s_add_u32 s58, s34, s3
	s_addc_u32 s59, s35, 0
	s_add_u32 s58, s58, 0xe700000
	s_addc_u32 s59, s59, 0
	ds_read_b128 v[204:207], v212 offset:0
	s_waitcnt lgkmcnt(0)
	global_store_dwordx4 v213, v[204:207], s[58:59]
	s_add_u32 s58, s58, 0x4000
	s_addc_u32 s59, s59, 0
	ds_read_b128 v[208:211], v212 offset:1024
	s_waitcnt lgkmcnt(0)
	global_store_dwordx4 v213, v[208:211], s[58:59]
	s_add_u32 s58, s58, 0x4000
	s_addc_u32 s59, s59, 0
	ds_read_b128 v[204:207], v212 offset:2048
	s_waitcnt lgkmcnt(0)
	global_store_dwordx4 v213, v[204:207], s[58:59]
	s_add_u32 s58, s58, 0x4000
	s_addc_u32 s59, s59, 0
	ds_read_b128 v[208:211], v212 offset:3072
	s_waitcnt lgkmcnt(0)
	global_store_dwordx4 v213, v[208:211], s[58:59]
	s_add_u32 s58, s58, 0x4000
	s_addc_u32 s59, s59, 0
	ds_read_b128 v[204:207], v212 offset:4096
	s_waitcnt lgkmcnt(0)
	global_store_dwordx4 v213, v[204:207], s[58:59]
	s_add_u32 s58, s58, 0x4000
	s_addc_u32 s59, s59, 0
	ds_read_b128 v[208:211], v212 offset:5120
	s_waitcnt lgkmcnt(0)
	global_store_dwordx4 v213, v[208:211], s[58:59]
	s_add_u32 s58, s58, 0x4000
	s_addc_u32 s59, s59, 0
	ds_read_b128 v[204:207], v212 offset:6144
	s_waitcnt lgkmcnt(0)
	global_store_dwordx4 v213, v[204:207], s[58:59]
	s_add_u32 s58, s58, 0x4000
	s_addc_u32 s59, s59, 0
	ds_read_b128 v[208:211], v212 offset:7168
	s_waitcnt lgkmcnt(0)
	global_store_dwordx4 v213, v[208:211], s[58:59]
	s_xor_b32 s11, s11, 1
	s_add_u32 s0, s0, 128
	s_cmp_lt_u32 s0, 0x2b0
	s_cbranch_scc1 .Lc32_ffn1_loop
.Lc32_ffn1_done:
	v_readlane_b32 s48, v255, 27
	v_readlane_b32 s49, v255, 28
	v_mul_u32_u24_e32 v138, 0x28000, v136
	v_lshl_add_u32 v138, v137, 4, v138
	s_mul_i32 s3, s52, 0xa000
	s_nop 1
	s_add_u32 s48, s48, s3
	s_addc_u32 s49, s49, 0
	s_mov_b32 s0, s72
	s_cmp_ge_u32 s0, 0x140
	s_cbranch_scc1 .Lc32_mixer_done
	s_lshl_b32 s3, s0, 7
	s_add_u32 s56, s48, s3
	s_addc_u32 s57, s49, 0
	global_load_dwordx4 v[6:9], v138, s[56:57]
	s_add_u32 s56, s56, 0xa000
	s_addc_u32 s57, s57, 0
	global_load_dwordx4 v[10:13], v138, s[56:57]
	s_add_u32 s56, s56, 0xa000
	s_addc_u32 s57, s57, 0
	global_load_dwordx4 v[14:17], v138, s[56:57]
	s_add_u32 s56, s56, 0xa000
	s_addc_u32 s57, s57, 0
	global_load_dwordx4 v[18:21], v138, s[56:57]
	s_add_u32 s56, s56, 0x122000
	s_addc_u32 s57, s57, 0
	global_load_dwordx4 v[22:25], v138, s[56:57]
	s_add_u32 s56, s56, 0xa000
	s_addc_u32 s57, s57, 0
	global_load_dwordx4 v[26:29], v138, s[56:57]
	s_add_u32 s56, s56, 0xa000
	s_addc_u32 s57, s57, 0
	global_load_dwordx4 v[30:33], v138, s[56:57]
	s_add_u32 s56, s56, 0xa000
	s_addc_u32 s57, s57, 0
	global_load_dwordx4 v[34:37], v138, s[56:57]
	s_add_u32 s56, s56, 0x122000
	s_addc_u32 s57, s57, 0
	global_load_dwordx4 v[38:41], v138, s[56:57]
	s_add_u32 s56, s56, 0xa000
	s_addc_u32 s57, s57, 0
	global_load_dwordx4 v[42:45], v138, s[56:57]
	s_add_u32 s56, s56, 0xa000
	s_addc_u32 s57, s57, 0
	global_load_dwordx4 v[46:49], v138, s[56:57]
	s_add_u32 s56, s56, 0xa000
	s_addc_u32 s57, s57, 0
	global_load_dwordx4 v[50:53], v138, s[56:57]
	s_add_u32 s56, s56, 0x122000
	s_addc_u32 s57, s57, 0
	global_load_dwordx4 v[54:57], v138, s[56:57]
	s_add_u32 s56, s56, 0xa000
	s_addc_u32 s57, s57, 0
	global_load_dwordx4 v[58:61], v138, s[56:57]
	s_add_u32 s56, s56, 0xa000
	s_addc_u32 s57, s57, 0
	global_load_dwordx4 v[62:65], v138, s[56:57]
	s_add_u32 s56, s56, 0xa000
	s_addc_u32 s57, s57, 0
	global_load_dwordx4 v[66:69], v138, s[56:57]
	s_add_u32 s56, s56, 0x122000
	s_addc_u32 s57, s57, 0
	global_load_dwordx4 v[70:73], v138, s[56:57]
	s_add_u32 s56, s56, 0xa000
	s_addc_u32 s57, s57, 0
	global_load_dwordx4 v[74:77], v138, s[56:57]
	s_add_u32 s56, s56, 0xa000
	s_addc_u32 s57, s57, 0
	global_load_dwordx4 v[78:81], v138, s[56:57]
	s_add_u32 s56, s56, 0xa000
	s_addc_u32 s57, s57, 0
	global_load_dwordx4 v[82:85], v138, s[56:57]
	s_add_u32 s56, s56, 0x122000
	s_addc_u32 s57, s57, 0
	global_load_dwordx4 v[86:89], v138, s[56:57]
	s_add_u32 s56, s56, 0xa000
	s_addc_u32 s57, s57, 0
	global_load_dwordx4 v[90:93], v138, s[56:57]
	s_add_u32 s56, s56, 0xa000
	s_addc_u32 s57, s57, 0
	global_load_dwordx4 v[94:97], v138, s[56:57]
	s_add_u32 s56, s56, 0xa000
	s_addc_u32 s57, s57, 0
	global_load_dwordx4 v[98:101], v138, s[56:57]
	s_add_u32 s56, s56, 0x122000
	s_addc_u32 s57, s57, 0
	global_load_dwordx4 v[102:105], v138, s[56:57]
	s_add_u32 s56, s56, 0xa000
	s_addc_u32 s57, s57, 0
	global_load_dwordx4 v[106:109], v138, s[56:57]
	s_add_u32 s56, s56, 0xa000
	s_addc_u32 s57, s57, 0
	global_load_dwordx4 v[110:113], v138, s[56:57]
	s_add_u32 s56, s56, 0xa000
	s_addc_u32 s57, s57, 0
	global_load_dwordx4 v[114:117], v138, s[56:57]
	s_add_u32 s56, s56, 0x122000
	s_addc_u32 s57, s57, 0
	global_load_dwordx4 v[118:121], v138, s[56:57]
	s_add_u32 s56, s56, 0xa000
	s_addc_u32 s57, s57, 0
	global_load_dwordx4 v[122:125], v138, s[56:57]
	s_add_u32 s56, s56, 0xa000
	s_addc_u32 s57, s57, 0
	global_load_dwordx4 v[126:129], v138, s[56:57]
	s_add_u32 s56, s56, 0xa000
	s_addc_u32 s57, s57, 0
	global_load_dwordx4 v[130:133], v138, s[56:57]

.Lc32_mixer_got:
	v_max_f32_e32 v220, v220, v240
	v_max_f32_e32 v221, v221, v242
	v_max_f32_e32 v222, v222, v244
	v_max_f32_e32 v223, v223, v246
	s_mov_b64 exec, s[70:71]
	v_lshlrev_b32_e32 v174, 2, v137
	ds_bpermute_b32 v175, v174, v220
	ds_bpermute_b32 v176, v174, v221
	ds_bpermute_b32 v177, v174, v222
	ds_bpermute_b32 v178, v174, v223
	s_waitcnt lgkmcnt(0)
	v_mov_b32_e32 v220, v175
	v_mov_b32_e32 v221, v176
	v_mov_b32_e32 v222, v177
	v_mov_b32_e32 v223, v178
	s_or_b32 s3, s1, s12
	s_cmp_lg_u32 s3, 0
	s_cbranch_scc1 .Lc32_mixer_nocm
	s_lshl_b32 s3, s2, 2
	s_add_u32 s56, s34, s3
	s_addc_u32 s57, s35, 0
	s_add_u32 s56, s56, 0xe0000
	s_addc_u32 s57, s57, 0
	s_mov_b64 s[70:71], exec
	s_mov_b64 exec, 0xff
	global_store_dwordx4 v230, v[220:223], s[56:57]
	s_mov_b64 exec, s[70:71]
.Lc32_mixer_nocm:
	v_div_scale_f32 v175, s[70:71], v220, v220, s74
	v_rcp_f32_e32 v176, v175
	s_nop 0
	v_fma_f32 v177, -v175, v176, 1.0
	v_fmac_f32_e32 v176, v177, v176
	v_div_scale_f32 v177, vcc, s74, v220, s74
	v_mul_f32_e32 v178, v177, v176
	v_fma_f32 v180, -v175, v178, v177
	v_fmac_f32_e32 v178, v180, v176
	v_fma_f32 v175, -v175, v178, v177
	s_nop 0
	v_div_fmas_f32 v175, v175, v176, v178
	v_div_fixup_f32 v175, v175, v220, s74
	v_cmp_lt_f32_e32 vcc, 0, v220
	s_nop 1
	v_cndmask_b32_e32 v226, 0, v175, vcc
	v_div_scale_f32 v175, s[70:71], v221, v221, s74
	v_rcp_f32_e32 v176, v175
	s_nop 0
	v_fma_f32 v177, -v175, v176, 1.0
	v_fmac_f32_e32 v176, v177, v176
	v_div_scale_f32 v177, vcc, s74, v221, s74
	v_mul_f32_e32 v178, v177, v176
	v_fma_f32 v180, -v175, v178, v177
	v_fmac_f32_e32 v178, v180, v176
	v_fma_f32 v175, -v175, v178, v177
	s_nop 0
	v_div_fmas_f32 v175, v175, v176, v178
	v_div_fixup_f32 v175, v175, v221, s74
	v_cmp_lt_f32_e32 vcc, 0, v221
	s_nop 1
	v_cndmask_b32_e32 v227, 0, v175, vcc
	v_div_scale_f32 v175, s[70:71], v222, v222, s74
	v_rcp_f32_e32 v176, v175
	s_nop 0
	v_fma_f32 v177, -v175, v176, 1.0
	v_fmac_f32_e32 v176, v177, v176
	v_div_scale_f32 v177, vcc, s74, v222, s74
	v_mul_f32_e32 v178, v177, v176
	v_fma_f32 v180, -v175, v178, v177
	v_fmac_f32_e32 v178, v180, v176
	v_fma_f32 v175, -v175, v178, v177
	s_nop 0
	v_div_fmas_f32 v175, v175, v176, v178
	v_div_fixup_f32 v175, v175, v222, s74
	v_cmp_lt_f32_e32 vcc, 0, v222
	s_nop 1
	v_cndmask_b32_e32 v228, 0, v175, vcc
	v_div_scale_f32 v175, s[70:71], v223, v223, s74
	v_rcp_f32_e32 v176, v175
	s_nop 0
	v_fma_f32 v177, -v175, v176, 1.0
	v_fmac_f32_e32 v176, v177, v176
	v_div_scale_f32 v177, vcc, s74, v223, s74
	v_mul_f32_e32 v178, v177, v176
	v_fma_f32 v180, -v175, v178, v177
	v_fmac_f32_e32 v178, v180, v176
	v_fma_f32 v175, -v175, v178, v177
	s_nop 0
	v_div_fmas_f32 v175, v175, v176, v178
	v_div_fixup_f32 v175, v175, v223, s74
	v_cmp_lt_f32_e32 vcc, 0, v223
	s_nop 1
	v_cndmask_b32_e32 v229, 0, v175, vcc
	s_lshl_b32 s3, s2, 13
	s_lshl_b32 s10, s52, 1
	s_add_u32 s3, s3, s10
	s_add_u32 s36, s34, s3
	s_addc_u32 s37, s35, 0
	s_add_u32 s36, s36, 0x3f400000
	s_addc_u32 s37, s37, 0
	s_add_u32 s38, s36, 0x2000
	s_addc_u32 s39, s37, 0
	s_add_u32 s78, s38, 0x2000
	s_addc_u32 s79, s39, 0
	s_add_u32 s80, s78, 0x2000
	s_addc_u32 s81, s79, 0
	s_add_u32 s10, s0, 128
	s_lshl_b32 s3, s10, 7
	s_add_u32 s56, s48, s3
	s_addc_u32 s57, s49, 0
	s_cmp_ge_u32 s2, 0x1800
	s_cbranch_scc1 .Lc32_mixer_nobf_0
	v_cvt_pk_bf16_f32 v236, v6, v10
	v_cvt_pk_bf16_f32 v237, v14, v18
	global_store_dwordx2 v231, v[236:237], s[36:37] offset:0
	v_cvt_pk_bf16_f32 v238, v7, v11
	v_cvt_pk_bf16_f32 v239, v15, v19
	global_store_dwordx2 v231, v[238:239], s[38:39] offset:0
	v_cvt_pk_bf16_f32 v236, v8, v12
	v_cvt_pk_bf16_f32 v237, v16, v20
	global_store_dwordx2 v231, v[236:237], s[78:79] offset:0
	v_cvt_pk_bf16_f32 v238, v9, v13
	v_cvt_pk_bf16_f32 v239, v17, v21
	global_store_dwordx2 v231, v[238:239], s[80:81] offset:0
.Lc32_mixer_nobf_0:
	v_mul_f32_e32 v186, v6, v226
	v_mul_f32_e32 v187, v7, v227
	v_rndne_f32_e32 v186, v186
	v_rndne_f32_e32 v187, v187
	v_cvt_i32_f32_sdwa v190, v186 dst_sel:BYTE_0 dst_unused:UNUSED_PAD src0_sel:DWORD
	v_cvt_i32_f32_sdwa v196, v187 dst_sel:BYTE_0 dst_unused:UNUSED_PAD src0_sel:DWORD
	v_mul_f32_e32 v186, v10, v226
	v_mul_f32_e32 v187, v11, v227
	v_rndne_f32_e32 v186, v186
	v_rndne_f32_e32 v187, v187
	v_cvt_i32_f32_sdwa v190, v186 dst_sel:BYTE_1 dst_unused:UNUSED_PRESERVE src0_sel:DWORD
	v_cvt_i32_f32_sdwa v196, v187 dst_sel:BYTE_1 dst_unused:UNUSED_PRESERVE src0_sel:DWORD
	v_mul_f32_e32 v186, v14, v226
	v_mul_f32_e32 v187, v15, v227
	v_rndne_f32_e32 v186, v186
	v_rndne_f32_e32 v187, v187
	v_cvt_i32_f32_sdwa v190, v186 dst_sel:BYTE_2 dst_unused:UNUSED_PRESERVE src0_sel:DWORD
	v_cvt_i32_f32_sdwa v196, v187 dst_sel:BYTE_2 dst_unused:UNUSED_PRESERVE src0_sel:DWORD
	v_mul_f32_e32 v186, v18, v226
	v_mul_f32_e32 v187, v19, v227
	v_rndne_f32_e32 v186, v186
	v_rndne_f32_e32 v187, v187
	v_cvt_i32_f32_sdwa v190, v186 dst_sel:BYTE_3 dst_unused:UNUSED_PRESERVE src0_sel:DWORD
	v_cvt_i32_f32_sdwa v196, v187 dst_sel:BYTE_3 dst_unused:UNUSED_PRESERVE src0_sel:DWORD
	s_nop 0
	ds_write_b32 v139, v190 offset:0
	ds_write_b32 v139, v196 offset:256
	v_mul_f32_e32 v186, v8, v228
	v_mul_f32_e32 v187, v9, v229
	v_rndne_f32_e32 v186, v186
	v_rndne_f32_e32 v187, v187
	v_cvt_i32_f32_sdwa v190, v186 dst_sel:BYTE_0 dst_unused:UNUSED_PAD src0_sel:DWORD
	v_cvt_i32_f32_sdwa v196, v187 dst_sel:BYTE_0 dst_unused:UNUSED_PAD src0_sel:DWORD
	v_mul_f32_e32 v186, v12, v228
	v_mul_f32_e32 v187, v13, v229
	v_rndne_f32_e32 v186, v186
	v_rndne_f32_e32 v187, v187
	v_cvt_i32_f32_sdwa v190, v186 dst_sel:BYTE_1 dst_unused:UNUSED_PRESERVE src0_sel:DWORD
	v_cvt_i32_f32_sdwa v196, v187 dst_sel:BYTE_1 dst_unused:UNUSED_PRESERVE src0_sel:DWORD
	v_mul_f32_e32 v186, v16, v228
	v_mul_f32_e32 v187, v17, v229
	v_rndne_f32_e32 v186, v186
	v_rndne_f32_e32 v187, v187
	v_cvt_i32_f32_sdwa v190, v186 dst_sel:BYTE_2 dst_unused:UNUSED_PRESERVE src0_sel:DWORD
	v_cvt_i32_f32_sdwa v196, v187 dst_sel:BYTE_2 dst_unused:UNUSED_PRESERVE src0_sel:DWORD
	v_mul_f32_e32 v186, v20, v228
	v_mul_f32_e32 v187, v21, v229
	v_rndne_f32_e32 v186, v186
	v_rndne_f32_e32 v187, v187
	v_cvt_i32_f32_sdwa v190, v186 dst_sel:BYTE_3 dst_unused:UNUSED_PRESERVE src0_sel:DWORD
	v_cvt_i32_f32_sdwa v196, v187 dst_sel:BYTE_3 dst_unused:UNUSED_PRESERVE src0_sel:DWORD
	s_nop 0
	ds_write_b32 v139, v190 offset:512
	ds_write_b32 v139, v196 offset:768
	s_cmp_ge_u32 s10, 0x140
	s_cbranch_scc1 .Lc32_mixer_nopf_0
	global_load_dwordx4 v[6:9], v138, s[56:57]
	s_add_u32 s56, s56, 0xa000
	s_addc_u32 s57, s57, 0
	global_load_dwordx4 v[10:13], v138, s[56:57]
	s_add_u32 s56, s56, 0xa000
	s_addc_u32 s57, s57, 0
	global_load_dwordx4 v[14:17], v138, s[56:57]
	s_add_u32 s56, s56, 0xa000
	s_addc_u32 s57, s57, 0
	global_load_dwordx4 v[18:21], v138, s[56:57]
	s_add_u32 s56, s56, 0x122000
	s_addc_u32 s57, s57, 0
.Lc32_mixer_nopf_0:
	s_cmp_ge_u32 s2, 0x1800
	s_cbranch_scc1 .Lc32_mixer_nobf_1
	v_cvt_pk_bf16_f32 v236, v22, v26
	v_cvt_pk_bf16_f32 v237, v30, v34
	global_store_dwordx2 v231, v[236:237], s[36:37] offset:64
	v_cvt_pk_bf16_f32 v238, v23, v27
	v_cvt_pk_bf16_f32 v239, v31, v35
	global_store_dwordx2 v231, v[238:239], s[38:39] offset:64
	v_cvt_pk_bf16_f32 v236, v24, v28
	v_cvt_pk_bf16_f32 v237, v32, v36
	global_store_dwordx2 v231, v[236:237], s[78:79] offset:64
	v_cvt_pk_bf16_f32 v238, v25, v29
	v_cvt_pk_bf16_f32 v239, v33, v37
	global_store_dwordx2 v231, v[238:239], s[80:81] offset:64
.Lc32_mixer_nobf_1:
	v_mul_f32_e32 v186, v22, v226
	v_mul_f32_e32 v187, v23, v227
	v_rndne_f32_e32 v186, v186
	v_rndne_f32_e32 v187, v187
	v_cvt_i32_f32_sdwa v190, v186 dst_sel:BYTE_0 dst_unused:UNUSED_PAD src0_sel:DWORD
	v_cvt_i32_f32_sdwa v196, v187 dst_sel:BYTE_0 dst_unused:UNUSED_PAD src0_sel:DWORD
	v_mul_f32_e32 v186, v26, v226
	v_mul_f32_e32 v187, v27, v227
	v_rndne_f32_e32 v186, v186
	v_rndne_f32_e32 v187, v187
	v_cvt_i32_f32_sdwa v190, v186 dst_sel:BYTE_1 dst_unused:UNUSED_PRESERVE src0_sel:DWORD
	v_cvt_i32_f32_sdwa v196, v187 dst_sel:BYTE_1 dst_unused:UNUSED_PRESERVE src0_sel:DWORD
	v_mul_f32_e32 v186, v30, v226
	v_mul_f32_e32 v187, v31, v227
	v_rndne_f32_e32 v186, v186
	v_rndne_f32_e32 v187, v187
	v_cvt_i32_f32_sdwa v190, v186 dst_sel:BYTE_2 dst_unused:UNUSED_PRESERVE src0_sel:DWORD
	v_cvt_i32_f32_sdwa v196, v187 dst_sel:BYTE_2 dst_unused:UNUSED_PRESERVE src0_sel:DWORD
	v_mul_f32_e32 v186, v34, v226
	v_mul_f32_e32 v187, v35, v227
	v_rndne_f32_e32 v186, v186
	v_rndne_f32_e32 v187, v187
	v_cvt_i32_f32_sdwa v190, v186 dst_sel:BYTE_3 dst_unused:UNUSED_PRESERVE src0_sel:DWORD
	v_cvt_i32_f32_sdwa v196, v187 dst_sel:BYTE_3 dst_unused:UNUSED_PRESERVE src0_sel:DWORD
	s_nop 0
	ds_write_b32 v139, v190 offset:32
	ds_write_b32 v139, v196 offset:288
	v_mul_f32_e32 v186, v24, v228
	v_mul_f32_e32 v187, v25, v229
	v_rndne_f32_e32 v186, v186
	v_rndne_f32_e32 v187, v187
	v_cvt_i32_f32_sdwa v190, v186 dst_sel:BYTE_0 dst_unused:UNUSED_PAD src0_sel:DWORD
	v_cvt_i32_f32_sdwa v196, v187 dst_sel:BYTE_0 dst_unused:UNUSED_PAD src0_sel:DWORD
	v_mul_f32_e32 v186, v28, v228
	v_mul_f32_e32 v187, v29, v229
	v_rndne_f32_e32 v186, v186
	v_rndne_f32_e32 v187, v187
	v_cvt_i32_f32_sdwa v190, v186 dst_sel:BYTE_1 dst_unused:UNUSED_PRESERVE src0_sel:DWORD
	v_cvt_i32_f32_sdwa v196, v187 dst_sel:BYTE_1 dst_unused:UNUSED_PRESERVE src0_sel:DWORD
	v_mul_f32_e32 v186, v32, v228
	v_mul_f32_e32 v187, v33, v229
	v_rndne_f32_e32 v186, v186
	v_rndne_f32_e32 v187, v187
	v_cvt_i32_f32_sdwa v190, v186 dst_sel:BYTE_2 dst_unused:UNUSED_PRESERVE src0_sel:DWORD
	v_cvt_i32_f32_sdwa v196, v187 dst_sel:BYTE_2 dst_unused:UNUSED_PRESERVE src0_sel:DWORD
	v_mul_f32_e32 v186, v36, v228
	v_mul_f32_e32 v187, v37, v229
	v_rndne_f32_e32 v186, v186
	v_rndne_f32_e32 v187, v187
	v_cvt_i32_f32_sdwa v190, v186 dst_sel:BYTE_3 dst_unused:UNUSED_PRESERVE src0_sel:DWORD
	v_cvt_i32_f32_sdwa v196, v187 dst_sel:BYTE_3 dst_unused:UNUSED_PRESERVE src0_sel:DWORD
	s_nop 0
	ds_write_b32 v139, v190 offset:544
	ds_write_b32 v139, v196 offset:800
	s_cmp_ge_u32 s10, 0x140
	s_cbranch_scc1 .Lc32_mixer_nopf_1
	global_load_dwordx4 v[22:25], v138, s[56:57]
	s_add_u32 s56, s56, 0xa000
	s_addc_u32 s57, s57, 0
	global_load_dwordx4 v[26:29], v138, s[56:57]
	s_add_u32 s56, s56, 0xa000
	s_addc_u32 s57, s57, 0
	global_load_dwordx4 v[30:33], v138, s[56:57]
	s_add_u32 s56, s56, 0xa000
	s_addc_u32 s57, s57, 0
	global_load_dwordx4 v[34:37], v138, s[56:57]
	s_add_u32 s56, s56, 0x122000
	s_addc_u32 s57, s57, 0
.Lc32_mixer_nopf_1:
	s_cmp_ge_u32 s2, 0x1800
	s_cbranch_scc1 .Lc32_mixer_nobf_2
	v_cvt_pk_bf16_f32 v236, v38, v42
	v_cvt_pk_bf16_f32 v237, v46, v50
	global_store_dwordx2 v231, v[236:237], s[36:37] offset:128
	v_cvt_pk_bf16_f32 v238, v39, v43
	v_cvt_pk_bf16_f32 v239, v47, v51
	global_store_dwordx2 v231, v[238:239], s[38:39] offset:128
	v_cvt_pk_bf16_f32 v236, v40, v44
	v_cvt_pk_bf16_f32 v237, v48, v52
	global_store_dwordx2 v231, v[236:237], s[78:79] offset:128
	v_cvt_pk_bf16_f32 v238, v41, v45
	v_cvt_pk_bf16_f32 v239, v49, v53
	global_store_dwordx2 v231, v[238:239], s[80:81] offset:128
.Lc32_mixer_nobf_2:
	v_mul_f32_e32 v186, v38, v226
	v_mul_f32_e32 v187, v39, v227
	v_rndne_f32_e32 v186, v186
	v_rndne_f32_e32 v187, v187
	v_cvt_i32_f32_sdwa v190, v186 dst_sel:BYTE_0 dst_unused:UNUSED_PAD src0_sel:DWORD
	v_cvt_i32_f32_sdwa v196, v187 dst_sel:BYTE_0 dst_unused:UNUSED_PAD src0_sel:DWORD
	v_mul_f32_e32 v186, v42, v226
	v_mul_f32_e32 v187, v43, v227
	v_rndne_f32_e32 v186, v186
	v_rndne_f32_e32 v187, v187
	v_cvt_i32_f32_sdwa v190, v186 dst_sel:BYTE_1 dst_unused:UNUSED_PRESERVE src0_sel:DWORD
	v_cvt_i32_f32_sdwa v196, v187 dst_sel:BYTE_1 dst_unused:UNUSED_PRESERVE src0_sel:DWORD
	v_mul_f32_e32 v186, v46, v226
	v_mul_f32_e32 v187, v47, v227
	v_rndne_f32_e32 v186, v186
	v_rndne_f32_e32 v187, v187
	v_cvt_i32_f32_sdwa v190, v186 dst_sel:BYTE_2 dst_unused:UNUSED_PRESERVE src0_sel:DWORD
	v_cvt_i32_f32_sdwa v196, v187 dst_sel:BYTE_2 dst_unused:UNUSED_PRESERVE src0_sel:DWORD
	v_mul_f32_e32 v186, v50, v226
	v_mul_f32_e32 v187, v51, v227
	v_rndne_f32_e32 v186, v186
	v_rndne_f32_e32 v187, v187
	v_cvt_i32_f32_sdwa v190, v186 dst_sel:BYTE_3 dst_unused:UNUSED_PRESERVE src0_sel:DWORD
	v_cvt_i32_f32_sdwa v196, v187 dst_sel:BYTE_3 dst_unused:UNUSED_PRESERVE src0_sel:DWORD
	s_nop 0
	ds_write_b32 v139, v190 offset:64
	ds_write_b32 v139, v196 offset:320
	v_mul_f32_e32 v186, v40, v228
	v_mul_f32_e32 v187, v41, v229
	v_rndne_f32_e32 v186, v186
	v_rndne_f32_e32 v187, v187
	v_cvt_i32_f32_sdwa v190, v186 dst_sel:BYTE_0 dst_unused:UNUSED_PAD src0_sel:DWORD
	v_cvt_i32_f32_sdwa v196, v187 dst_sel:BYTE_0 dst_unused:UNUSED_PAD src0_sel:DWORD
	v_mul_f32_e32 v186, v44, v228
	v_mul_f32_e32 v187, v45, v229
	v_rndne_f32_e32 v186, v186
	v_rndne_f32_e32 v187, v187
	v_cvt_i32_f32_sdwa v190, v186 dst_sel:BYTE_1 dst_unused:UNUSED_PRESERVE src0_sel:DWORD
	v_cvt_i32_f32_sdwa v196, v187 dst_sel:BYTE_1 dst_unused:UNUSED_PRESERVE src0_sel:DWORD
	v_mul_f32_e32 v186, v48, v228
	v_mul_f32_e32 v187, v49, v229
	v_rndne_f32_e32 v186, v186
	v_rndne_f32_e32 v187, v187
	v_cvt_i32_f32_sdwa v190, v186 dst_sel:BYTE_2 dst_unused:UNUSED_PRESERVE src0_sel:DWORD
	v_cvt_i32_f32_sdwa v196, v187 dst_sel:BYTE_2 dst_unused:UNUSED_PRESERVE src0_sel:DWORD
	v_mul_f32_e32 v186, v52, v228
	v_mul_f32_e32 v187, v53, v229
	v_rndne_f32_e32 v186, v186
	v_rndne_f32_e32 v187, v187
	v_cvt_i32_f32_sdwa v190, v186 dst_sel:BYTE_3 dst_unused:UNUSED_PRESERVE src0_sel:DWORD
	v_cvt_i32_f32_sdwa v196, v187 dst_sel:BYTE_3 dst_unused:UNUSED_PRESERVE src0_sel:DWORD
	s_nop 0
	ds_write_b32 v139, v190 offset:576
	ds_write_b32 v139, v196 offset:832
	s_cmp_ge_u32 s10, 0x140
	s_cbranch_scc1 .Lc32_mixer_nopf_2
	global_load_dwordx4 v[38:41], v138, s[56:57]
	s_add_u32 s56, s56, 0xa000
	s_addc_u32 s57, s57, 0
	global_load_dwordx4 v[42:45], v138, s[56:57]
	s_add_u32 s56, s56, 0xa000
	s_addc_u32 s57, s57, 0
	global_load_dwordx4 v[46:49], v138, s[56:57]
	s_add_u32 s56, s56, 0xa000
	s_addc_u32 s57, s57, 0
	global_load_dwordx4 v[50:53], v138, s[56:57]
	s_add_u32 s56, s56, 0x122000
	s_addc_u32 s57, s57, 0
.Lc32_mixer_nopf_2:
	s_cmp_ge_u32 s2, 0x1800
	s_cbranch_scc1 .Lc32_mixer_nobf_3
	v_cvt_pk_bf16_f32 v236, v54, v58
	v_cvt_pk_bf16_f32 v237, v62, v66
	global_store_dwordx2 v231, v[236:237], s[36:37] offset:192
	v_cvt_pk_bf16_f32 v238, v55, v59
	v_cvt_pk_bf16_f32 v239, v63, v67
	global_store_dwordx2 v231, v[238:239], s[38:39] offset:192
	v_cvt_pk_bf16_f32 v236, v56, v60
	v_cvt_pk_bf16_f32 v237, v64, v68
	global_store_dwordx2 v231, v[236:237], s[78:79] offset:192
	v_cvt_pk_bf16_f32 v238, v57, v61
	v_cvt_pk_bf16_f32 v239, v65, v69
	global_store_dwordx2 v231, v[238:239], s[80:81] offset:192
.Lc32_mixer_nobf_3:
	v_mul_f32_e32 v186, v54, v226
	v_mul_f32_e32 v187, v55, v227
	v_rndne_f32_e32 v186, v186
	v_rndne_f32_e32 v187, v187
	v_cvt_i32_f32_sdwa v190, v186 dst_sel:BYTE_0 dst_unused:UNUSED_PAD src0_sel:DWORD
	v_cvt_i32_f32_sdwa v196, v187 dst_sel:BYTE_0 dst_unused:UNUSED_PAD src0_sel:DWORD
	v_mul_f32_e32 v186, v58, v226
	v_mul_f32_e32 v187, v59, v227
	v_rndne_f32_e32 v186, v186
	v_rndne_f32_e32 v187, v187
	v_cvt_i32_f32_sdwa v190, v186 dst_sel:BYTE_1 dst_unused:UNUSED_PRESERVE src0_sel:DWORD
	v_cvt_i32_f32_sdwa v196, v187 dst_sel:BYTE_1 dst_unused:UNUSED_PRESERVE src0_sel:DWORD
	v_mul_f32_e32 v186, v62, v226
	v_mul_f32_e32 v187, v63, v227
	v_rndne_f32_e32 v186, v186
	v_rndne_f32_e32 v187, v187
	v_cvt_i32_f32_sdwa v190, v186 dst_sel:BYTE_2 dst_unused:UNUSED_PRESERVE src0_sel:DWORD
	v_cvt_i32_f32_sdwa v196, v187 dst_sel:BYTE_2 dst_unused:UNUSED_PRESERVE src0_sel:DWORD
	v_mul_f32_e32 v186, v66, v226
	v_mul_f32_e32 v187, v67, v227
	v_rndne_f32_e32 v186, v186
	v_rndne_f32_e32 v187, v187
	v_cvt_i32_f32_sdwa v190, v186 dst_sel:BYTE_3 dst_unused:UNUSED_PRESERVE src0_sel:DWORD
	v_cvt_i32_f32_sdwa v196, v187 dst_sel:BYTE_3 dst_unused:UNUSED_PRESERVE src0_sel:DWORD
	s_nop 0
	ds_write_b32 v139, v190 offset:96
	ds_write_b32 v139, v196 offset:352
	v_mul_f32_e32 v186, v56, v228
	v_mul_f32_e32 v187, v57, v229
	v_rndne_f32_e32 v186, v186
	v_rndne_f32_e32 v187, v187
	v_cvt_i32_f32_sdwa v190, v186 dst_sel:BYTE_0 dst_unused:UNUSED_PAD src0_sel:DWORD
	v_cvt_i32_f32_sdwa v196, v187 dst_sel:BYTE_0 dst_unused:UNUSED_PAD src0_sel:DWORD
	v_mul_f32_e32 v186, v60, v228
	v_mul_f32_e32 v187, v61, v229
	v_rndne_f32_e32 v186, v186
	v_rndne_f32_e32 v187, v187
	v_cvt_i32_f32_sdwa v190, v186 dst_sel:BYTE_1 dst_unused:UNUSED_PRESERVE src0_sel:DWORD
	v_cvt_i32_f32_sdwa v196, v187 dst_sel:BYTE_1 dst_unused:UNUSED_PRESERVE src0_sel:DWORD
	v_mul_f32_e32 v186, v64, v228
	v_mul_f32_e32 v187, v65, v229
	v_rndne_f32_e32 v186, v186
	v_rndne_f32_e32 v187, v187
	v_cvt_i32_f32_sdwa v190, v186 dst_sel:BYTE_2 dst_unused:UNUSED_PRESERVE src0_sel:DWORD
	v_cvt_i32_f32_sdwa v196, v187 dst_sel:BYTE_2 dst_unused:UNUSED_PRESERVE src0_sel:DWORD
	v_mul_f32_e32 v186, v68, v228
	v_mul_f32_e32 v187, v69, v229
	v_rndne_f32_e32 v186, v186
	v_rndne_f32_e32 v187, v187
	v_cvt_i32_f32_sdwa v190, v186 dst_sel:BYTE_3 dst_unused:UNUSED_PRESERVE src0_sel:DWORD
	v_cvt_i32_f32_sdwa v196, v187 dst_sel:BYTE_3 dst_unused:UNUSED_PRESERVE src0_sel:DWORD
	s_nop 0
	ds_write_b32 v139, v190 offset:608
	ds_write_b32 v139, v196 offset:864
	s_cmp_ge_u32 s10, 0x140
	s_cbranch_scc1 .Lc32_mixer_nopf_3
	global_load_dwordx4 v[54:57], v138, s[56:57]
	s_add_u32 s56, s56, 0xa000
	s_addc_u32 s57, s57, 0
	global_load_dwordx4 v[58:61], v138, s[56:57]
	s_add_u32 s56, s56, 0xa000
	s_addc_u32 s57, s57, 0
	global_load_dwordx4 v[62:65], v138, s[56:57]
	s_add_u32 s56, s56, 0xa000
	s_addc_u32 s57, s57, 0
	global_load_dwordx4 v[66:69], v138, s[56:57]
	s_add_u32 s56, s56, 0x122000
	s_addc_u32 s57, s57, 0
.Lc32_mixer_nopf_3:
	s_cmp_ge_u32 s2, 0x1800
	s_cbranch_scc1 .Lc32_mixer_nobf_4
	v_cvt_pk_bf16_f32 v236, v70, v74
	v_cvt_pk_bf16_f32 v237, v78, v82
	global_store_dwordx2 v231, v[236:237], s[36:37] offset:256
	v_cvt_pk_bf16_f32 v238, v71, v75
	v_cvt_pk_bf16_f32 v239, v79, v83
	global_store_dwordx2 v231, v[238:239], s[38:39] offset:256
	v_cvt_pk_bf16_f32 v236, v72, v76
	v_cvt_pk_bf16_f32 v237, v80, v84
	global_store_dwordx2 v231, v[236:237], s[78:79] offset:256
	v_cvt_pk_bf16_f32 v238, v73, v77
	v_cvt_pk_bf16_f32 v239, v81, v85
	global_store_dwordx2 v231, v[238:239], s[80:81] offset:256
.Lc32_mixer_nobf_4:
	v_mul_f32_e32 v186, v70, v226
	v_mul_f32_e32 v187, v71, v227
	v_rndne_f32_e32 v186, v186
	v_rndne_f32_e32 v187, v187
	v_cvt_i32_f32_sdwa v190, v186 dst_sel:BYTE_0 dst_unused:UNUSED_PAD src0_sel:DWORD
	v_cvt_i32_f32_sdwa v196, v187 dst_sel:BYTE_0 dst_unused:UNUSED_PAD src0_sel:DWORD
	v_mul_f32_e32 v186, v74, v226
	v_mul_f32_e32 v187, v75, v227
	v_rndne_f32_e32 v186, v186
	v_rndne_f32_e32 v187, v187
	v_cvt_i32_f32_sdwa v190, v186 dst_sel:BYTE_1 dst_unused:UNUSED_PRESERVE src0_sel:DWORD
	v_cvt_i32_f32_sdwa v196, v187 dst_sel:BYTE_1 dst_unused:UNUSED_PRESERVE src0_sel:DWORD
	v_mul_f32_e32 v186, v78, v226
	v_mul_f32_e32 v187, v79, v227
	v_rndne_f32_e32 v186, v186
	v_rndne_f32_e32 v187, v187
	v_cvt_i32_f32_sdwa v190, v186 dst_sel:BYTE_2 dst_unused:UNUSED_PRESERVE src0_sel:DWORD
	v_cvt_i32_f32_sdwa v196, v187 dst_sel:BYTE_2 dst_unused:UNUSED_PRESERVE src0_sel:DWORD
	v_mul_f32_e32 v186, v82, v226
	v_mul_f32_e32 v187, v83, v227
	v_rndne_f32_e32 v186, v186
	v_rndne_f32_e32 v187, v187
	v_cvt_i32_f32_sdwa v190, v186 dst_sel:BYTE_3 dst_unused:UNUSED_PRESERVE src0_sel:DWORD
	v_cvt_i32_f32_sdwa v196, v187 dst_sel:BYTE_3 dst_unused:UNUSED_PRESERVE src0_sel:DWORD
	s_nop 0
	ds_write_b32 v139, v190 offset:128
	ds_write_b32 v139, v196 offset:384
	v_mul_f32_e32 v186, v72, v228
	v_mul_f32_e32 v187, v73, v229
	v_rndne_f32_e32 v186, v186
	v_rndne_f32_e32 v187, v187
	v_cvt_i32_f32_sdwa v190, v186 dst_sel:BYTE_0 dst_unused:UNUSED_PAD src0_sel:DWORD
	v_cvt_i32_f32_sdwa v196, v187 dst_sel:BYTE_0 dst_unused:UNUSED_PAD src0_sel:DWORD
	v_mul_f32_e32 v186, v76, v228
	v_mul_f32_e32 v187, v77, v229
	v_rndne_f32_e32 v186, v186
	v_rndne_f32_e32 v187, v187
	v_cvt_i32_f32_sdwa v190, v186 dst_sel:BYTE_1 dst_unused:UNUSED_PRESERVE src0_sel:DWORD
	v_cvt_i32_f32_sdwa v196, v187 dst_sel:BYTE_1 dst_unused:UNUSED_PRESERVE src0_sel:DWORD
	v_mul_f32_e32 v186, v80, v228
	v_mul_f32_e32 v187, v81, v229
	v_rndne_f32_e32 v186, v186
	v_rndne_f32_e32 v187, v187
	v_cvt_i32_f32_sdwa v190, v186 dst_sel:BYTE_2 dst_unused:UNUSED_PRESERVE src0_sel:DWORD
	v_cvt_i32_f32_sdwa v196, v187 dst_sel:BYTE_2 dst_unused:UNUSED_PRESERVE src0_sel:DWORD
	v_mul_f32_e32 v186, v84, v228
	v_mul_f32_e32 v187, v85, v229
	v_rndne_f32_e32 v186, v186
	v_rndne_f32_e32 v187, v187
	v_cvt_i32_f32_sdwa v190, v186 dst_sel:BYTE_3 dst_unused:UNUSED_PRESERVE src0_sel:DWORD
	v_cvt_i32_f32_sdwa v196, v187 dst_sel:BYTE_3 dst_unused:UNUSED_PRESERVE src0_sel:DWORD
	s_nop 0
	ds_write_b32 v139, v190 offset:640
	ds_write_b32 v139, v196 offset:896
	s_cmp_ge_u32 s10, 0x140
	s_cbranch_scc1 .Lc32_mixer_nopf_4
	global_load_dwordx4 v[70:73], v138, s[56:57]
	s_add_u32 s56, s56, 0xa000
	s_addc_u32 s57, s57, 0
	global_load_dwordx4 v[74:77], v138, s[56:57]
	s_add_u32 s56, s56, 0xa000
	s_addc_u32 s57, s57, 0
	global_load_dwordx4 v[78:81], v138, s[56:57]
	s_add_u32 s56, s56, 0xa000
	s_addc_u32 s57, s57, 0
	global_load_dwordx4 v[82:85], v138, s[56:57]
	s_add_u32 s56, s56, 0x122000
	s_addc_u32 s57, s57, 0
.Lc32_mixer_nopf_4:
	s_cmp_ge_u32 s2, 0x1800
	s_cbranch_scc1 .Lc32_mixer_nobf_5
	v_cvt_pk_bf16_f32 v236, v86, v90
	v_cvt_pk_bf16_f32 v237, v94, v98
	global_store_dwordx2 v231, v[236:237], s[36:37] offset:320
	v_cvt_pk_bf16_f32 v238, v87, v91
	v_cvt_pk_bf16_f32 v239, v95, v99
	global_store_dwordx2 v231, v[238:239], s[38:39] offset:320
	v_cvt_pk_bf16_f32 v236, v88, v92
	v_cvt_pk_bf16_f32 v237, v96, v100
	global_store_dwordx2 v231, v[236:237], s[78:79] offset:320
	v_cvt_pk_bf16_f32 v238, v89, v93
	v_cvt_pk_bf16_f32 v239, v97, v101
	global_store_dwordx2 v231, v[238:239], s[80:81] offset:320
.Lc32_mixer_nobf_5:
	v_mul_f32_e32 v186, v86, v226
	v_mul_f32_e32 v187, v87, v227
	v_rndne_f32_e32 v186, v186
	v_rndne_f32_e32 v187, v187
	v_cvt_i32_f32_sdwa v190, v186 dst_sel:BYTE_0 dst_unused:UNUSED_PAD src0_sel:DWORD
	v_cvt_i32_f32_sdwa v196, v187 dst_sel:BYTE_0 dst_unused:UNUSED_PAD src0_sel:DWORD
	v_mul_f32_e32 v186, v90, v226
	v_mul_f32_e32 v187, v91, v227
	v_rndne_f32_e32 v186, v186
	v_rndne_f32_e32 v187, v187
	v_cvt_i32_f32_sdwa v190, v186 dst_sel:BYTE_1 dst_unused:UNUSED_PRESERVE src0_sel:DWORD
	v_cvt_i32_f32_sdwa v196, v187 dst_sel:BYTE_1 dst_unused:UNUSED_PRESERVE src0_sel:DWORD
	v_mul_f32_e32 v186, v94, v226
	v_mul_f32_e32 v187, v95, v227
	v_rndne_f32_e32 v186, v186
	v_rndne_f32_e32 v187, v187
	v_cvt_i32_f32_sdwa v190, v186 dst_sel:BYTE_2 dst_unused:UNUSED_PRESERVE src0_sel:DWORD
	v_cvt_i32_f32_sdwa v196, v187 dst_sel:BYTE_2 dst_unused:UNUSED_PRESERVE src0_sel:DWORD
	v_mul_f32_e32 v186, v98, v226
	v_mul_f32_e32 v187, v99, v227
	v_rndne_f32_e32 v186, v186
	v_rndne_f32_e32 v187, v187
	v_cvt_i32_f32_sdwa v190, v186 dst_sel:BYTE_3 dst_unused:UNUSED_PRESERVE src0_sel:DWORD
	v_cvt_i32_f32_sdwa v196, v187 dst_sel:BYTE_3 dst_unused:UNUSED_PRESERVE src0_sel:DWORD
	s_nop 0
	ds_write_b32 v139, v190 offset:160
	ds_write_b32 v139, v196 offset:416
	v_mul_f32_e32 v186, v88, v228
	v_mul_f32_e32 v187, v89, v229
	v_rndne_f32_e32 v186, v186
	v_rndne_f32_e32 v187, v187
	v_cvt_i32_f32_sdwa v190, v186 dst_sel:BYTE_0 dst_unused:UNUSED_PAD src0_sel:DWORD
	v_cvt_i32_f32_sdwa v196, v187 dst_sel:BYTE_0 dst_unused:UNUSED_PAD src0_sel:DWORD
	v_mul_f32_e32 v186, v92, v228
	v_mul_f32_e32 v187, v93, v229
	v_rndne_f32_e32 v186, v186
	v_rndne_f32_e32 v187, v187
	v_cvt_i32_f32_sdwa v190, v186 dst_sel:BYTE_1 dst_unused:UNUSED_PRESERVE src0_sel:DWORD
	v_cvt_i32_f32_sdwa v196, v187 dst_sel:BYTE_1 dst_unused:UNUSED_PRESERVE src0_sel:DWORD
	v_mul_f32_e32 v186, v96, v228
	v_mul_f32_e32 v187, v97, v229
	v_rndne_f32_e32 v186, v186
	v_rndne_f32_e32 v187, v187
	v_cvt_i32_f32_sdwa v190, v186 dst_sel:BYTE_2 dst_unused:UNUSED_PRESERVE src0_sel:DWORD
	v_cvt_i32_f32_sdwa v196, v187 dst_sel:BYTE_2 dst_unused:UNUSED_PRESERVE src0_sel:DWORD
	v_mul_f32_e32 v186, v100, v228
	v_mul_f32_e32 v187, v101, v229
	v_rndne_f32_e32 v186, v186
	v_rndne_f32_e32 v187, v187
	v_cvt_i32_f32_sdwa v190, v186 dst_sel:BYTE_3 dst_unused:UNUSED_PRESERVE src0_sel:DWORD
	v_cvt_i32_f32_sdwa v196, v187 dst_sel:BYTE_3 dst_unused:UNUSED_PRESERVE src0_sel:DWORD
	s_nop 0
	ds_write_b32 v139, v190 offset:672
	ds_write_b32 v139, v196 offset:928
	s_cmp_ge_u32 s10, 0x140
	s_cbranch_scc1 .Lc32_mixer_nopf_5
	global_load_dwordx4 v[86:89], v138, s[56:57]
	s_add_u32 s56, s56, 0xa000
	s_addc_u32 s57, s57, 0
	global_load_dwordx4 v[90:93], v138, s[56:57]
	s_add_u32 s56, s56, 0xa000
	s_addc_u32 s57, s57, 0
	global_load_dwordx4 v[94:97], v138, s[56:57]
	s_add_u32 s56, s56, 0xa000
	s_addc_u32 s57, s57, 0
	global_load_dwordx4 v[98:101], v138, s[56:57]
	s_add_u32 s56, s56, 0x122000
	s_addc_u32 s57, s57, 0
.Lc32_mixer_nopf_5:
	s_cmp_ge_u32 s2, 0x1800
	s_cbranch_scc1 .Lc32_mixer_nobf_6
	v_cvt_pk_bf16_f32 v236, v102, v106
	v_cvt_pk_bf16_f32 v237, v110, v114
	global_store_dwordx2 v231, v[236:237], s[36:37] offset:384
	v_cvt_pk_bf16_f32 v238, v103, v107
	v_cvt_pk_bf16_f32 v239, v111, v115
	global_store_dwordx2 v231, v[238:239], s[38:39] offset:384
	v_cvt_pk_bf16_f32 v236, v104, v108
	v_cvt_pk_bf16_f32 v237, v112, v116
	global_store_dwordx2 v231, v[236:237], s[78:79] offset:384
	v_cvt_pk_bf16_f32 v238, v105, v109
	v_cvt_pk_bf16_f32 v239, v113, v117
	global_store_dwordx2 v231, v[238:239], s[80:81] offset:384
.Lc32_mixer_nobf_6:
	v_mul_f32_e32 v186, v102, v226
	v_mul_f32_e32 v187, v103, v227
	v_rndne_f32_e32 v186, v186
	v_rndne_f32_e32 v187, v187
	v_cvt_i32_f32_sdwa v190, v186 dst_sel:BYTE_0 dst_unused:UNUSED_PAD src0_sel:DWORD
	v_cvt_i32_f32_sdwa v196, v187 dst_sel:BYTE_0 dst_unused:UNUSED_PAD src0_sel:DWORD
	v_mul_f32_e32 v186, v106, v226
	v_mul_f32_e32 v187, v107, v227
	v_rndne_f32_e32 v186, v186
	v_rndne_f32_e32 v187, v187
	v_cvt_i32_f32_sdwa v190, v186 dst_sel:BYTE_1 dst_unused:UNUSED_PRESERVE src0_sel:DWORD
	v_cvt_i32_f32_sdwa v196, v187 dst_sel:BYTE_1 dst_unused:UNUSED_PRESERVE src0_sel:DWORD
	v_mul_f32_e32 v186, v110, v226
	v_mul_f32_e32 v187, v111, v227
	v_rndne_f32_e32 v186, v186
	v_rndne_f32_e32 v187, v187
	v_cvt_i32_f32_sdwa v190, v186 dst_sel:BYTE_2 dst_unused:UNUSED_PRESERVE src0_sel:DWORD
	v_cvt_i32_f32_sdwa v196, v187 dst_sel:BYTE_2 dst_unused:UNUSED_PRESERVE src0_sel:DWORD
	v_mul_f32_e32 v186, v114, v226
	v_mul_f32_e32 v187, v115, v227
	v_rndne_f32_e32 v186, v186
	v_rndne_f32_e32 v187, v187
	v_cvt_i32_f32_sdwa v190, v186 dst_sel:BYTE_3 dst_unused:UNUSED_PRESERVE src0_sel:DWORD
	v_cvt_i32_f32_sdwa v196, v187 dst_sel:BYTE_3 dst_unused:UNUSED_PRESERVE src0_sel:DWORD
	s_nop 0
	ds_write_b32 v139, v190 offset:192
	ds_write_b32 v139, v196 offset:448
	v_mul_f32_e32 v186, v104, v228
	v_mul_f32_e32 v187, v105, v229
	v_rndne_f32_e32 v186, v186
	v_rndne_f32_e32 v187, v187
	v_cvt_i32_f32_sdwa v190, v186 dst_sel:BYTE_0 dst_unused:UNUSED_PAD src0_sel:DWORD
	v_cvt_i32_f32_sdwa v196, v187 dst_sel:BYTE_0 dst_unused:UNUSED_PAD src0_sel:DWORD
	v_mul_f32_e32 v186, v108, v228
	v_mul_f32_e32 v187, v109, v229
	v_rndne_f32_e32 v186, v186
	v_rndne_f32_e32 v187, v187
	v_cvt_i32_f32_sdwa v190, v186 dst_sel:BYTE_1 dst_unused:UNUSED_PRESERVE src0_sel:DWORD
	v_cvt_i32_f32_sdwa v196, v187 dst_sel:BYTE_1 dst_unused:UNUSED_PRESERVE src0_sel:DWORD
	v_mul_f32_e32 v186, v112, v228
	v_mul_f32_e32 v187, v113, v229
	v_rndne_f32_e32 v186, v186
	v_rndne_f32_e32 v187, v187
	v_cvt_i32_f32_sdwa v190, v186 dst_sel:BYTE_2 dst_unused:UNUSED_PRESERVE src0_sel:DWORD
	v_cvt_i32_f32_sdwa v196, v187 dst_sel:BYTE_2 dst_unused:UNUSED_PRESERVE src0_sel:DWORD
	v_mul_f32_e32 v186, v116, v228
	v_mul_f32_e32 v187, v117, v229
	v_rndne_f32_e32 v186, v186
	v_rndne_f32_e32 v187, v187
	v_cvt_i32_f32_sdwa v190, v186 dst_sel:BYTE_3 dst_unused:UNUSED_PRESERVE src0_sel:DWORD
	v_cvt_i32_f32_sdwa v196, v187 dst_sel:BYTE_3 dst_unused:UNUSED_PRESERVE src0_sel:DWORD
	s_nop 0
	ds_write_b32 v139, v190 offset:704
	ds_write_b32 v139, v196 offset:960
	s_cmp_ge_u32 s10, 0x140
	s_cbranch_scc1 .Lc32_mixer_nopf_6
	global_load_dwordx4 v[102:105], v138, s[56:57]
	s_add_u32 s56, s56, 0xa000
	s_addc_u32 s57, s57, 0
	global_load_dwordx4 v[106:109], v138, s[56:57]
	s_add_u32 s56, s56, 0xa000
	s_addc_u32 s57, s57, 0
	global_load_dwordx4 v[110:113], v138, s[56:57]
	s_add_u32 s56, s56, 0xa000
	s_addc_u32 s57, s57, 0
	global_load_dwordx4 v[114:117], v138, s[56:57]
	s_add_u32 s56, s56, 0x122000
	s_addc_u32 s57, s57, 0
.Lc32_mixer_nopf_6:
	s_cmp_ge_u32 s2, 0x1800
	s_cbranch_scc1 .Lc32_mixer_nobf_7
	v_cvt_pk_bf16_f32 v236, v118, v122
	v_cvt_pk_bf16_f32 v237, v126, v130
	global_store_dwordx2 v231, v[236:237], s[36:37] offset:448
	v_cvt_pk_bf16_f32 v238, v119, v123
	v_cvt_pk_bf16_f32 v239, v127, v131
	global_store_dwordx2 v231, v[238:239], s[38:39] offset:448
	v_cvt_pk_bf16_f32 v236, v120, v124
	v_cvt_pk_bf16_f32 v237, v128, v132
	global_store_dwordx2 v231, v[236:237], s[78:79] offset:448
	v_cvt_pk_bf16_f32 v238, v121, v125
	v_cvt_pk_bf16_f32 v239, v129, v133
	global_store_dwordx2 v231, v[238:239], s[80:81] offset:448
.Lc32_mixer_nobf_7:
	v_mul_f32_e32 v186, v118, v226
	v_mul_f32_e32 v187, v119, v227
	v_rndne_f32_e32 v186, v186
	v_rndne_f32_e32 v187, v187
	v_cvt_i32_f32_sdwa v190, v186 dst_sel:BYTE_0 dst_unused:UNUSED_PAD src0_sel:DWORD
	v_cvt_i32_f32_sdwa v196, v187 dst_sel:BYTE_0 dst_unused:UNUSED_PAD src0_sel:DWORD
	v_mul_f32_e32 v186, v122, v226
	v_mul_f32_e32 v187, v123, v227
	v_rndne_f32_e32 v186, v186
	v_rndne_f32_e32 v187, v187
	v_cvt_i32_f32_sdwa v190, v186 dst_sel:BYTE_1 dst_unused:UNUSED_PRESERVE src0_sel:DWORD
	v_cvt_i32_f32_sdwa v196, v187 dst_sel:BYTE_1 dst_unused:UNUSED_PRESERVE src0_sel:DWORD
	v_mul_f32_e32 v186, v126, v226
	v_mul_f32_e32 v187, v127, v227
	v_rndne_f32_e32 v186, v186
	v_rndne_f32_e32 v187, v187
	v_cvt_i32_f32_sdwa v190, v186 dst_sel:BYTE_2 dst_unused:UNUSED_PRESERVE src0_sel:DWORD
	v_cvt_i32_f32_sdwa v196, v187 dst_sel:BYTE_2 dst_unused:UNUSED_PRESERVE src0_sel:DWORD
	v_mul_f32_e32 v186, v130, v226
	v_mul_f32_e32 v187, v131, v227
	v_rndne_f32_e32 v186, v186
	v_rndne_f32_e32 v187, v187
	v_cvt_i32_f32_sdwa v190, v186 dst_sel:BYTE_3 dst_unused:UNUSED_PRESERVE src0_sel:DWORD
	v_cvt_i32_f32_sdwa v196, v187 dst_sel:BYTE_3 dst_unused:UNUSED_PRESERVE src0_sel:DWORD
	s_nop 0
	ds_write_b32 v139, v190 offset:224
	ds_write_b32 v139, v196 offset:480
	v_mul_f32_e32 v186, v120, v228
	v_mul_f32_e32 v187, v121, v229
	v_rndne_f32_e32 v186, v186
	v_rndne_f32_e32 v187, v187
	v_cvt_i32_f32_sdwa v190, v186 dst_sel:BYTE_0 dst_unused:UNUSED_PAD src0_sel:DWORD
	v_cvt_i32_f32_sdwa v196, v187 dst_sel:BYTE_0 dst_unused:UNUSED_PAD src0_sel:DWORD
	v_mul_f32_e32 v186, v124, v228
	v_mul_f32_e32 v187, v125, v229
	v_rndne_f32_e32 v186, v186
	v_rndne_f32_e32 v187, v187
	v_cvt_i32_f32_sdwa v190, v186 dst_sel:BYTE_1 dst_unused:UNUSED_PRESERVE src0_sel:DWORD
	v_cvt_i32_f32_sdwa v196, v187 dst_sel:BYTE_1 dst_unused:UNUSED_PRESERVE src0_sel:DWORD
	v_mul_f32_e32 v186, v128, v228
	v_mul_f32_e32 v187, v129, v229
	v_rndne_f32_e32 v186, v186
	v_rndne_f32_e32 v187, v187
	v_cvt_i32_f32_sdwa v190, v186 dst_sel:BYTE_2 dst_unused:UNUSED_PRESERVE src0_sel:DWORD
	v_cvt_i32_f32_sdwa v196, v187 dst_sel:BYTE_2 dst_unused:UNUSED_PRESERVE src0_sel:DWORD
	v_mul_f32_e32 v186, v132, v228
	v_mul_f32_e32 v187, v133, v229
	v_rndne_f32_e32 v186, v186
	v_rndne_f32_e32 v187, v187
	v_cvt_i32_f32_sdwa v190, v186 dst_sel:BYTE_3 dst_unused:UNUSED_PRESERVE src0_sel:DWORD
	v_cvt_i32_f32_sdwa v196, v187 dst_sel:BYTE_3 dst_unused:UNUSED_PRESERVE src0_sel:DWORD
	s_nop 0
	ds_write_b32 v139, v190 offset:736
	ds_write_b32 v139, v196 offset:992
	s_cmp_ge_u32 s10, 0x140
	s_cbranch_scc1 .Lc32_mixer_nopf_7
	global_load_dwordx4 v[118:121], v138, s[56:57]
	s_add_u32 s56, s56, 0xa000
	s_addc_u32 s57, s57, 0
	global_load_dwordx4 v[122:125], v138, s[56:57]
	s_add_u32 s56, s56, 0xa000
	s_addc_u32 s57, s57, 0
	global_load_dwordx4 v[126:129], v138, s[56:57]
	s_add_u32 s56, s56, 0xa000
	s_addc_u32 s57, s57, 0
	global_load_dwordx4 v[130:133], v138, s[56:57]
.Lc32_mixer_nopf_7:
	s_waitcnt lgkmcnt(0)
	s_lshl_b32 s3, s60, 12
	s_add_u32 s3, s3, s52
	s_add_u32 s58, s34, s3
	s_addc_u32 s59, s35, 0
	s_add_u32 s58, s58, 0x100000
	s_addc_u32 s59, s59, 0
	ds_read_b128 v[204:207], v212 offset:0
	s_waitcnt lgkmcnt(0)
	global_store_dwordx4 v213, v[204:207], s[58:59]
	s_add_u32 s58, s58, 0x4000
	s_addc_u32 s59, s59, 0
	ds_read_b128 v[208:211], v212 offset:1024
	s_waitcnt lgkmcnt(0)
	global_store_dwordx4 v213, v[208:211], s[58:59]
	s_add_u32 s58, s58, 0x4000
	s_addc_u32 s59, s59, 0
	ds_read_b128 v[204:207], v212 offset:2048
	s_waitcnt lgkmcnt(0)
	global_store_dwordx4 v213, v[204:207], s[58:59]
	s_add_u32 s58, s58, 0x4000
	s_addc_u32 s59, s59, 0
	ds_read_b128 v[208:211], v212 offset:3072
	s_waitcnt lgkmcnt(0)
	global_store_dwordx4 v213, v[208:211], s[58:59]
	s_add_u32 s58, s58, 0x4000
	s_addc_u32 s59, s59, 0
	ds_read_b128 v[204:207], v212 offset:4096
	s_waitcnt lgkmcnt(0)
	global_store_dwordx4 v213, v[204:207], s[58:59]
	s_add_u32 s58, s58, 0x4000
	s_addc_u32 s59, s59, 0
	ds_read_b128 v[208:211], v212 offset:5120
	s_waitcnt lgkmcnt(0)
	global_store_dwordx4 v213, v[208:211], s[58:59]
	s_add_u32 s58, s58, 0x4000
	s_addc_u32 s59, s59, 0
	ds_read_b128 v[204:207], v212 offset:6144
	s_waitcnt lgkmcnt(0)
	global_store_dwordx4 v213, v[204:207], s[58:59]
	s_add_u32 s58, s58, 0x4000
	s_addc_u32 s59, s59, 0
	ds_read_b128 v[208:211], v212 offset:7168
	s_waitcnt lgkmcnt(0)
	global_store_dwordx4 v213, v[208:211], s[58:59]
	s_xor_b32 s11, s11, 1
	s_add_u32 s0, s0, 128
	s_cmp_lt_u32 s0, 0x140
	s_cbranch_scc1 .Lc32_mixer_loop

.LBB0_484:
	v_mbcnt_lo_u32_b32 v135, -1, 0
	v_mbcnt_hi_u32_b32 v135, -1, v135
	v_lshrrev_b32_e32 v136, 3, v135
	v_and_b32_e32 v137, 7, v135
	v_lshlrev_b32_e32 v230, 4, v137
	v_lshlrev_b32_e32 v195, 5, v137
	v_lshlrev_b32_e32 v231, 15, v137
	v_lshl_add_u32 v231, v136, 3, v231
	v_readlane_b32 s7, v254, 17
	v_readlane_b32 s1, v254, 16
	v_readlane_b32 s13, v254, 15
	s_mov_b32 s11, 0x42fe0000
	s_mov_b32 s5, 0
	s_and_b32 s60, s13, 1
	s_lshr_b32 s13, s13, 1
	s_mov_b32 s61, 64
	s_lshl_b32 s64, s60, 11
	s_lshl_b32 s3, s1, 8
	s_add_u32 s64, s64, s3
	s_lshl_b32 s3, s13, 10
	s_add_u32 s62, s34, s3
	s_addc_u32 s63, s35, 0
	s_add_u32 s62, s62, 0x10000
	s_addc_u32 s63, s63, 0
	v_lshlrev_b32_e32 v139, 10, v137
	v_lshl_add_u32 v139, v136, 2, v139
	v_add_u32_e32 v139, s7, v139
	v_lshlrev_b32_e32 v174, 2, v135
	v_xor_b32_e32 v192, 0x20, v174
	v_xor_b32_e32 v193, 0x40, v174
	v_xor_b32_e32 v194, 0x80, v174
	v_lshrrev_b32_e32 v175, 4, v135
	v_and_b32_e32 v176, 15, v135
	v_lshlrev_b32_e32 v212, 8, v175
	v_lshl_add_u32 v212, v176, 4, v212
	v_add_u32_e32 v212, s7, v212
	v_lshlrev_b32_e32 v213, 12, v175
	v_lshl_add_u32 v213, v176, 4, v213
	v_readlane_b32 s52, v255, 61
	v_readlane_b32 s53, v255, 62
	v_mul_u32_u24_e32 v138, 0x56000, v136
	v_lshl_add_u32 v138, v137, 4, v138
	s_mul_i32 s3, s64, 0x15800
	s_nop 1
	s_add_u32 s52, s52, s3
	s_addc_u32 s53, s53, 0
	s_mov_b32 s0, s13
	s_cmp_ge_u32 s0, 0x2b0
	s_cbranch_scc1 .Lc32p3_ffn2_done
	s_lshl_b32 s3, s0, 7
	s_add_u32 s54, s52, s3
	s_addc_u32 s55, s53, 0
	global_load_dwordx4 v[6:9], v138, s[54:55]
	s_add_u32 s54, s54, 0x15800
	s_addc_u32 s55, s55, 0
	global_load_dwordx4 v[10:13], v138, s[54:55]
	s_add_u32 s54, s54, 0x15800
	s_addc_u32 s55, s55, 0
	global_load_dwordx4 v[14:17], v138, s[54:55]
	s_add_u32 s54, s54, 0x15800
	s_addc_u32 s55, s55, 0
	global_load_dwordx4 v[18:21], v138, s[54:55]
	s_add_u32 s54, s54, 0x26f800
	s_addc_u32 s55, s55, 0
	global_load_dwordx4 v[22:25], v138, s[54:55]
	s_add_u32 s54, s54, 0x15800
	s_addc_u32 s55, s55, 0
	global_load_dwordx4 v[26:29], v138, s[54:55]
	s_add_u32 s54, s54, 0x15800
	s_addc_u32 s55, s55, 0
	global_load_dwordx4 v[30:33], v138, s[54:55]
	s_add_u32 s54, s54, 0x15800
	s_addc_u32 s55, s55, 0
	global_load_dwordx4 v[34:37], v138, s[54:55]
	s_add_u32 s54, s54, 0x26f800
	s_addc_u32 s55, s55, 0
	global_load_dwordx4 v[38:41], v138, s[54:55]
	s_add_u32 s54, s54, 0x15800
	s_addc_u32 s55, s55, 0
	global_load_dwordx4 v[42:45], v138, s[54:55]
	s_add_u32 s54, s54, 0x15800
	s_addc_u32 s55, s55, 0
	global_load_dwordx4 v[46:49], v138, s[54:55]
	s_add_u32 s54, s54, 0x15800
	s_addc_u32 s55, s55, 0
	global_load_dwordx4 v[50:53], v138, s[54:55]
	s_add_u32 s54, s54, 0x26f800
	s_addc_u32 s55, s55, 0
	global_load_dwordx4 v[54:57], v138, s[54:55]
	s_add_u32 s54, s54, 0x15800
	s_addc_u32 s55, s55, 0
	global_load_dwordx4 v[58:61], v138, s[54:55]
	s_add_u32 s54, s54, 0x15800
	s_addc_u32 s55, s55, 0
	global_load_dwordx4 v[62:65], v138, s[54:55]
	s_add_u32 s54, s54, 0x15800
	s_addc_u32 s55, s55, 0
	global_load_dwordx4 v[66:69], v138, s[54:55]
	s_add_u32 s54, s54, 0x26f800
	s_addc_u32 s55, s55, 0
	global_load_dwordx4 v[70:73], v138, s[54:55]
	s_add_u32 s54, s54, 0x15800
	s_addc_u32 s55, s55, 0
	global_load_dwordx4 v[74:77], v138, s[54:55]
	s_add_u32 s54, s54, 0x15800
	s_addc_u32 s55, s55, 0
	global_load_dwordx4 v[78:81], v138, s[54:55]
	s_add_u32 s54, s54, 0x15800
	s_addc_u32 s55, s55, 0
	global_load_dwordx4 v[82:85], v138, s[54:55]
	s_add_u32 s54, s54, 0x26f800
	s_addc_u32 s55, s55, 0
	global_load_dwordx4 v[86:89], v138, s[54:55]
	s_add_u32 s54, s54, 0x15800
	s_addc_u32 s55, s55, 0
	global_load_dwordx4 v[90:93], v138, s[54:55]
	s_add_u32 s54, s54, 0x15800
	s_addc_u32 s55, s55, 0
	global_load_dwordx4 v[94:97], v138, s[54:55]
	s_add_u32 s54, s54, 0x15800
	s_addc_u32 s55, s55, 0
	global_load_dwordx4 v[98:101], v138, s[54:55]
	s_add_u32 s54, s54, 0x26f800
	s_addc_u32 s55, s55, 0
	global_load_dwordx4 v[102:105], v138, s[54:55]
	s_add_u32 s54, s54, 0x15800
	s_addc_u32 s55, s55, 0
	global_load_dwordx4 v[106:109], v138, s[54:55]
	s_add_u32 s54, s54, 0x15800
	s_addc_u32 s55, s55, 0
	global_load_dwordx4 v[110:113], v138, s[54:55]
	s_add_u32 s54, s54, 0x15800
	s_addc_u32 s55, s55, 0
	global_load_dwordx4 v[114:117], v138, s[54:55]
	s_add_u32 s54, s54, 0x26f800
	s_addc_u32 s55, s55, 0
	global_load_dwordx4 v[118:121], v138, s[54:55]
	s_add_u32 s54, s54, 0x15800
	s_addc_u32 s55, s55, 0
	global_load_dwordx4 v[122:125], v138, s[54:55]
	s_add_u32 s54, s54, 0x15800
	s_addc_u32 s55, s55, 0
	global_load_dwordx4 v[126:129], v138, s[54:55]
	s_add_u32 s54, s54, 0x15800
	s_addc_u32 s55, s55, 0
	global_load_dwordx4 v[130:133], v138, s[54:55]
.Lc32p3_ffn2_loop:
	s_lshl_b32 s2, s0, 5
	s_add_u32 s61, s61, 1
	s_cmp_ge_u32 s2, 0x2b00
	s_cselect_b32 s12, 128, 0
	s_cselect_b32 s3, 0x2b00, 0
	s_sub_u32 s3, s2, s3
	s_lshr_b32 s6, s3, 7
	s_lshl_b32 s6, s6, 8
	s_and_b32 s3, s3, 127
	s_add_u32 s6, s6, s3
	s_add_u32 s6, s6, s12
	s_lshl_b32 s10, s5, 10
	s_add_u32 s10, s10, 0x21000
	s_lshl_b32 s3, s1, 7
	s_add_u32 s3, s3, s10
	v_add_u32_e32 v172, s3, v230
	v_add_u32_e32 v173, s10, v230
	s_waitcnt vmcnt(0)
	v_max3_f32 v216, |v6|, |v10|, |v14|
	v_max3_f32 v216, v216, |v18|, |v22|
	v_max3_f32 v216, v216, |v26|, |v30|
	v_max3_f32 v216, v216, |v34|, |v38|
	v_max3_f32 v216, v216, |v42|, |v46|
	v_max3_f32 v216, v216, |v50|, |v54|
	v_max3_f32 v216, v216, |v58|, |v62|
	v_max3_f32 v216, v216, |v66|, |v70|
	v_max3_f32 v216, v216, |v74|, |v78|
	v_max3_f32 v216, v216, |v82|, |v86|
	v_max3_f32 v216, v216, |v90|, |v94|
	v_max3_f32 v216, v216, |v98|, |v102|
	v_max3_f32 v216, v216, |v106|, |v110|
	v_max3_f32 v216, v216, |v114|, |v118|
	v_max3_f32 v216, v216, |v122|, |v126|
	v_max_f32_e64 v216, v216, |v130|
	v_max3_f32 v217, |v7|, |v11|, |v15|
	v_max3_f32 v217, v217, |v19|, |v23|
	v_max3_f32 v217, v217, |v27|, |v31|
	v_max3_f32 v217, v217, |v35|, |v39|
	v_max3_f32 v217, v217, |v43|, |v47|
	v_max3_f32 v217, v217, |v51|, |v55|
	v_max3_f32 v217, v217, |v59|, |v63|
	v_max3_f32 v217, v217, |v67|, |v71|
	v_max3_f32 v217, v217, |v75|, |v79|
	v_max3_f32 v217, v217, |v83|, |v87|
	v_max3_f32 v217, v217, |v91|, |v95|
	v_max3_f32 v217, v217, |v99|, |v103|
	v_max3_f32 v217, v217, |v107|, |v111|
	v_max3_f32 v217, v217, |v115|, |v119|
	v_max3_f32 v217, v217, |v123|, |v127|
	v_max_f32_e64 v217, v217, |v131|
	v_max3_f32 v218, |v8|, |v12|, |v16|
	v_max3_f32 v218, v218, |v20|, |v24|
	v_max3_f32 v218, v218, |v28|, |v32|
	v_max3_f32 v218, v218, |v36|, |v40|
	v_max3_f32 v218, v218, |v44|, |v48|
	v_max3_f32 v218, v218, |v52|, |v56|
	v_max3_f32 v218, v218, |v60|, |v64|
	v_max3_f32 v218, v218, |v68|, |v72|
	v_max3_f32 v218, v218, |v76|, |v80|
	v_max3_f32 v218, v218, |v84|, |v88|
	v_max3_f32 v218, v218, |v92|, |v96|
	v_max3_f32 v218, v218, |v100|, |v104|
	v_max3_f32 v218, v218, |v108|, |v112|
	v_max3_f32 v218, v218, |v116|, |v120|
	v_max3_f32 v218, v218, |v124|, |v128|
	v_max_f32_e64 v218, v218, |v132|
	v_max3_f32 v219, |v9|, |v13|, |v17|
	v_max3_f32 v219, v219, |v21|, |v25|
	v_max3_f32 v219, v219, |v29|, |v33|
	v_max3_f32 v219, v219, |v37|, |v41|
	v_max3_f32 v219, v219, |v45|, |v49|
	v_max3_f32 v219, v219, |v53|, |v57|
	v_max3_f32 v219, v219, |v61|, |v65|
	v_max3_f32 v219, v219, |v69|, |v73|
	v_max3_f32 v219, v219, |v77|, |v81|
	v_max3_f32 v219, v219, |v85|, |v89|
	v_max3_f32 v219, v219, |v93|, |v97|
	v_max3_f32 v219, v219, |v101|, |v105|
	v_max3_f32 v219, v219, |v109|, |v113|
	v_max3_f32 v219, v219, |v117|, |v121|
	v_max3_f32 v219, v219, |v125|, |v129|
	v_max_f32_e64 v219, v219, |v133|
	ds_bpermute_b32 v174, v192, v216
	ds_bpermute_b32 v175, v192, v217
	ds_bpermute_b32 v176, v192, v218
	ds_bpermute_b32 v177, v192, v219
	s_waitcnt lgkmcnt(0)
	v_max_f32_e32 v216, v216, v174
	v_max_f32_e32 v217, v217, v175
	v_max_f32_e32 v218, v218, v176
	v_max_f32_e32 v219, v219, v177
	ds_bpermute_b32 v174, v193, v216
	ds_bpermute_b32 v175, v193, v217
	ds_bpermute_b32 v176, v193, v218
	ds_bpermute_b32 v177, v193, v219
	s_waitcnt lgkmcnt(0)
	v_max_f32_e32 v216, v216, v174
	v_max_f32_e32 v217, v217, v175
	v_max_f32_e32 v218, v218, v176
	v_max_f32_e32 v219, v219, v177
	ds_bpermute_b32 v174, v194, v216
	ds_bpermute_b32 v175, v194, v217
	ds_bpermute_b32 v176, v194, v218
	ds_bpermute_b32 v177, v194, v219
	s_waitcnt lgkmcnt(0)
	v_max_f32_e32 v216, v216, v174
	v_max_f32_e32 v217, v217, v175
	v_max_f32_e32 v218, v218, v176
	v_max_f32_e32 v219, v219, v177
	s_mov_b64 s[58:59], exec
	s_mov_b64 exec, 0xff
	ds_write_b128 v172, v[216:219]
	s_mov_b64 exec, s[58:59]
	s_waitcnt lgkmcnt(0)
	s_barrier
	ds_read_b128 v[140:143], v173 offset:0
	ds_read_b128 v[144:147], v173 offset:128
	ds_read_b128 v[148:151], v173 offset:256
	ds_read_b128 v[152:155], v173 offset:384
	ds_read_b128 v[156:159], v173 offset:512
	ds_read_b128 v[160:163], v173 offset:640
	ds_read_b128 v[164:167], v173 offset:768
	ds_read_b128 v[232:235], v173 offset:896
	s_waitcnt lgkmcnt(0)
	v_max3_f32 v220, v140, v144, v148
	v_max3_f32 v220, v220, v152, v156
	v_max3_f32 v220, v220, v160, v164
	v_max_f32_e32 v220, v220, v232
	v_max3_f32 v221, v141, v145, v149
	v_max3_f32 v221, v221, v153, v157
	v_max3_f32 v221, v221, v161, v165
	v_max_f32_e32 v221, v221, v233
	v_max3_f32 v222, v142, v146, v150
	v_max3_f32 v222, v222, v154, v158
	v_max3_f32 v222, v222, v162, v166
	v_max_f32_e32 v222, v222, v234
	v_max3_f32 v223, v143, v147, v151
	v_max3_f32 v223, v223, v155, v159
	v_max3_f32 v223, v223, v163, v167
	v_max_f32_e32 v223, v223, v235
	s_lshl_b32 s3, s5, 9
	s_lshl_b32 s4, s60, 8
	s_add_u32 s4, s4, s3
	s_add_u32 s66, s62, s4
	s_addc_u32 s67, s63, 0
	s_mov_b64 s[58:59], exec
	s_mov_b64 exec, 0xff
	s_cmp_lg_u32 s1, 0
	s_cbranch_scc1 .Lc32p3_ffn2_nopub
	v_mov_b32_e32 v249, s61
	v_mov_b32_e32 v248, v220
	global_store_dwordx2 v195, v[248:249], s[66:67] offset:0 sc0 sc1
	s_nop 1
	v_mov_b32_e32 v248, v221
	global_store_dwordx2 v195, v[248:249], s[66:67] offset:8 sc0 sc1
	s_nop 1
	v_mov_b32_e32 v248, v222
	global_store_dwordx2 v195, v[248:249], s[66:67] offset:16 sc0 sc1
	s_nop 1
	v_mov_b32_e32 v248, v223
	global_store_dwordx2 v195, v[248:249], s[66:67] offset:24 sc0 sc1
	s_nop 1
.Lc32p3_ffn2_nopub:
	s_xor_b32 s4, s4, 0x100
	s_add_u32 s66, s62, s4
	s_addc_u32 s67, s63, 0
	s_movk_i32 s65, 0x1000
.Lc32p3_ffn2_poll:
	global_load_dwordx2 v[240:241], v195, s[66:67] offset:0 sc0 sc1
	global_load_dwordx2 v[242:243], v195, s[66:67] offset:8 sc0 sc1
	global_load_dwordx2 v[244:245], v195, s[66:67] offset:16 sc0 sc1
	global_load_dwordx2 v[246:247], v195, s[66:67] offset:24 sc0 sc1
	s_waitcnt vmcnt(0)
	v_cmp_ne_u32_e32 vcc, s61, v241
	v_cmp_ne_u32_e64 s[54:55], s61, v243
	s_nop 1
	s_or_b64 vcc, vcc, s[54:55]
	v_cmp_ne_u32_e64 s[54:55], s61, v245
	s_nop 1
	s_or_b64 vcc, vcc, s[54:55]
	v_cmp_ne_u32_e64 s[54:55], s61, v247
	s_nop 1
	s_or_b64 vcc, vcc, s[54:55]
	s_nop 1
	s_and_b64 vcc, vcc, exec
	s_cbranch_vccz .Lc32p3_ffn2_got
	s_sleep 1
	s_sub_u32 s65, s65, 1
	s_cmp_lg_u32 s65, 0
	s_cbranch_scc1 .Lc32p3_ffn2_poll
.Lc32p3_ffn2_got:
	v_max_f32_e32 v220, v220, v240
	v_max_f32_e32 v221, v221, v242
	v_max_f32_e32 v222, v222, v244
	v_max_f32_e32 v223, v223, v246
	s_mov_b64 exec, s[58:59]
	v_lshlrev_b32_e32 v174, 2, v137
	ds_bpermute_b32 v175, v174, v220
	ds_bpermute_b32 v176, v174, v221
	ds_bpermute_b32 v177, v174, v222
	ds_bpermute_b32 v178, v174, v223
	s_waitcnt lgkmcnt(0)
	v_mov_b32_e32 v220, v175
	v_mov_b32_e32 v221, v176
	v_mov_b32_e32 v222, v177
	v_mov_b32_e32 v223, v178
	s_or_b32 s3, s1, s60
	s_cmp_lg_u32 s3, 0
	s_cbranch_scc1 .Lc32p3_ffn2_nocm
	s_lshl_b32 s3, s2, 2
	s_add_u32 s54, s34, s3
	s_addc_u32 s55, s35, 0
	s_add_u32 s54, s54, 0x60000
	s_addc_u32 s55, s55, 0
	s_mov_b64 s[58:59], exec
	s_mov_b64 exec, 0xff
	global_store_dwordx4 v230, v[220:223], s[54:55]
	s_mov_b64 exec, s[58:59]
.Lc32p3_ffn2_nocm:
	v_div_scale_f32 v175, s[58:59], v220, v220, s11
	v_rcp_f32_e32 v176, v175
	s_nop 0
	v_fma_f32 v177, -v175, v176, 1.0
	v_fmac_f32_e32 v176, v177, v176
	v_div_scale_f32 v177, vcc, s11, v220, s11
	v_mul_f32_e32 v178, v177, v176
	v_fma_f32 v180, -v175, v178, v177
	v_fmac_f32_e32 v178, v180, v176
	v_fma_f32 v175, -v175, v178, v177
	s_nop 0
	v_div_fmas_f32 v175, v175, v176, v178
	v_div_fixup_f32 v175, v175, v220, s11
	v_cmp_lt_f32_e32 vcc, 0, v220
	s_nop 1
	v_cndmask_b32_e32 v226, 0, v175, vcc
	v_div_scale_f32 v175, s[58:59], v221, v221, s11
	v_rcp_f32_e32 v176, v175
	s_nop 0
	v_fma_f32 v177, -v175, v176, 1.0
	v_fmac_f32_e32 v176, v177, v176
	v_div_scale_f32 v177, vcc, s11, v221, s11
	v_mul_f32_e32 v178, v177, v176
	v_fma_f32 v180, -v175, v178, v177
	v_fmac_f32_e32 v178, v180, v176
	v_fma_f32 v175, -v175, v178, v177
	s_nop 0
	v_div_fmas_f32 v175, v175, v176, v178
	v_div_fixup_f32 v175, v175, v221, s11
	v_cmp_lt_f32_e32 vcc, 0, v221
	s_nop 1
	v_cndmask_b32_e32 v227, 0, v175, vcc
	v_div_scale_f32 v175, s[58:59], v222, v222, s11
	v_rcp_f32_e32 v176, v175
	s_nop 0
	v_fma_f32 v177, -v175, v176, 1.0
	v_fmac_f32_e32 v176, v177, v176
	v_div_scale_f32 v177, vcc, s11, v222, s11
	v_mul_f32_e32 v178, v177, v176
	v_fma_f32 v180, -v175, v178, v177
	v_fmac_f32_e32 v178, v180, v176
	v_fma_f32 v175, -v175, v178, v177
	s_nop 0
	v_div_fmas_f32 v175, v175, v176, v178
	v_div_fixup_f32 v175, v175, v222, s11
	v_cmp_lt_f32_e32 vcc, 0, v222
	s_nop 1
	v_cndmask_b32_e32 v228, 0, v175, vcc
	v_div_scale_f32 v175, s[58:59], v223, v223, s11
	v_rcp_f32_e32 v176, v175
	s_nop 0
	v_fma_f32 v177, -v175, v176, 1.0
	v_fmac_f32_e32 v176, v177, v176
	v_div_scale_f32 v177, vcc, s11, v223, s11
	v_mul_f32_e32 v178, v177, v176
	v_fma_f32 v180, -v175, v178, v177
	v_fmac_f32_e32 v178, v180, v176
	v_fma_f32 v175, -v175, v178, v177
	s_nop 0
	v_div_fmas_f32 v175, v175, v176, v178
	v_div_fixup_f32 v175, v175, v223, s11
	v_cmp_lt_f32_e32 vcc, 0, v223
	s_nop 1
	v_cndmask_b32_e32 v229, 0, v175, vcc
	s_add_u32 s4, s0, 128
	s_lshl_b32 s3, s4, 7
	s_add_u32 s54, s52, s3
	s_addc_u32 s55, s53, 0
	v_mul_f32_e32 v186, v6, v226
	v_mul_f32_e32 v187, v7, v227
	v_rndne_f32_e32 v186, v186
	v_rndne_f32_e32 v187, v187
	v_cvt_i32_f32_sdwa v190, v186 dst_sel:BYTE_0 dst_unused:UNUSED_PAD src0_sel:DWORD
	v_cvt_i32_f32_sdwa v196, v187 dst_sel:BYTE_0 dst_unused:UNUSED_PAD src0_sel:DWORD
	v_mul_f32_e32 v186, v10, v226
	v_mul_f32_e32 v187, v11, v227
	v_rndne_f32_e32 v186, v186
	v_rndne_f32_e32 v187, v187
	v_cvt_i32_f32_sdwa v190, v186 dst_sel:BYTE_1 dst_unused:UNUSED_PRESERVE src0_sel:DWORD
	v_cvt_i32_f32_sdwa v196, v187 dst_sel:BYTE_1 dst_unused:UNUSED_PRESERVE src0_sel:DWORD
	v_mul_f32_e32 v186, v14, v226
	v_mul_f32_e32 v187, v15, v227
	v_rndne_f32_e32 v186, v186
	v_rndne_f32_e32 v187, v187
	v_cvt_i32_f32_sdwa v190, v186 dst_sel:BYTE_2 dst_unused:UNUSED_PRESERVE src0_sel:DWORD
	v_cvt_i32_f32_sdwa v196, v187 dst_sel:BYTE_2 dst_unused:UNUSED_PRESERVE src0_sel:DWORD
	v_mul_f32_e32 v186, v18, v226
	v_mul_f32_e32 v187, v19, v227
	v_rndne_f32_e32 v186, v186
	v_rndne_f32_e32 v187, v187
	v_cvt_i32_f32_sdwa v190, v186 dst_sel:BYTE_3 dst_unused:UNUSED_PRESERVE src0_sel:DWORD
	v_cvt_i32_f32_sdwa v196, v187 dst_sel:BYTE_3 dst_unused:UNUSED_PRESERVE src0_sel:DWORD
	s_nop 0
	ds_write_b32 v139, v190 offset:0
	ds_write_b32 v139, v196 offset:256
	v_mul_f32_e32 v186, v8, v228
	v_mul_f32_e32 v187, v9, v229
	v_rndne_f32_e32 v186, v186
	v_rndne_f32_e32 v187, v187
	v_cvt_i32_f32_sdwa v190, v186 dst_sel:BYTE_0 dst_unused:UNUSED_PAD src0_sel:DWORD
	v_cvt_i32_f32_sdwa v196, v187 dst_sel:BYTE_0 dst_unused:UNUSED_PAD src0_sel:DWORD
	v_mul_f32_e32 v186, v12, v228
	v_mul_f32_e32 v187, v13, v229
	v_rndne_f32_e32 v186, v186
	v_rndne_f32_e32 v187, v187
	v_cvt_i32_f32_sdwa v190, v186 dst_sel:BYTE_1 dst_unused:UNUSED_PRESERVE src0_sel:DWORD
	v_cvt_i32_f32_sdwa v196, v187 dst_sel:BYTE_1 dst_unused:UNUSED_PRESERVE src0_sel:DWORD
	v_mul_f32_e32 v186, v16, v228
	v_mul_f32_e32 v187, v17, v229
	v_rndne_f32_e32 v186, v186
	v_rndne_f32_e32 v187, v187
	v_cvt_i32_f32_sdwa v190, v186 dst_sel:BYTE_2 dst_unused:UNUSED_PRESERVE src0_sel:DWORD
	v_cvt_i32_f32_sdwa v196, v187 dst_sel:BYTE_2 dst_unused:UNUSED_PRESERVE src0_sel:DWORD
	v_mul_f32_e32 v186, v20, v228
	v_mul_f32_e32 v187, v21, v229
	v_rndne_f32_e32 v186, v186
	v_rndne_f32_e32 v187, v187
	v_cvt_i32_f32_sdwa v190, v186 dst_sel:BYTE_3 dst_unused:UNUSED_PRESERVE src0_sel:DWORD
	v_cvt_i32_f32_sdwa v196, v187 dst_sel:BYTE_3 dst_unused:UNUSED_PRESERVE src0_sel:DWORD
	s_nop 0
	ds_write_b32 v139, v190 offset:512
	ds_write_b32 v139, v196 offset:768
	s_cmp_ge_u32 s4, 0x2b0
	s_cbranch_scc1 .Lc32p3_ffn2_nopf_0
	global_load_dwordx4 v[6:9], v138, s[54:55]
	s_add_u32 s54, s54, 0x15800
	s_addc_u32 s55, s55, 0
	global_load_dwordx4 v[10:13], v138, s[54:55]
	s_add_u32 s54, s54, 0x15800
	s_addc_u32 s55, s55, 0
	global_load_dwordx4 v[14:17], v138, s[54:55]
	s_add_u32 s54, s54, 0x15800
	s_addc_u32 s55, s55, 0
	global_load_dwordx4 v[18:21], v138, s[54:55]
	s_add_u32 s54, s54, 0x26f800
	s_addc_u32 s55, s55, 0
.Lc32p3_ffn2_nopf_0:
	v_mul_f32_e32 v186, v22, v226
	v_mul_f32_e32 v187, v23, v227
	v_rndne_f32_e32 v186, v186
	v_rndne_f32_e32 v187, v187
	v_cvt_i32_f32_sdwa v190, v186 dst_sel:BYTE_0 dst_unused:UNUSED_PAD src0_sel:DWORD
	v_cvt_i32_f32_sdwa v196, v187 dst_sel:BYTE_0 dst_unused:UNUSED_PAD src0_sel:DWORD
	v_mul_f32_e32 v186, v26, v226
	v_mul_f32_e32 v187, v27, v227
	v_rndne_f32_e32 v186, v186
	v_rndne_f32_e32 v187, v187
	v_cvt_i32_f32_sdwa v190, v186 dst_sel:BYTE_1 dst_unused:UNUSED_PRESERVE src0_sel:DWORD
	v_cvt_i32_f32_sdwa v196, v187 dst_sel:BYTE_1 dst_unused:UNUSED_PRESERVE src0_sel:DWORD
	v_mul_f32_e32 v186, v30, v226
	v_mul_f32_e32 v187, v31, v227
	v_rndne_f32_e32 v186, v186
	v_rndne_f32_e32 v187, v187
	v_cvt_i32_f32_sdwa v190, v186 dst_sel:BYTE_2 dst_unused:UNUSED_PRESERVE src0_sel:DWORD
	v_cvt_i32_f32_sdwa v196, v187 dst_sel:BYTE_2 dst_unused:UNUSED_PRESERVE src0_sel:DWORD
	v_mul_f32_e32 v186, v34, v226
	v_mul_f32_e32 v187, v35, v227
	v_rndne_f32_e32 v186, v186
	v_rndne_f32_e32 v187, v187
	v_cvt_i32_f32_sdwa v190, v186 dst_sel:BYTE_3 dst_unused:UNUSED_PRESERVE src0_sel:DWORD
	v_cvt_i32_f32_sdwa v196, v187 dst_sel:BYTE_3 dst_unused:UNUSED_PRESERVE src0_sel:DWORD
	s_nop 0
	ds_write_b32 v139, v190 offset:32
	ds_write_b32 v139, v196 offset:288
	v_mul_f32_e32 v186, v24, v228
	v_mul_f32_e32 v187, v25, v229
	v_rndne_f32_e32 v186, v186
	v_rndne_f32_e32 v187, v187
	v_cvt_i32_f32_sdwa v190, v186 dst_sel:BYTE_0 dst_unused:UNUSED_PAD src0_sel:DWORD
	v_cvt_i32_f32_sdwa v196, v187 dst_sel:BYTE_0 dst_unused:UNUSED_PAD src0_sel:DWORD
	v_mul_f32_e32 v186, v28, v228
	v_mul_f32_e32 v187, v29, v229
	v_rndne_f32_e32 v186, v186
	v_rndne_f32_e32 v187, v187
	v_cvt_i32_f32_sdwa v190, v186 dst_sel:BYTE_1 dst_unused:UNUSED_PRESERVE src0_sel:DWORD
	v_cvt_i32_f32_sdwa v196, v187 dst_sel:BYTE_1 dst_unused:UNUSED_PRESERVE src0_sel:DWORD
	v_mul_f32_e32 v186, v32, v228
	v_mul_f32_e32 v187, v33, v229
	v_rndne_f32_e32 v186, v186
	v_rndne_f32_e32 v187, v187
	v_cvt_i32_f32_sdwa v190, v186 dst_sel:BYTE_2 dst_unused:UNUSED_PRESERVE src0_sel:DWORD
	v_cvt_i32_f32_sdwa v196, v187 dst_sel:BYTE_2 dst_unused:UNUSED_PRESERVE src0_sel:DWORD
	v_mul_f32_e32 v186, v36, v228
	v_mul_f32_e32 v187, v37, v229
	v_rndne_f32_e32 v186, v186
	v_rndne_f32_e32 v187, v187
	v_cvt_i32_f32_sdwa v190, v186 dst_sel:BYTE_3 dst_unused:UNUSED_PRESERVE src0_sel:DWORD
	v_cvt_i32_f32_sdwa v196, v187 dst_sel:BYTE_3 dst_unused:UNUSED_PRESERVE src0_sel:DWORD
	s_nop 0
	ds_write_b32 v139, v190 offset:544
	ds_write_b32 v139, v196 offset:800
	s_cmp_ge_u32 s4, 0x2b0
	s_cbranch_scc1 .Lc32p3_ffn2_nopf_1
	global_load_dwordx4 v[22:25], v138, s[54:55]
	s_add_u32 s54, s54, 0x15800
	s_addc_u32 s55, s55, 0
	global_load_dwordx4 v[26:29], v138, s[54:55]
	s_add_u32 s54, s54, 0x15800
	s_addc_u32 s55, s55, 0
	global_load_dwordx4 v[30:33], v138, s[54:55]
	s_add_u32 s54, s54, 0x15800
	s_addc_u32 s55, s55, 0
	global_load_dwordx4 v[34:37], v138, s[54:55]
	s_add_u32 s54, s54, 0x26f800
	s_addc_u32 s55, s55, 0
.Lc32p3_ffn2_nopf_1:
	v_mul_f32_e32 v186, v38, v226
	v_mul_f32_e32 v187, v39, v227
	v_rndne_f32_e32 v186, v186
	v_rndne_f32_e32 v187, v187
	v_cvt_i32_f32_sdwa v190, v186 dst_sel:BYTE_0 dst_unused:UNUSED_PAD src0_sel:DWORD
	v_cvt_i32_f32_sdwa v196, v187 dst_sel:BYTE_0 dst_unused:UNUSED_PAD src0_sel:DWORD
	v_mul_f32_e32 v186, v42, v226
	v_mul_f32_e32 v187, v43, v227
	v_rndne_f32_e32 v186, v186
	v_rndne_f32_e32 v187, v187
	v_cvt_i32_f32_sdwa v190, v186 dst_sel:BYTE_1 dst_unused:UNUSED_PRESERVE src0_sel:DWORD
	v_cvt_i32_f32_sdwa v196, v187 dst_sel:BYTE_1 dst_unused:UNUSED_PRESERVE src0_sel:DWORD
	v_mul_f32_e32 v186, v46, v226
	v_mul_f32_e32 v187, v47, v227
	v_rndne_f32_e32 v186, v186
	v_rndne_f32_e32 v187, v187
	v_cvt_i32_f32_sdwa v190, v186 dst_sel:BYTE_2 dst_unused:UNUSED_PRESERVE src0_sel:DWORD
	v_cvt_i32_f32_sdwa v196, v187 dst_sel:BYTE_2 dst_unused:UNUSED_PRESERVE src0_sel:DWORD
	v_mul_f32_e32 v186, v50, v226
	v_mul_f32_e32 v187, v51, v227
	v_rndne_f32_e32 v186, v186
	v_rndne_f32_e32 v187, v187
	v_cvt_i32_f32_sdwa v190, v186 dst_sel:BYTE_3 dst_unused:UNUSED_PRESERVE src0_sel:DWORD
	v_cvt_i32_f32_sdwa v196, v187 dst_sel:BYTE_3 dst_unused:UNUSED_PRESERVE src0_sel:DWORD
	s_nop 0
	ds_write_b32 v139, v190 offset:64
	ds_write_b32 v139, v196 offset:320
	v_mul_f32_e32 v186, v40, v228
	v_mul_f32_e32 v187, v41, v229
	v_rndne_f32_e32 v186, v186
	v_rndne_f32_e32 v187, v187
	v_cvt_i32_f32_sdwa v190, v186 dst_sel:BYTE_0 dst_unused:UNUSED_PAD src0_sel:DWORD
	v_cvt_i32_f32_sdwa v196, v187 dst_sel:BYTE_0 dst_unused:UNUSED_PAD src0_sel:DWORD
	v_mul_f32_e32 v186, v44, v228
	v_mul_f32_e32 v187, v45, v229
	v_rndne_f32_e32 v186, v186
	v_rndne_f32_e32 v187, v187
	v_cvt_i32_f32_sdwa v190, v186 dst_sel:BYTE_1 dst_unused:UNUSED_PRESERVE src0_sel:DWORD
	v_cvt_i32_f32_sdwa v196, v187 dst_sel:BYTE_1 dst_unused:UNUSED_PRESERVE src0_sel:DWORD
	v_mul_f32_e32 v186, v48, v228
	v_mul_f32_e32 v187, v49, v229
	v_rndne_f32_e32 v186, v186
	v_rndne_f32_e32 v187, v187
	v_cvt_i32_f32_sdwa v190, v186 dst_sel:BYTE_2 dst_unused:UNUSED_PRESERVE src0_sel:DWORD
	v_cvt_i32_f32_sdwa v196, v187 dst_sel:BYTE_2 dst_unused:UNUSED_PRESERVE src0_sel:DWORD
	v_mul_f32_e32 v186, v52, v228
	v_mul_f32_e32 v187, v53, v229
	v_rndne_f32_e32 v186, v186
	v_rndne_f32_e32 v187, v187
	v_cvt_i32_f32_sdwa v190, v186 dst_sel:BYTE_3 dst_unused:UNUSED_PRESERVE src0_sel:DWORD
	v_cvt_i32_f32_sdwa v196, v187 dst_sel:BYTE_3 dst_unused:UNUSED_PRESERVE src0_sel:DWORD
	s_nop 0
	ds_write_b32 v139, v190 offset:576
	ds_write_b32 v139, v196 offset:832
	s_cmp_ge_u32 s4, 0x2b0
	s_cbranch_scc1 .Lc32p3_ffn2_nopf_2
	global_load_dwordx4 v[38:41], v138, s[54:55]
	s_add_u32 s54, s54, 0x15800
	s_addc_u32 s55, s55, 0
	global_load_dwordx4 v[42:45], v138, s[54:55]
	s_add_u32 s54, s54, 0x15800
	s_addc_u32 s55, s55, 0
	global_load_dwordx4 v[46:49], v138, s[54:55]
	s_add_u32 s54, s54, 0x15800
	s_addc_u32 s55, s55, 0
	global_load_dwordx4 v[50:53], v138, s[54:55]
	s_add_u32 s54, s54, 0x26f800
	s_addc_u32 s55, s55, 0
.Lc32p3_ffn2_nopf_2:
	v_mul_f32_e32 v186, v54, v226
	v_mul_f32_e32 v187, v55, v227
	v_rndne_f32_e32 v186, v186
	v_rndne_f32_e32 v187, v187
	v_cvt_i32_f32_sdwa v190, v186 dst_sel:BYTE_0 dst_unused:UNUSED_PAD src0_sel:DWORD
	v_cvt_i32_f32_sdwa v196, v187 dst_sel:BYTE_0 dst_unused:UNUSED_PAD src0_sel:DWORD
	v_mul_f32_e32 v186, v58, v226
	v_mul_f32_e32 v187, v59, v227
	v_rndne_f32_e32 v186, v186
	v_rndne_f32_e32 v187, v187
	v_cvt_i32_f32_sdwa v190, v186 dst_sel:BYTE_1 dst_unused:UNUSED_PRESERVE src0_sel:DWORD
	v_cvt_i32_f32_sdwa v196, v187 dst_sel:BYTE_1 dst_unused:UNUSED_PRESERVE src0_sel:DWORD
	v_mul_f32_e32 v186, v62, v226
	v_mul_f32_e32 v187, v63, v227
	v_rndne_f32_e32 v186, v186
	v_rndne_f32_e32 v187, v187
	v_cvt_i32_f32_sdwa v190, v186 dst_sel:BYTE_2 dst_unused:UNUSED_PRESERVE src0_sel:DWORD
	v_cvt_i32_f32_sdwa v196, v187 dst_sel:BYTE_2 dst_unused:UNUSED_PRESERVE src0_sel:DWORD
	v_mul_f32_e32 v186, v66, v226
	v_mul_f32_e32 v187, v67, v227
	v_rndne_f32_e32 v186, v186
	v_rndne_f32_e32 v187, v187
	v_cvt_i32_f32_sdwa v190, v186 dst_sel:BYTE_3 dst_unused:UNUSED_PRESERVE src0_sel:DWORD
	v_cvt_i32_f32_sdwa v196, v187 dst_sel:BYTE_3 dst_unused:UNUSED_PRESERVE src0_sel:DWORD
	s_nop 0
	ds_write_b32 v139, v190 offset:96
	ds_write_b32 v139, v196 offset:352
	v_mul_f32_e32 v186, v56, v228
	v_mul_f32_e32 v187, v57, v229
	v_rndne_f32_e32 v186, v186
	v_rndne_f32_e32 v187, v187
	v_cvt_i32_f32_sdwa v190, v186 dst_sel:BYTE_0 dst_unused:UNUSED_PAD src0_sel:DWORD
	v_cvt_i32_f32_sdwa v196, v187 dst_sel:BYTE_0 dst_unused:UNUSED_PAD src0_sel:DWORD
	v_mul_f32_e32 v186, v60, v228
	v_mul_f32_e32 v187, v61, v229
	v_rndne_f32_e32 v186, v186
	v_rndne_f32_e32 v187, v187
	v_cvt_i32_f32_sdwa v190, v186 dst_sel:BYTE_1 dst_unused:UNUSED_PRESERVE src0_sel:DWORD
	v_cvt_i32_f32_sdwa v196, v187 dst_sel:BYTE_1 dst_unused:UNUSED_PRESERVE src0_sel:DWORD
	v_mul_f32_e32 v186, v64, v228
	v_mul_f32_e32 v187, v65, v229
	v_rndne_f32_e32 v186, v186
	v_rndne_f32_e32 v187, v187
	v_cvt_i32_f32_sdwa v190, v186 dst_sel:BYTE_2 dst_unused:UNUSED_PRESERVE src0_sel:DWORD
	v_cvt_i32_f32_sdwa v196, v187 dst_sel:BYTE_2 dst_unused:UNUSED_PRESERVE src0_sel:DWORD
	v_mul_f32_e32 v186, v68, v228
	v_mul_f32_e32 v187, v69, v229
	v_rndne_f32_e32 v186, v186
	v_rndne_f32_e32 v187, v187
	v_cvt_i32_f32_sdwa v190, v186 dst_sel:BYTE_3 dst_unused:UNUSED_PRESERVE src0_sel:DWORD
	v_cvt_i32_f32_sdwa v196, v187 dst_sel:BYTE_3 dst_unused:UNUSED_PRESERVE src0_sel:DWORD
	s_nop 0
	ds_write_b32 v139, v190 offset:608
	ds_write_b32 v139, v196 offset:864
	s_cmp_ge_u32 s4, 0x2b0
	s_cbranch_scc1 .Lc32p3_ffn2_nopf_3
	global_load_dwordx4 v[54:57], v138, s[54:55]
	s_add_u32 s54, s54, 0x15800
	s_addc_u32 s55, s55, 0
	global_load_dwordx4 v[58:61], v138, s[54:55]
	s_add_u32 s54, s54, 0x15800
	s_addc_u32 s55, s55, 0
	global_load_dwordx4 v[62:65], v138, s[54:55]
	s_add_u32 s54, s54, 0x15800
	s_addc_u32 s55, s55, 0
	global_load_dwordx4 v[66:69], v138, s[54:55]
	s_add_u32 s54, s54, 0x26f800
	s_addc_u32 s55, s55, 0
.Lc32p3_ffn2_nopf_3:
	v_mul_f32_e32 v186, v70, v226
	v_mul_f32_e32 v187, v71, v227
	v_rndne_f32_e32 v186, v186
	v_rndne_f32_e32 v187, v187
	v_cvt_i32_f32_sdwa v190, v186 dst_sel:BYTE_0 dst_unused:UNUSED_PAD src0_sel:DWORD
	v_cvt_i32_f32_sdwa v196, v187 dst_sel:BYTE_0 dst_unused:UNUSED_PAD src0_sel:DWORD
	v_mul_f32_e32 v186, v74, v226
	v_mul_f32_e32 v187, v75, v227
	v_rndne_f32_e32 v186, v186
	v_rndne_f32_e32 v187, v187
	v_cvt_i32_f32_sdwa v190, v186 dst_sel:BYTE_1 dst_unused:UNUSED_PRESERVE src0_sel:DWORD
	v_cvt_i32_f32_sdwa v196, v187 dst_sel:BYTE_1 dst_unused:UNUSED_PRESERVE src0_sel:DWORD
	v_mul_f32_e32 v186, v78, v226
	v_mul_f32_e32 v187, v79, v227
	v_rndne_f32_e32 v186, v186
	v_rndne_f32_e32 v187, v187
	v_cvt_i32_f32_sdwa v190, v186 dst_sel:BYTE_2 dst_unused:UNUSED_PRESERVE src0_sel:DWORD
	v_cvt_i32_f32_sdwa v196, v187 dst_sel:BYTE_2 dst_unused:UNUSED_PRESERVE src0_sel:DWORD
	v_mul_f32_e32 v186, v82, v226
	v_mul_f32_e32 v187, v83, v227
	v_rndne_f32_e32 v186, v186
	v_rndne_f32_e32 v187, v187
	v_cvt_i32_f32_sdwa v190, v186 dst_sel:BYTE_3 dst_unused:UNUSED_PRESERVE src0_sel:DWORD
	v_cvt_i32_f32_sdwa v196, v187 dst_sel:BYTE_3 dst_unused:UNUSED_PRESERVE src0_sel:DWORD
	s_nop 0
	ds_write_b32 v139, v190 offset:128
	ds_write_b32 v139, v196 offset:384
	v_mul_f32_e32 v186, v72, v228
	v_mul_f32_e32 v187, v73, v229
	v_rndne_f32_e32 v186, v186
	v_rndne_f32_e32 v187, v187
	v_cvt_i32_f32_sdwa v190, v186 dst_sel:BYTE_0 dst_unused:UNUSED_PAD src0_sel:DWORD
	v_cvt_i32_f32_sdwa v196, v187 dst_sel:BYTE_0 dst_unused:UNUSED_PAD src0_sel:DWORD
	v_mul_f32_e32 v186, v76, v228
	v_mul_f32_e32 v187, v77, v229
	v_rndne_f32_e32 v186, v186
	v_rndne_f32_e32 v187, v187
	v_cvt_i32_f32_sdwa v190, v186 dst_sel:BYTE_1 dst_unused:UNUSED_PRESERVE src0_sel:DWORD
	v_cvt_i32_f32_sdwa v196, v187 dst_sel:BYTE_1 dst_unused:UNUSED_PRESERVE src0_sel:DWORD
	v_mul_f32_e32 v186, v80, v228
	v_mul_f32_e32 v187, v81, v229
	v_rndne_f32_e32 v186, v186
	v_rndne_f32_e32 v187, v187
	v_cvt_i32_f32_sdwa v190, v186 dst_sel:BYTE_2 dst_unused:UNUSED_PRESERVE src0_sel:DWORD
	v_cvt_i32_f32_sdwa v196, v187 dst_sel:BYTE_2 dst_unused:UNUSED_PRESERVE src0_sel:DWORD
	v_mul_f32_e32 v186, v84, v228
	v_mul_f32_e32 v187, v85, v229
	v_rndne_f32_e32 v186, v186
	v_rndne_f32_e32 v187, v187
	v_cvt_i32_f32_sdwa v190, v186 dst_sel:BYTE_3 dst_unused:UNUSED_PRESERVE src0_sel:DWORD
	v_cvt_i32_f32_sdwa v196, v187 dst_sel:BYTE_3 dst_unused:UNUSED_PRESERVE src0_sel:DWORD
	s_nop 0
	ds_write_b32 v139, v190 offset:640
	ds_write_b32 v139, v196 offset:896
	s_cmp_ge_u32 s4, 0x2b0
	s_cbranch_scc1 .Lc32p3_ffn2_nopf_4
	global_load_dwordx4 v[70:73], v138, s[54:55]
	s_add_u32 s54, s54, 0x15800
	s_addc_u32 s55, s55, 0
	global_load_dwordx4 v[74:77], v138, s[54:55]
	s_add_u32 s54, s54, 0x15800
	s_addc_u32 s55, s55, 0
	global_load_dwordx4 v[78:81], v138, s[54:55]
	s_add_u32 s54, s54, 0x15800
	s_addc_u32 s55, s55, 0
	global_load_dwordx4 v[82:85], v138, s[54:55]
	s_add_u32 s54, s54, 0x26f800
	s_addc_u32 s55, s55, 0
.Lc32p3_ffn2_nopf_4:
	v_mul_f32_e32 v186, v86, v226
	v_mul_f32_e32 v187, v87, v227
	v_rndne_f32_e32 v186, v186
	v_rndne_f32_e32 v187, v187
	v_cvt_i32_f32_sdwa v190, v186 dst_sel:BYTE_0 dst_unused:UNUSED_PAD src0_sel:DWORD
	v_cvt_i32_f32_sdwa v196, v187 dst_sel:BYTE_0 dst_unused:UNUSED_PAD src0_sel:DWORD
	v_mul_f32_e32 v186, v90, v226
	v_mul_f32_e32 v187, v91, v227
	v_rndne_f32_e32 v186, v186
	v_rndne_f32_e32 v187, v187
	v_cvt_i32_f32_sdwa v190, v186 dst_sel:BYTE_1 dst_unused:UNUSED_PRESERVE src0_sel:DWORD
	v_cvt_i32_f32_sdwa v196, v187 dst_sel:BYTE_1 dst_unused:UNUSED_PRESERVE src0_sel:DWORD
	v_mul_f32_e32 v186, v94, v226
	v_mul_f32_e32 v187, v95, v227
	v_rndne_f32_e32 v186, v186
	v_rndne_f32_e32 v187, v187
	v_cvt_i32_f32_sdwa v190, v186 dst_sel:BYTE_2 dst_unused:UNUSED_PRESERVE src0_sel:DWORD
	v_cvt_i32_f32_sdwa v196, v187 dst_sel:BYTE_2 dst_unused:UNUSED_PRESERVE src0_sel:DWORD
	v_mul_f32_e32 v186, v98, v226
	v_mul_f32_e32 v187, v99, v227
	v_rndne_f32_e32 v186, v186
	v_rndne_f32_e32 v187, v187
	v_cvt_i32_f32_sdwa v190, v186 dst_sel:BYTE_3 dst_unused:UNUSED_PRESERVE src0_sel:DWORD
	v_cvt_i32_f32_sdwa v196, v187 dst_sel:BYTE_3 dst_unused:UNUSED_PRESERVE src0_sel:DWORD
	s_nop 0
	ds_write_b32 v139, v190 offset:160
	ds_write_b32 v139, v196 offset:416
	v_mul_f32_e32 v186, v88, v228
	v_mul_f32_e32 v187, v89, v229
	v_rndne_f32_e32 v186, v186
	v_rndne_f32_e32 v187, v187
	v_cvt_i32_f32_sdwa v190, v186 dst_sel:BYTE_0 dst_unused:UNUSED_PAD src0_sel:DWORD
	v_cvt_i32_f32_sdwa v196, v187 dst_sel:BYTE_0 dst_unused:UNUSED_PAD src0_sel:DWORD
	v_mul_f32_e32 v186, v92, v228
	v_mul_f32_e32 v187, v93, v229
	v_rndne_f32_e32 v186, v186
	v_rndne_f32_e32 v187, v187
	v_cvt_i32_f32_sdwa v190, v186 dst_sel:BYTE_1 dst_unused:UNUSED_PRESERVE src0_sel:DWORD
	v_cvt_i32_f32_sdwa v196, v187 dst_sel:BYTE_1 dst_unused:UNUSED_PRESERVE src0_sel:DWORD
	v_mul_f32_e32 v186, v96, v228
	v_mul_f32_e32 v187, v97, v229
	v_rndne_f32_e32 v186, v186
	v_rndne_f32_e32 v187, v187
	v_cvt_i32_f32_sdwa v190, v186 dst_sel:BYTE_2 dst_unused:UNUSED_PRESERVE src0_sel:DWORD
	v_cvt_i32_f32_sdwa v196, v187 dst_sel:BYTE_2 dst_unused:UNUSED_PRESERVE src0_sel:DWORD
	v_mul_f32_e32 v186, v100, v228
	v_mul_f32_e32 v187, v101, v229
	v_rndne_f32_e32 v186, v186
	v_rndne_f32_e32 v187, v187
	v_cvt_i32_f32_sdwa v190, v186 dst_sel:BYTE_3 dst_unused:UNUSED_PRESERVE src0_sel:DWORD
	v_cvt_i32_f32_sdwa v196, v187 dst_sel:BYTE_3 dst_unused:UNUSED_PRESERVE src0_sel:DWORD
	s_nop 0
	ds_write_b32 v139, v190 offset:672
	ds_write_b32 v139, v196 offset:928
	s_cmp_ge_u32 s4, 0x2b0
	s_cbranch_scc1 .Lc32p3_ffn2_nopf_5
	global_load_dwordx4 v[86:89], v138, s[54:55]
	s_add_u32 s54, s54, 0x15800
	s_addc_u32 s55, s55, 0
	global_load_dwordx4 v[90:93], v138, s[54:55]
	s_add_u32 s54, s54, 0x15800
	s_addc_u32 s55, s55, 0
	global_load_dwordx4 v[94:97], v138, s[54:55]
	s_add_u32 s54, s54, 0x15800
	s_addc_u32 s55, s55, 0
	global_load_dwordx4 v[98:101], v138, s[54:55]
	s_add_u32 s54, s54, 0x26f800
	s_addc_u32 s55, s55, 0
.Lc32p3_ffn2_nopf_5:
	v_mul_f32_e32 v186, v102, v226
	v_mul_f32_e32 v187, v103, v227
	v_rndne_f32_e32 v186, v186
	v_rndne_f32_e32 v187, v187
	v_cvt_i32_f32_sdwa v190, v186 dst_sel:BYTE_0 dst_unused:UNUSED_PAD src0_sel:DWORD
	v_cvt_i32_f32_sdwa v196, v187 dst_sel:BYTE_0 dst_unused:UNUSED_PAD src0_sel:DWORD
	v_mul_f32_e32 v186, v106, v226
	v_mul_f32_e32 v187, v107, v227
	v_rndne_f32_e32 v186, v186
	v_rndne_f32_e32 v187, v187
	v_cvt_i32_f32_sdwa v190, v186 dst_sel:BYTE_1 dst_unused:UNUSED_PRESERVE src0_sel:DWORD
	v_cvt_i32_f32_sdwa v196, v187 dst_sel:BYTE_1 dst_unused:UNUSED_PRESERVE src0_sel:DWORD
	v_mul_f32_e32 v186, v110, v226
	v_mul_f32_e32 v187, v111, v227
	v_rndne_f32_e32 v186, v186
	v_rndne_f32_e32 v187, v187
	v_cvt_i32_f32_sdwa v190, v186 dst_sel:BYTE_2 dst_unused:UNUSED_PRESERVE src0_sel:DWORD
	v_cvt_i32_f32_sdwa v196, v187 dst_sel:BYTE_2 dst_unused:UNUSED_PRESERVE src0_sel:DWORD
	v_mul_f32_e32 v186, v114, v226
	v_mul_f32_e32 v187, v115, v227
	v_rndne_f32_e32 v186, v186
	v_rndne_f32_e32 v187, v187
	v_cvt_i32_f32_sdwa v190, v186 dst_sel:BYTE_3 dst_unused:UNUSED_PRESERVE src0_sel:DWORD
	v_cvt_i32_f32_sdwa v196, v187 dst_sel:BYTE_3 dst_unused:UNUSED_PRESERVE src0_sel:DWORD
	s_nop 0
	ds_write_b32 v139, v190 offset:192
	ds_write_b32 v139, v196 offset:448
	v_mul_f32_e32 v186, v104, v228
	v_mul_f32_e32 v187, v105, v229
	v_rndne_f32_e32 v186, v186
	v_rndne_f32_e32 v187, v187
	v_cvt_i32_f32_sdwa v190, v186 dst_sel:BYTE_0 dst_unused:UNUSED_PAD src0_sel:DWORD
	v_cvt_i32_f32_sdwa v196, v187 dst_sel:BYTE_0 dst_unused:UNUSED_PAD src0_sel:DWORD
	v_mul_f32_e32 v186, v108, v228
	v_mul_f32_e32 v187, v109, v229
	v_rndne_f32_e32 v186, v186
	v_rndne_f32_e32 v187, v187
	v_cvt_i32_f32_sdwa v190, v186 dst_sel:BYTE_1 dst_unused:UNUSED_PRESERVE src0_sel:DWORD
	v_cvt_i32_f32_sdwa v196, v187 dst_sel:BYTE_1 dst_unused:UNUSED_PRESERVE src0_sel:DWORD
	v_mul_f32_e32 v186, v112, v228
	v_mul_f32_e32 v187, v113, v229
	v_rndne_f32_e32 v186, v186
	v_rndne_f32_e32 v187, v187
	v_cvt_i32_f32_sdwa v190, v186 dst_sel:BYTE_2 dst_unused:UNUSED_PRESERVE src0_sel:DWORD
	v_cvt_i32_f32_sdwa v196, v187 dst_sel:BYTE_2 dst_unused:UNUSED_PRESERVE src0_sel:DWORD
	v_mul_f32_e32 v186, v116, v228
	v_mul_f32_e32 v187, v117, v229
	v_rndne_f32_e32 v186, v186
	v_rndne_f32_e32 v187, v187
	v_cvt_i32_f32_sdwa v190, v186 dst_sel:BYTE_3 dst_unused:UNUSED_PRESERVE src0_sel:DWORD
	v_cvt_i32_f32_sdwa v196, v187 dst_sel:BYTE_3 dst_unused:UNUSED_PRESERVE src0_sel:DWORD
	s_nop 0
	ds_write_b32 v139, v190 offset:704
	ds_write_b32 v139, v196 offset:960
	s_cmp_ge_u32 s4, 0x2b0
	s_cbranch_scc1 .Lc32p3_ffn2_nopf_6
	global_load_dwordx4 v[102:105], v138, s[54:55]
	s_add_u32 s54, s54, 0x15800
	s_addc_u32 s55, s55, 0
	global_load_dwordx4 v[106:109], v138, s[54:55]
	s_add_u32 s54, s54, 0x15800
	s_addc_u32 s55, s55, 0
	global_load_dwordx4 v[110:113], v138, s[54:55]
	s_add_u32 s54, s54, 0x15800
	s_addc_u32 s55, s55, 0
	global_load_dwordx4 v[114:117], v138, s[54:55]
	s_add_u32 s54, s54, 0x26f800
	s_addc_u32 s55, s55, 0
.Lc32p3_ffn2_nopf_6:
	v_mul_f32_e32 v186, v118, v226
	v_mul_f32_e32 v187, v119, v227
	v_rndne_f32_e32 v186, v186
	v_rndne_f32_e32 v187, v187
	v_cvt_i32_f32_sdwa v190, v186 dst_sel:BYTE_0 dst_unused:UNUSED_PAD src0_sel:DWORD
	v_cvt_i32_f32_sdwa v196, v187 dst_sel:BYTE_0 dst_unused:UNUSED_PAD src0_sel:DWORD
	v_mul_f32_e32 v186, v122, v226
	v_mul_f32_e32 v187, v123, v227
	v_rndne_f32_e32 v186, v186
	v_rndne_f32_e32 v187, v187
	v_cvt_i32_f32_sdwa v190, v186 dst_sel:BYTE_1 dst_unused:UNUSED_PRESERVE src0_sel:DWORD
	v_cvt_i32_f32_sdwa v196, v187 dst_sel:BYTE_1 dst_unused:UNUSED_PRESERVE src0_sel:DWORD
	v_mul_f32_e32 v186, v126, v226
	v_mul_f32_e32 v187, v127, v227
	v_rndne_f32_e32 v186, v186
	v_rndne_f32_e32 v187, v187
	v_cvt_i32_f32_sdwa v190, v186 dst_sel:BYTE_2 dst_unused:UNUSED_PRESERVE src0_sel:DWORD
	v_cvt_i32_f32_sdwa v196, v187 dst_sel:BYTE_2 dst_unused:UNUSED_PRESERVE src0_sel:DWORD
	v_mul_f32_e32 v186, v130, v226
	v_mul_f32_e32 v187, v131, v227
	v_rndne_f32_e32 v186, v186
	v_rndne_f32_e32 v187, v187
	v_cvt_i32_f32_sdwa v190, v186 dst_sel:BYTE_3 dst_unused:UNUSED_PRESERVE src0_sel:DWORD
	v_cvt_i32_f32_sdwa v196, v187 dst_sel:BYTE_3 dst_unused:UNUSED_PRESERVE src0_sel:DWORD
	s_nop 0
	ds_write_b32 v139, v190 offset:224
	ds_write_b32 v139, v196 offset:480
	v_mul_f32_e32 v186, v120, v228
	v_mul_f32_e32 v187, v121, v229
	v_rndne_f32_e32 v186, v186
	v_rndne_f32_e32 v187, v187
	v_cvt_i32_f32_sdwa v190, v186 dst_sel:BYTE_0 dst_unused:UNUSED_PAD src0_sel:DWORD
	v_cvt_i32_f32_sdwa v196, v187 dst_sel:BYTE_0 dst_unused:UNUSED_PAD src0_sel:DWORD
	v_mul_f32_e32 v186, v124, v228
	v_mul_f32_e32 v187, v125, v229
	v_rndne_f32_e32 v186, v186
	v_rndne_f32_e32 v187, v187
	v_cvt_i32_f32_sdwa v190, v186 dst_sel:BYTE_1 dst_unused:UNUSED_PRESERVE src0_sel:DWORD
	v_cvt_i32_f32_sdwa v196, v187 dst_sel:BYTE_1 dst_unused:UNUSED_PRESERVE src0_sel:DWORD
	v_mul_f32_e32 v186, v128, v228
	v_mul_f32_e32 v187, v129, v229
	v_rndne_f32_e32 v186, v186
	v_rndne_f32_e32 v187, v187
	v_cvt_i32_f32_sdwa v190, v186 dst_sel:BYTE_2 dst_unused:UNUSED_PRESERVE src0_sel:DWORD
	v_cvt_i32_f32_sdwa v196, v187 dst_sel:BYTE_2 dst_unused:UNUSED_PRESERVE src0_sel:DWORD
	v_mul_f32_e32 v186, v132, v228
	v_mul_f32_e32 v187, v133, v229
	v_rndne_f32_e32 v186, v186
	v_rndne_f32_e32 v187, v187
	v_cvt_i32_f32_sdwa v190, v186 dst_sel:BYTE_3 dst_unused:UNUSED_PRESERVE src0_sel:DWORD
	v_cvt_i32_f32_sdwa v196, v187 dst_sel:BYTE_3 dst_unused:UNUSED_PRESERVE src0_sel:DWORD
	s_nop 0
	ds_write_b32 v139, v190 offset:736
	ds_write_b32 v139, v196 offset:992
	s_cmp_ge_u32 s4, 0x2b0
	s_cbranch_scc1 .Lc32p3_ffn2_nopf_7
	global_load_dwordx4 v[118:121], v138, s[54:55]
	s_add_u32 s54, s54, 0x15800
	s_addc_u32 s55, s55, 0
	global_load_dwordx4 v[122:125], v138, s[54:55]
	s_add_u32 s54, s54, 0x15800
	s_addc_u32 s55, s55, 0
	global_load_dwordx4 v[126:129], v138, s[54:55]
	s_add_u32 s54, s54, 0x15800
	s_addc_u32 s55, s55, 0
	global_load_dwordx4 v[130:133], v138, s[54:55]
.Lc32p3_ffn2_nopf_7:
	s_waitcnt lgkmcnt(0)
	s_lshl_b32 s3, s6, 12
	s_add_u32 s3, s3, s64
	s_add_u32 s56, s34, s3
	s_addc_u32 s57, s35, 0
	s_add_u32 s56, s56, 0xe700000
	s_addc_u32 s57, s57, 0
	ds_read_b128 v[204:207], v212 offset:0
	s_waitcnt lgkmcnt(0)
	global_store_dwordx4 v213, v[204:207], s[56:57]
	s_add_u32 s56, s56, 0x4000
	s_addc_u32 s57, s57, 0
	ds_read_b128 v[208:211], v212 offset:1024
	s_waitcnt lgkmcnt(0)
	global_store_dwordx4 v213, v[208:211], s[56:57]
	s_add_u32 s56, s56, 0x4000
	s_addc_u32 s57, s57, 0
	ds_read_b128 v[204:207], v212 offset:2048
	s_waitcnt lgkmcnt(0)
	global_store_dwordx4 v213, v[204:207], s[56:57]
	s_add_u32 s56, s56, 0x4000
	s_addc_u32 s57, s57, 0
	ds_read_b128 v[208:211], v212 offset:3072
	s_waitcnt lgkmcnt(0)
	global_store_dwordx4 v213, v[208:211], s[56:57]
	s_add_u32 s56, s56, 0x4000
	s_addc_u32 s57, s57, 0
	ds_read_b128 v[204:207], v212 offset:4096
	s_waitcnt lgkmcnt(0)
	global_store_dwordx4 v213, v[204:207], s[56:57]
	s_add_u32 s56, s56, 0x4000
	s_addc_u32 s57, s57, 0
	ds_read_b128 v[208:211], v212 offset:5120
	s_waitcnt lgkmcnt(0)
	global_store_dwordx4 v213, v[208:211], s[56:57]
	s_add_u32 s56, s56, 0x4000
	s_addc_u32 s57, s57, 0
	ds_read_b128 v[204:207], v212 offset:6144
	s_waitcnt lgkmcnt(0)
	global_store_dwordx4 v213, v[204:207], s[56:57]
	s_add_u32 s56, s56, 0x4000
	s_addc_u32 s57, s57, 0
	ds_read_b128 v[208:211], v212 offset:7168
	s_waitcnt lgkmcnt(0)
	global_store_dwordx4 v213, v[208:211], s[56:57]
	s_xor_b32 s5, s5, 1
	s_add_u32 s0, s0, 128
	s_cmp_lt_u32 s0, 0x2b0
	s_cbranch_scc1 .Lc32p3_ffn2_loop
